# nt hint extended to colmax sampled weight reads (P2 tail) and P4 once-read streams (xbc rows, PREV, z) on top of P0/P3
# baseline (speedup 1.0000x reference)
; __device__ __forceinline__ void ph_colmax(const float* __restrict__ W, const float* __restrict__ g, int K, int N, unsigned* cmax, int gw, int NGW, int lane) {
;     ...
;     for (int item = gw; item < nitems; item += NGW) { const int kb = item / ncb, cb = item % ncb, col = cb * 256 + lane * 4;
;         f32x4 m = {0.f, 0.f, 0.f, 0.f};
;         f32x4 v[16];
; #pragma unroll
;         for (int kk = 0; kk < 16; ++kk) v[kk] = *(const f32x4*)(W + (size_t)(kb * 64 + 4 * kk) * N + col);
; #pragma unroll
;         for (int kk = 0; kk < 16; ++kk) { const float gg = g ? g[kb * 64 + 4 * kk] : 1.f;
.LBB0_659:
	s_mul_hi_i32 s18, s5, 0x2fa0be83
	s_lshr_b32 s19, s18, 31
	s_ashr_i32 s18, s18, 4
	s_add_i32 s18, s18, s19
	s_mul_i32 s19, s18, 0xffffaa00
	v_add_u32_e32 v66, s19, v68
	s_lshl_b32 s18, s18, 6
	v_ashrrev_i32_e32 v67, 31, v66
	v_lshl_add_u64 v[2:3], v[66:67], 2, s[10:11]
	s_or_b32 s19, s18, 4
	v_mad_i64_i32 v[4:5], s[20:21], s18, v69, v[2:3]
	v_mad_i64_i32 v[6:7], s[20:21], s19, v69, v[2:3]
	s_or_b32 s19, s18, 8
	global_load_dwordx4 v[62:65], v[4:5], off nt
	global_load_dwordx4 v[50:53], v[6:7], off nt
	v_mad_i64_i32 v[4:5], s[20:21], s19, v69, v[2:3]
	s_or_b32 s19, s18, 12
	v_mad_i64_i32 v[6:7], s[20:21], s19, v69, v[2:3]
	s_or_b32 s19, s18, 16
	global_load_dwordx4 v[58:61], v[4:5], off nt
	global_load_dwordx4 v[42:45], v[6:7], off nt
	v_mad_i64_i32 v[4:5], s[20:21], s19, v69, v[2:3]
	s_or_b32 s19, s18, 20
	v_mad_i64_i32 v[6:7], s[20:21], s19, v69, v[2:3]
	s_or_b32 s19, s18, 24
	global_load_dwordx4 v[54:57], v[4:5], off nt
	global_load_dwordx4 v[34:37], v[6:7], off nt
	v_mad_i64_i32 v[4:5], s[20:21], s19, v69, v[2:3]
	s_or_b32 s19, s18, 28
	v_mad_i64_i32 v[6:7], s[20:21], s19, v69, v[2:3]
	s_or_b32 s19, s18, 32
	global_load_dwordx4 v[46:49], v[4:5], off nt
	global_load_dwordx4 v[26:29], v[6:7], off nt
	v_mad_i64_i32 v[4:5], s[20:21], s19, v69, v[2:3]
	s_or_b32 s19, s18, 36
	v_mad_i64_i32 v[6:7], s[20:21], s19, v69, v[2:3]
	s_or_b32 s19, s18, 40
	global_load_dwordx4 v[38:41], v[4:5], off nt
	global_load_dwordx4 v[18:21], v[6:7], off nt
	v_mad_i64_i32 v[4:5], s[20:21], s19, v69, v[2:3]
	s_or_b32 s19, s18, 44
	v_mad_i64_i32 v[6:7], s[20:21], s19, v69, v[2:3]
	s_or_b32 s19, s18, 48
	global_load_dwordx4 v[30:33], v[4:5], off nt
	global_load_dwordx4 v[10:13], v[6:7], off nt
	v_mad_i64_i32 v[4:5], s[20:21], s19, v69, v[2:3]
	s_or_b32 s19, s18, 52
	v_mad_i64_i32 v[14:15], s[20:21], s19, v69, v[2:3]
	s_or_b32 s19, s18, 56
	v_mad_i64_i32 v[72:73], s[20:21], s19, v69, v[2:3]
	s_or_b32 s19, s18, 60
	global_load_dwordx4 v[22:25], v[4:5], off nt
	global_load_dwordx4 v[6:9], v[14:15], off nt
	v_mad_i64_i32 v[74:75], s[20:21], s19, v69, v[2:3]
	global_load_dwordx4 v[14:17], v[72:73], off nt
	global_load_dwordx4 v[2:5], v[74:75], off nt
	s_ashr_i32 s19, s18, 31
	v_mov_b32_e32 v71, 1.0
	s_and_b64 vcc, exec, s[6:7]
	v_mov_b32_e32 v72, 1.0
	s_cbranch_vccnz .LBB0_661
	s_lshl_b64 s[20:21], s[18:19], 2
	s_add_u32 s20, s8, s20
	s_addc_u32 s21, s9, s21
	global_load_dword v72, v70, s[20:21]

; __device__ __forceinline__ void ph_colmax(const float* __restrict__ W, const float* __restrict__ g, int K, int N, unsigned* cmax, int gw, int NGW, int lane) {
;     ...
;     for (int item = gw; item < nitems; item += NGW) { const int kb = item / ncb, cb = item % ncb, col = cb * 256 + lane * 4;
;         f32x4 m = {0.f, 0.f, 0.f, 0.f};
;         f32x4 v[16];
; #pragma unroll
;         for (int kk = 0; kk < 16; ++kk) v[kk] = *(const f32x4*)(W + (size_t)(kb * 64 + 4 * kk) * N + col);
; #pragma unroll
;         for (int kk = 0; kk < 16; ++kk) { const float gg = g ? g[kb * 64 + 4 * kk] : 1.f;
; #pragma unroll
;             for (int e = 0; e < 4; ++e) m[e] = fmaxf(m[e], fabsf(v[kk][e] * gg)); }
; #pragma unroll
;         for (int e = 0; e < 4; ++e) atomicMax(cmax + col + e, __float_as_uint(m[e] * CMAX_SAFE)); }
.LBB0_693:
	s_ashr_i32 s5, s1, 31
	s_lshr_b32 s5, s5, 28
	s_add_i32 s5, s1, s5
	s_ashr_i32 s5, s5, 4
	s_lshl_b32 s10, s5, 12
	s_lshl_b32 s12, s5, 6
	v_subrev_u32_e32 v2, s10, v1
	s_or_b32 s10, s12, 4
	v_ashrrev_i32_e32 v3, 31, v2
	s_ashr_i32 s13, s12, 31
	s_or_b32 s14, s12, 8
	s_or_b32 s16, s12, 12
	s_or_b32 s18, s12, 16
	s_or_b32 s20, s12, 20
	s_or_b32 s22, s12, 24
	s_or_b32 s24, s12, 28
	s_or_b32 s26, s12, 32
	s_or_b32 s28, s12, 36
	s_or_b32 s30, s12, 40
	s_or_b32 s34, s12, 44
	s_or_b32 s36, s12, 48
	s_or_b32 s38, s12, 52
	s_or_b32 s40, s12, 56
	s_or_b32 s42, s12, 60
	s_ashr_i32 s11, s10, 31
	v_lshlrev_b64 v[66:67], 2, v[2:3]
	s_lshl_b64 s[12:13], s[12:13], 14
	s_ashr_i32 s15, s14, 31
	s_ashr_i32 s17, s16, 31
	s_ashr_i32 s19, s18, 31
	s_ashr_i32 s21, s20, 31
	s_ashr_i32 s23, s22, 31
	s_ashr_i32 s25, s24, 31
	s_ashr_i32 s27, s26, 31
	s_ashr_i32 s29, s28, 31
	s_ashr_i32 s31, s30, 31
	s_ashr_i32 s35, s34, 31
	s_ashr_i32 s37, s36, 31
	s_ashr_i32 s39, s38, 31
	s_ashr_i32 s41, s40, 31
	s_ashr_i32 s43, s42, 31
	s_lshl_b64 s[10:11], s[10:11], 14
	v_lshl_add_u64 v[2:3], s[6:7], 0, v[66:67]
	s_lshl_b64 s[14:15], s[14:15], 14
	s_lshl_b64 s[16:17], s[16:17], 14
	s_lshl_b64 s[18:19], s[18:19], 14
	s_lshl_b64 s[20:21], s[20:21], 14
	s_lshl_b64 s[22:23], s[22:23], 14
	s_lshl_b64 s[24:25], s[24:25], 14
	s_lshl_b64 s[26:27], s[26:27], 14
	s_lshl_b64 s[28:29], s[28:29], 14
	s_lshl_b64 s[30:31], s[30:31], 14
	s_lshl_b64 s[34:35], s[34:35], 14
	s_lshl_b64 s[36:37], s[36:37], 14
	s_lshl_b64 s[38:39], s[38:39], 14
	s_lshl_b64 s[40:41], s[40:41], 14
	s_lshl_b64 s[42:43], s[42:43], 14
	v_lshl_add_u64 v[62:63], v[2:3], 0, s[12:13]
	v_lshl_add_u64 v[64:65], v[2:3], 0, s[10:11]
	v_lshl_add_u64 v[68:69], v[2:3], 0, s[14:15]
	v_lshl_add_u64 v[70:71], v[2:3], 0, s[16:17]
	v_lshl_add_u64 v[72:73], v[2:3], 0, s[18:19]
	v_lshl_add_u64 v[74:75], v[2:3], 0, s[20:21]
	v_lshl_add_u64 v[76:77], v[2:3], 0, s[22:23]
	v_lshl_add_u64 v[78:79], v[2:3], 0, s[24:25]
	v_lshl_add_u64 v[80:81], v[2:3], 0, s[26:27]
	v_lshl_add_u64 v[82:83], v[2:3], 0, s[28:29]
	v_lshl_add_u64 v[84:85], v[2:3], 0, s[30:31]
	v_lshl_add_u64 v[86:87], v[2:3], 0, s[34:35]
	v_lshl_add_u64 v[88:89], v[2:3], 0, s[36:37]
	v_lshl_add_u64 v[90:91], v[2:3], 0, s[38:39]
	v_lshl_add_u64 v[92:93], v[2:3], 0, s[40:41]
	v_lshl_add_u64 v[94:95], v[2:3], 0, s[42:43]
	global_load_dwordx4 v[2:5], v[62:63], off nt
	global_load_dwordx4 v[6:9], v[64:65], off nt
	global_load_dwordx4 v[10:13], v[68:69], off nt
	global_load_dwordx4 v[14:17], v[70:71], off nt
	global_load_dwordx4 v[18:21], v[72:73], off nt
	global_load_dwordx4 v[22:25], v[74:75], off nt
	global_load_dwordx4 v[26:29], v[76:77], off nt
	global_load_dwordx4 v[30:33], v[78:79], off nt
	global_load_dwordx4 v[34:37], v[80:81], off nt
	global_load_dwordx4 v[38:41], v[82:83], off nt
	global_load_dwordx4 v[42:45], v[84:85], off nt
	global_load_dwordx4 v[46:49], v[86:87], off nt
	global_load_dwordx4 v[50:53], v[88:89], off nt
	global_load_dwordx4 v[54:57], v[90:91], off nt
	global_load_dwordx4 v[58:61], v[92:93], off nt
	global_load_dwordx4 v[62:65], v[94:95], off nt
	v_lshl_add_u64 v[66:67], s[8:9], 0, v[66:67]
	s_add_i32 s1, s1, s3
	s_cmpk_lt_i32 s1, 0x400
	v_add_u32_e32 v1, s4, v1
	s_waitcnt vmcnt(0)
	v_max3_f32 v2, |v2|, 0, |v6|
	v_max3_f32 v3, |v3|, 0, |v7|
	v_max3_f32 v4, |v4|, 0, |v8|
	v_max3_f32 v5, |v5|, 0, |v9|
	v_max3_f32 v2, v2, |v10|, |v14|
	v_max3_f32 v3, v3, |v11|, |v15|
	v_max3_f32 v4, v4, |v12|, |v16|
	v_max3_f32 v5, v5, |v13|, |v17|
	v_max3_f32 v2, v2, |v18|, |v22|
	v_max3_f32 v3, v3, |v19|, |v23|
	v_max3_f32 v4, v4, |v20|, |v24|
	v_max3_f32 v5, v5, |v21|, |v25|
	v_max3_f32 v2, v2, |v26|, |v30|
	v_max3_f32 v3, v3, |v27|, |v31|
	v_max3_f32 v4, v4, |v28|, |v32|
	v_max3_f32 v5, v5, |v29|, |v33|
	v_max3_f32 v2, v2, |v34|, |v38|
	v_max3_f32 v3, v3, |v35|, |v39|
	v_max3_f32 v4, v4, |v36|, |v40|
	v_max3_f32 v5, v5, |v37|, |v41|
	v_max3_f32 v2, v2, |v42|, |v46|
	v_max3_f32 v3, v3, |v43|, |v47|
	v_max3_f32 v4, v4, |v44|, |v48|
	v_max3_f32 v5, v5, |v45|, |v49|
	v_max3_f32 v2, v2, |v50|, |v54|
	v_max3_f32 v3, v3, |v51|, |v55|
	v_max3_f32 v4, v4, |v52|, |v56|
	v_max3_f32 v5, v5, |v53|, |v57|
	v_max3_f32 v2, v2, |v58|, |v62|
	v_max3_f32 v3, v3, |v59|, |v63|
	v_max3_f32 v4, v4, |v60|, |v64|
	v_max3_f32 v5, v5, |v61|, |v65|
	v_mul_f32_e32 v2, 0x3f8ccccd, v2
	v_mul_f32_e32 v3, 0x3f8ccccd, v3
	v_mul_f32_e32 v4, 0x3f8ccccd, v4
	v_mul_f32_e32 v5, 0x3f8ccccd, v5
	global_atomic_umax v[66:67], v2, off
	global_atomic_umax v[66:67], v3, off offset:4
	global_atomic_umax v[66:67], v4, off offset:8
	global_atomic_umax v[66:67], v5, off offset:12
	s_cbranch_scc1 .LBB0_693

; template <bool NEED_C>
; __device__ __forceinline__ void ssd_stage(LAS unsigned char* lds, const bf16_t* XBC, const float* cw, const float* cb, const float* DT, const float* a_log, int c, int g, int tid, int lane, int wave) {
;     ...
;         if (cgi < 32) { col = g * 256 + cgi * 8; tile = lds + SSD_XT + (cgi >> 4) * 32768; tch = cgi & 15; }
;         else if (cgi < 48) { col = 2048 + g * 128 + (cgi - 32) * 8; tile = lds + SSD_BT; tch = cgi - 32; }
;         else { col = 3072 + g * 128 + (cgi - 48) * 8; tile = lds + SSD_CT; tch = cgi - 48; }
;         if (NEED_C || cgi < 48) {
;             float w[4][8], b[8], xw[3][8];
; #pragma unroll
;             for (int k = 0; k < 4; ++k) { const f32x4 w0 = *(const f32x4*)(cw + k * XBCC + col), w1 = *(const f32x4*)(cw + k * XBCC + col + 4);
; #pragma unroll
;                 for (int e = 0; e < 4; ++e) { w[k][e] = w0[e]; w[k][4 + e] = w1[e]; } }
;             { const f32x4 b0 = *(const f32x4*)(cb + col), b1 = *(const f32x4*)(cb + col + 4);
; #pragma unroll
;               for (int e = 0; e < 4; ++e) { b[e] = b0[e]; b[4 + e] = b1[e]; } }
;             const int t0 = c * 128 + seg * 16;
;             u32x4 raw[19];
; #pragma unroll
;             for (int k = 0; k < 19; ++k) { const int tt = t0 - 3 + k;
;                 if (k >= 3 || tt >= 0) raw[k] = *(const u32x4*)(XBC + (size_t)tt * XBCC + col);
;                 else raw[k] = (u32x4){0u, 0u, 0u, 0u}; }
;             asm volatile("" ::: "memory");
.LBB0_1042:
	s_andn2_saveexec_b64 s[20:21], s[20:21]
	v_lshl_or_b32 v118, s42, 8, v141
	v_mov_b32_e32 v123, v142
	v_mov_b32_e32 v220, v143
	s_or_b64 exec, exec, s[20:21]
	v_lshlrev_b64 v[10:11], 2, v[118:119]
	s_waitcnt lgkmcnt(0)
	v_lshl_add_u64 v[6:7], s[24:25], 0, v[10:11]
	v_add_co_u32_e32 v4, vcc, 0x4000, v6
	v_lshl_add_u64 v[2:3], v[6:7], 0, s[52:53]
	s_nop 0
	v_addc_co_u32_e32 v5, vcc, 0, v7, vcc
	v_add_co_u32_e32 v12, vcc, s3, v6
	v_lshl_add_u64 v[8:9], v[6:7], 0, s[54:55]
	s_nop 0
	v_addc_co_u32_e32 v13, vcc, 0, v7, vcc
	global_load_dwordx4 v[86:89], v[6:7], off offset:16
	global_load_dwordx4 v[106:109], v[6:7], off
	global_load_dwordx4 v[14:17], v[4:5], off
	s_nop 0
	global_load_dwordx4 v[2:5], v[2:3], off offset:16
	s_nop 0
	global_load_dwordx4 v[110:113], v[12:13], off
	global_load_dwordx4 v[90:93], v[8:9], off offset:16
	v_lshl_add_u64 v[8:9], v[6:7], 0, s[56:57]
	v_add_co_u32_e32 v6, vcc, 0xc000, v6
	v_lshl_add_u64 v[22:23], s[26:27], 0, v[10:11]
	s_nop 0
	v_addc_co_u32_e32 v7, vcc, 0, v7, vcc
	global_load_dwordx4 v[18:21], v[6:7], off
	s_nop 0
	global_load_dwordx4 v[6:9], v[8:9], off offset:16
	s_nop 0
	global_load_dwordx4 v[10:13], v[22:23], off offset:16
	s_nop 0
	global_load_dwordx4 v[22:25], v[22:23], off
	s_ashr_i32 s89, s88, 3
	s_lshl_b32 s90, s89, 7
	v_add_u32_e32 v28, s90, v146
	v_lshl_add_u64 v[26:27], v[118:119], 1, s[34:35]
	v_cmp_lt_i32_e32 vcc, -1, v28
	v_mov_b32_e32 v98, 0
	v_mov_b32_e32 v94, 0
	v_mov_b32_e32 v95, 0
	v_mov_b32_e32 v96, 0
	v_mov_b32_e32 v97, 0
	s_and_saveexec_b64 s[20:21], vcc
	s_cbranch_execz .LBB0_1046
	v_mov_b32_e32 v29, v119
	v_lshlrev_b64 v[30:31], 13, v[28:29]
	v_lshl_add_u64 v[30:31], v[26:27], 0, v[30:31]
	global_load_dwordx4 v[94:97], v[30:31], off nt
.LBB0_1046:
	s_or_b64 exec, exec, s[20:21]
	v_cmp_lt_i32_e64 s[20:21], -2, v28
	v_mov_b32_e32 v99, 0
	v_mov_b32_e32 v100, 0
	v_mov_b32_e32 v101, 0
	s_and_saveexec_b64 s[58:59], s[20:21]
	s_cbranch_execz .LBB0_1048
	v_add_u32_e32 v118, 1, v28
	v_lshlrev_b64 v[30:31], 13, v[118:119]
	v_lshl_add_u64 v[30:31], v[26:27], 0, v[30:31]
	global_load_dwordx4 v[98:101], v[30:31], off nt
.LBB0_1048:
	s_or_b64 exec, exec, s[58:59]
	v_mov_b32_e32 v102, 0
	v_mov_b32_e32 v103, 0
	v_mov_b32_e32 v104, 0
	v_mov_b32_e32 v105, 0
	s_and_saveexec_b64 s[20:21], vcc
	s_cbranch_execz .LBB0_1050
	v_or_b32_e32 v118, 2, v28
	v_lshlrev_b64 v[30:31], 13, v[118:119]
	v_lshl_add_u64 v[30:31], v[26:27], 0, v[30:31]
	global_load_dwordx4 v[102:105], v[30:31], off nt
.LBB0_1050:
	s_or_b64 exec, exec, s[20:21]
	v_add_u32_e32 v30, s90, v145
	v_ashrrev_i32_e32 v31, 31, v30
	v_ashrrev_i32_e32 v29, 31, v28
	v_lshlrev_b64 v[30:31], 13, v[30:31]
	v_lshlrev_b64 v[28:29], 13, v[28:29]
	v_lshl_add_u64 v[30:31], v[26:27], 0, v[30:31]
	v_lshl_add_u64 v[26:27], v[26:27], 0, v[28:29]
	v_add_co_u32_e32 v28, vcc, s3, v26
	s_waitcnt vmcnt(0)
	v_lshlrev_b32_e32 v227, 16, v98
	v_addc_co_u32_e32 v29, vcc, 0, v27, vcc
	global_load_dwordx4 v[114:117], v[30:31], off nt
	global_load_dwordx4 v[78:81], v[28:29], off nt
	v_lshlrev_b32_e32 v226, 16, v94
	v_mov_b32_e32 v124, v106
	v_mov_b32_e32 v125, v14
	v_pk_mul_f32 v[34:35], v[124:125], v[226:227]
	v_lshlrev_b32_e32 v136, 16, v102
	v_add_f32_e32 v14, v22, v34
	v_mov_b32_e32 v126, v110
	v_mov_b32_e32 v127, v18
	v_add_f32_e32 v14, v14, v35
	v_and_b32_e32 v229, 0xffff0000, v98
	v_and_b32_e32 v228, 0xffff0000, v94
	v_and_b32_e32 v134, 0xffff0000, v102
	v_lshlrev_b32_e32 v230, 16, v95
	v_lshlrev_b32_e32 v231, 16, v99
	v_lshlrev_b32_e32 v130, 16, v103
	v_and_b32_e32 v233, 0xffff0000, v99
	v_and_b32_e32 v232, 0xffff0000, v95
	v_add_co_u32_e32 v28, vcc, s68, v26
	v_and_b32_e32 v235, 0xffff0000, v100
	s_nop 0
	v_addc_co_u32_e32 v29, vcc, 0, v27, vcc
	v_add_co_u32_e32 v30, vcc, s67, v26
	v_and_b32_e32 v234, 0xffff0000, v96
	s_nop 0
	v_addc_co_u32_e32 v31, vcc, 0, v27, vcc
	global_load_dwordx4 v[82:85], v[28:29], off nt
	global_load_dwordx4 v[70:73], v[30:31], off nt
	v_lshlrev_b32_e32 v236, 16, v97
	v_lshlrev_b32_e32 v237, 16, v101
	v_add_co_u32_e32 v28, vcc, s69, v26
	v_and_b32_e32 v101, 0xffff0000, v101
	s_nop 0
	v_addc_co_u32_e32 v29, vcc, 0, v27, vcc
	v_add_co_u32_e32 v30, vcc, s65, v26
	s_lshl_b32 s1, s42, 2
	s_nop 0
	v_addc_co_u32_e32 v31, vcc, 0, v27, vcc
	global_load_dwordx4 v[74:77], v[28:29], off nt
	global_load_dwordx4 v[62:65], v[30:31], off nt
	v_add_co_u32_e32 v28, vcc, s70, v26
	s_waitcnt vmcnt(5)
; __device__ __forceinline__ unsigned cvt_pk_bf16(float lo, float hi) { unsigned r; asm volatile("v_cvt_pk_bf16_f32 %0, %1, %2" : "=v"(r) : "v"(lo), "v"(hi)); return r; }
; #define LAS __attribute__((address_space(3)))
; __device__ __forceinline__ float silu_f(float x) { return x * __builtin_amdgcn_rcpf(1.f + __expf(-x)); }
; template <bool NEED_C>
; __device__ __forceinline__ void ssd_stage(LAS unsigned char* lds, const bf16_t* XBC, const float* cw, const float* cb, const float* DT, const float* a_log, int c, int g, int tid, int lane, int wave) {
;     ...
;             for (int k = 0; k < 19; ++k) { const int tt = t0 - 3 + k;
;                 if (k >= 3 || tt >= 0) raw[k] = *(const u32x4*)(XBC + (size_t)tt * XBCC + col);
;                 else raw[k] = (u32x4){0u, 0u, 0u, 0u}; }
;             asm volatile("" ::: "memory");
; #pragma unroll
;             for (int k = 0; k < 3; ++k) unpack8(raw[k], xw[k]);
; #pragma unroll
;             for (int i = 0; i < 16; ++i) { float xv[8]; unpack8(raw[3 + i], xv);
;                 float o[8];
; #pragma unroll
;                 for (int e = 0; e < 8; ++e) { o[e] = silu_f(b[e] + w[0][e] * xw[0][e] + w[1][e] * xw[1][e] + w[2][e] * xw[2][e] + w[3][e] * xv[e]); xw[0][e] = xw[1][e]; xw[1][e] = xw[2][e]; xw[2][e] = xv[e]; }
;                 u32x4 pk; pk.x = cvt_pk_bf16(o[0], o[1]); pk.y = cvt_pk_bf16(o[2], o[3]); pk.z = cvt_pk_bf16(o[4], o[5]); pk.w = cvt_pk_bf16(o[6], o[7]);
;                 *(LAS u32x4*)(tile + off_b(seg * 16 + i, tch)) = pk; }
	v_lshlrev_b32_e32 v137, 16, v114
	v_pk_mul_f32 v[34:35], v[126:127], v[136:137]
	v_and_b32_e32 v135, 0xffff0000, v114
	v_add_f32_e32 v14, v14, v34
	v_add_f32_e32 v118, v14, v35
	v_mul_f32_e32 v14, 0xbfb8aa3b, v118
	v_exp_f32_e32 v14, v14
	v_lshlrev_b32_e32 v131, 16, v115
	v_lshlrev_b32_e32 v133, 16, v116
	v_addc_co_u32_e32 v29, vcc, 0, v27, vcc
	v_add_f32_e32 v132, 1.0, v14
	v_mov_b32_e32 v14, v107
	v_pk_mul_f32 v[106:107], v[14:15], v[228:229]
	v_add_co_u32_e32 v30, vcc, s71, v26
	v_add_f32_e32 v18, v23, v106
	v_add_f32_e32 v94, v18, v107
	v_mov_b32_e32 v18, v111
	v_pk_mul_f32 v[106:107], v[18:19], v[134:135]
	v_addc_co_u32_e32 v31, vcc, 0, v27, vcc
	v_add_f32_e32 v94, v94, v106
	v_add_f32_e32 v98, v94, v107
	v_mov_b32_e32 v106, v108
	v_mov_b32_e32 v107, v16
	v_pk_mul_f32 v[110:111], v[106:107], v[230:231]
	v_mul_f32_e32 v94, 0xbfb8aa3b, v98
	v_add_f32_e32 v16, v24, v110
	v_add_f32_e32 v16, v16, v111
	v_mov_b32_e32 v110, v112
	v_mov_b32_e32 v111, v20
	v_pk_mul_f32 v[128:129], v[110:111], v[130:131]
	v_exp_f32_e32 v94, v94
	v_add_f32_e32 v16, v16, v128
	v_add_f32_e32 v102, v16, v129
	v_mul_f32_e32 v16, 0xbfb8aa3b, v102
	v_exp_f32_e32 v16, v16
	v_add_f32_e32 v20, 1.0, v94
	v_rcp_f32_e32 v112, v20
	v_and_b32_e32 v129, 0xffff0000, v115
	v_add_f32_e32 v16, 1.0, v16
	v_rcp_f32_e32 v114, v16
	v_mov_b32_e32 v16, v109
	v_pk_mul_f32 v[94:95], v[16:17], v[232:233]
	v_and_b32_e32 v128, 0xffff0000, v103
	v_add_f32_e32 v20, v25, v94
	v_add_f32_e32 v99, v20, v95
	v_mov_b32_e32 v20, v113
	v_pk_mul_f32 v[94:95], v[20:21], v[128:129]
	v_rcp_f32_e32 v108, v132
	v_add_f32_e32 v94, v99, v94
	v_add_f32_e32 v113, v94, v95
	v_mul_f32_e32 v94, 0xbfb8aa3b, v113
	v_exp_f32_e32 v94, v94
	v_mul_f32_e32 v118, v118, v108
	v_mul_f32_e32 v221, v98, v112
	v_lshlrev_b32_e32 v109, 16, v100
	v_add_f32_e32 v94, 1.0, v94
	v_rcp_f32_e32 v112, v94
	v_lshlrev_b32_e32 v108, 16, v96
	v_mov_b32_e32 v94, v86
	v_mov_b32_e32 v95, v2
	v_pk_mul_f32 v[98:99], v[94:95], v[108:109]
	v_lshlrev_b32_e32 v132, 16, v104
	v_add_f32_e32 v2, v10, v98
	v_add_f32_e32 v2, v2, v99
	v_mov_b32_e32 v98, v90
	v_mov_b32_e32 v99, v6
	v_mul_f32_e32 v223, v102, v114
	v_pk_mul_f32 v[102:103], v[98:99], v[132:133]
	v_and_b32_e32 v115, 0xffff0000, v116
	v_add_f32_e32 v2, v2, v102
	v_add_f32_e32 v108, v2, v103
	v_mul_f32_e32 v2, 0xbfb8aa3b, v108
	v_exp_f32_e32 v90, v2
	v_mov_b32_e32 v2, v87
	v_pk_mul_f32 v[86:87], v[2:3], v[234:235]
	v_and_b32_e32 v114, 0xffff0000, v104
	v_add_f32_e32 v6, v11, v86
	v_add_f32_e32 v96, v6, v87
	v_mov_b32_e32 v6, v91
	v_pk_mul_f32 v[86:87], v[6:7], v[114:115]
	v_lshlrev_b32_e32 v102, 16, v105
	v_add_f32_e32 v86, v96, v86
	v_add_f32_e32 v96, v86, v87
	v_mul_f32_e32 v86, 0xbfb8aa3b, v96
	v_exp_f32_e32 v86, v86
	v_add_f32_e32 v87, 1.0, v90
	v_rcp_f32_e32 v116, v87
	v_mov_b32_e32 v87, v4
	v_add_f32_e32 v222, 1.0, v86
	v_mov_b32_e32 v86, v88
	v_pk_mul_f32 v[90:91], v[86:87], v[236:237]
	v_lshlrev_b32_e32 v103, 16, v117
	v_add_f32_e32 v4, v12, v90
	v_add_f32_e32 v4, v4, v91
	v_mov_b32_e32 v90, v92
	v_mov_b32_e32 v91, v8
	v_mul_f32_e32 v104, v113, v112
	v_pk_mul_f32 v[112:113], v[90:91], v[102:103]
	v_and_b32_e32 v100, 0xffff0000, v97
	v_add_f32_e32 v4, v4, v112
	v_add_f32_e32 v92, v4, v113
	v_mul_f32_e32 v4, 0xbfb8aa3b, v92
	v_exp_f32_e32 v224, v4
	v_mov_b32_e32 v4, v89
	v_pk_mul_f32 v[88:89], v[4:5], v[100:101]
	global_load_dwordx4 v[66:69], v[28:29], off nt
	global_load_dwordx4 v[54:57], v[30:31], off nt
	v_add_co_u32_e32 v28, vcc, s72, v26
	v_add_f32_e32 v8, v13, v88
	s_nop 0
	v_addc_co_u32_e32 v29, vcc, 0, v27, vcc
	v_add_f32_e32 v97, v8, v89
	v_and_b32_e32 v113, 0xffff0000, v117
	v_and_b32_e32 v112, 0xffff0000, v105
	v_mov_b32_e32 v8, v93
	v_add_co_u32_e32 v30, vcc, s62, v26
	v_pk_mul_f32 v[88:89], v[8:9], v[112:113]
	s_nop 0
	v_addc_co_u32_e32 v31, vcc, 0, v27, vcc
	v_add_f32_e32 v88, v97, v88
	global_load_dwordx4 v[58:61], v[28:29], off nt
	global_load_dwordx4 v[46:49], v[30:31], off nt
	v_add_co_u32_e32 v28, vcc, s73, v26
	v_add_f32_e32 v88, v88, v89
	s_nop 0
	v_addc_co_u32_e32 v29, vcc, 0, v27, vcc
	v_mul_f32_e32 v89, 0xbfb8aa3b, v88
	v_add_co_u32_e32 v30, vcc, s75, v26
	v_exp_f32_e32 v89, v89
	s_nop 0
	v_addc_co_u32_e32 v31, vcc, 0, v27, vcc
	global_load_dwordx4 v[50:53], v[28:29], off nt
	global_load_dwordx4 v[38:41], v[30:31], off nt
	v_add_co_u32_e32 v28, vcc, s80, v26
	v_add_f32_e32 v89, 1.0, v89
	s_nop 0
	v_addc_co_u32_e32 v29, vcc, 0, v27, vcc
	v_add_co_u32_e32 v30, vcc, s81, v26
	v_add_f32_e32 v97, 1.0, v224
	s_nop 0
	v_addc_co_u32_e32 v31, vcc, 0, v27, vcc
	v_rcp_f32_e32 v89, v89
	global_load_dwordx4 v[42:45], v[28:29], off nt
	s_nop 0
	global_load_dwordx4 v[30:33], v[30:31], off nt
	v_add_co_u32_e32 v28, vcc, s82, v26
	v_rcp_f32_e32 v93, v222
	v_rcp_f32_e32 v97, v97
	v_addc_co_u32_e32 v29, vcc, 0, v27, vcc
	v_add_co_u32_e32 v26, vcc, s83, v26
	v_mul_f32_e32 v105, v108, v116
	s_nop 0
	v_addc_co_u32_e32 v27, vcc, 0, v27, vcc
	v_mul_f32_e32 v88, v88, v89
	v_lshlrev_b32_e32 v116, 4, v220
	global_load_dwordx4 v[34:37], v[28:29], off nt
	s_nop 0
	global_load_dwordx4 v[26:29], v[26:27], off nt
	v_mul_f32_e32 v93, v96, v93
	v_mul_f32_e32 v92, v92, v97
	v_cvt_pk_bf16_f32 v222, v118, v221
	v_cvt_pk_bf16_f32 v223, v223, v104
	v_cvt_pk_bf16_f32 v224, v105, v93
	v_cvt_pk_bf16_f32 v225, v92, v88
	v_add3_u32 v88, v123, v116, v147
	ds_write_b128 v88, v[222:225]
	v_pk_mov_b32 v[88:89], v[226:227], v[136:137] op_sel:[1,0]
	v_xor_b32_e32 v93, 64, v116
	v_pk_mul_f32 v[88:89], v[124:125], v[88:89]
	s_nop 0
	v_add_f32_e32 v88, v22, v88
	v_add_f32_e32 v92, v88, v89
	v_pk_mov_b32 v[88:89], v[228:229], v[134:135] op_sel:[1,0]
	s_nop 0
	v_pk_mul_f32 v[88:89], v[14:15], v[88:89]
	s_nop 0
	v_add_f32_e32 v88, v23, v88
	v_add_f32_e32 v96, v88, v89
	v_pk_mov_b32 v[88:89], v[230:231], v[130:131] op_sel:[1,0]
	v_add3_u32 v230, v123, v93, v147
	v_pk_mul_f32 v[88:89], v[106:107], v[88:89]
	s_nop 0
	v_add_f32_e32 v88, v24, v88
	v_add_f32_e32 v104, v88, v89
	v_pk_mov_b32 v[88:89], v[232:233], v[128:129] op_sel:[1,0]
	s_nop 0
	v_pk_mul_f32 v[88:89], v[16:17], v[88:89]
	s_nop 0
	v_add_f32_e32 v88, v25, v88
	v_add_f32_e32 v105, v88, v89
	v_pk_mov_b32 v[88:89], v[108:109], v[132:133] op_sel:[1,0]
	s_waitcnt vmcnt(13)
; __device__ __forceinline__ unsigned cvt_pk_bf16(float lo, float hi) { unsigned r; asm volatile("v_cvt_pk_bf16_f32 %0, %1, %2" : "=v"(r) : "v"(lo), "v"(hi)); return r; }
; #define LAS __attribute__((address_space(3)))
; __device__ __forceinline__ float silu_f(float x) { return x * __builtin_amdgcn_rcpf(1.f + __expf(-x)); }
; template <bool NEED_C>
; __device__ __forceinline__ void ssd_stage(LAS unsigned char* lds, const bf16_t* XBC, const float* cw, const float* cb, const float* DT, const float* a_log, int c, int g, int tid, int lane, int wave) {
;     ...
;             for (int i = 0; i < 16; ++i) { float xv[8]; unpack8(raw[3 + i], xv);
;                 float o[8];
; #pragma unroll
;                 for (int e = 0; e < 8; ++e) { o[e] = silu_f(b[e] + w[0][e] * xw[0][e] + w[1][e] * xw[1][e] + w[2][e] * xw[2][e] + w[3][e] * xv[e]); xw[0][e] = xw[1][e]; xw[1][e] = xw[2][e]; xw[2][e] = xv[e]; }
;                 u32x4 pk; pk.x = cvt_pk_bf16(o[0], o[1]); pk.y = cvt_pk_bf16(o[2], o[3]); pk.z = cvt_pk_bf16(o[4], o[5]); pk.w = cvt_pk_bf16(o[6], o[7]);
;                 *(LAS u32x4*)(tile + off_b(seg * 16 + i, tch)) = pk; }
	v_lshlrev_b32_e32 v109, 16, v82
	v_pk_mul_f32 v[88:89], v[94:95], v[88:89]
	v_lshlrev_b32_e32 v108, 16, v78
	v_add_f32_e32 v88, v10, v88
	v_add_f32_e32 v117, v88, v89
	v_pk_mov_b32 v[88:89], v[234:235], v[114:115] op_sel:[1,0]
	s_nop 0
	v_pk_mul_f32 v[88:89], v[2:3], v[88:89]
	s_nop 0
	v_add_f32_e32 v88, v11, v88
	v_add_f32_e32 v118, v88, v89
	v_pk_mov_b32 v[88:89], v[236:237], v[102:103] op_sel:[1,0]
	s_nop 0
	v_pk_mul_f32 v[88:89], v[86:87], v[88:89]
	s_nop 0
	v_add_f32_e32 v88, v12, v88
	v_add_f32_e32 v228, v88, v89
	v_pk_mov_b32 v[88:89], v[100:101], v[112:113] op_sel:[1,0]
	s_nop 0
	v_pk_mul_f32 v[88:89], v[4:5], v[88:89]
	s_nop 0
	v_add_f32_e32 v88, v13, v88
	v_add_f32_e32 v229, v88, v89
	v_pk_mul_f32 v[88:89], v[124:125], v[136:137]
	v_pk_mov_b32 v[136:137], v[136:137], v[108:109] op_sel:[1,0]
	v_add_f32_e32 v88, v22, v88
	v_add_f32_e32 v97, v88, v89
	v_pk_mul_f32 v[88:89], v[126:127], v[136:137]
	s_nop 0
	v_add_f32_e32 v88, v92, v88
	v_add_f32_e32 v100, v88, v89
	v_mul_f32_e32 v88, 0xbfb8aa3b, v100
	v_exp_f32_e32 v92, v88
	v_pk_mul_f32 v[88:89], v[126:127], v[108:109]
	s_nop 0
	v_add_f32_e32 v88, v97, v88
	v_add_f32_e32 v97, v88, v89
	v_mul_f32_e32 v88, 0xbfb8aa3b, v97
	v_exp_f32_e32 v88, v88
	v_add_f32_e32 v89, 1.0, v92
	v_rcp_f32_e32 v101, v89
	v_and_b32_e32 v89, 0xffff0000, v82
	v_add_f32_e32 v88, 1.0, v88
	v_rcp_f32_e32 v222, v88
	v_and_b32_e32 v88, 0xffff0000, v78
	v_pk_mov_b32 v[220:221], v[134:135], v[88:89] op_sel:[1,0]
	v_mul_f32_e32 v100, v100, v101
	v_pk_mul_f32 v[92:93], v[18:19], v[220:221]
	v_mul_f32_e32 v231, v97, v222
	v_add_f32_e32 v78, v96, v92
	v_add_f32_e32 v78, v78, v93
	v_mul_f32_e32 v82, 0xbfb8aa3b, v78
	v_pk_mul_f32 v[92:93], v[14:15], v[134:135]
	v_exp_f32_e32 v82, v82
	v_add_f32_e32 v92, v23, v92
	v_add_f32_e32 v96, v92, v93
	v_pk_mul_f32 v[92:93], v[18:19], v[88:89]
	v_add_f32_e32 v82, 1.0, v82
	v_add_f32_e32 v92, v96, v92
	v_add_f32_e32 v223, v92, v93
	v_mul_f32_e32 v92, 0xbfb8aa3b, v223
	v_rcp_f32_e32 v82, v82
	v_exp_f32_e32 v92, v92
	v_lshlrev_b32_e32 v97, 16, v83
	v_lshlrev_b32_e32 v96, 16, v79
	v_pk_mov_b32 v[134:135], v[130:131], v[96:97] op_sel:[1,0]
	v_mul_f32_e32 v78, v78, v82
	v_add_f32_e32 v82, 1.0, v92
	v_pk_mul_f32 v[92:93], v[110:111], v[134:135]
	v_rcp_f32_e32 v82, v82
	v_add_f32_e32 v92, v104, v92
	v_add_f32_e32 v101, v92, v93
	v_mul_f32_e32 v92, 0xbfb8aa3b, v101
	v_exp_f32_e32 v104, v92
	v_pk_mul_f32 v[92:93], v[106:107], v[130:131]
	v_mul_f32_e32 v232, v223, v82
	v_add_f32_e32 v92, v24, v92
	v_add_f32_e32 v130, v92, v93
	v_add_f32_e32 v92, 1.0, v104
	v_rcp_f32_e32 v104, v92
	v_pk_mul_f32 v[92:93], v[110:111], v[96:97]
	v_and_b32_e32 v83, 0xffff0000, v83
	v_add_f32_e32 v92, v130, v92
	v_add_f32_e32 v92, v92, v93
	v_mul_f32_e32 v93, 0xbfb8aa3b, v92
	v_exp_f32_e32 v93, v93
	v_and_b32_e32 v82, 0xffff0000, v79
	v_cvt_pk_bf16_f32 v130, v100, v78
	v_pk_mov_b32 v[222:223], v[128:129], v[82:83] op_sel:[1,0]
	v_add_f32_e32 v78, 1.0, v93
	v_rcp_f32_e32 v93, v78
	v_pk_mul_f32 v[78:79], v[20:21], v[222:223]
	v_mul_f32_e32 v100, v101, v104
	v_add_f32_e32 v78, v105, v78
	v_add_f32_e32 v101, v78, v79
	v_mul_f32_e32 v78, 0xbfb8aa3b, v101
	v_exp_f32_e32 v104, v78
	v_pk_mul_f32 v[78:79], v[16:17], v[128:129]
	v_mul_f32_e32 v233, v92, v93
	v_add_f32_e32 v78, v25, v78
	v_add_f32_e32 v105, v78, v79
	v_add_f32_e32 v78, 1.0, v104
	v_rcp_f32_e32 v104, v78
	v_pk_mul_f32 v[78:79], v[20:21], v[82:83]
	s_nop 0
	v_add_f32_e32 v78, v105, v78
	v_add_f32_e32 v224, v78, v79
	v_mul_f32_e32 v78, 0xbfb8aa3b, v224
	v_exp_f32_e32 v78, v78
	v_mul_f32_e32 v79, v101, v104
	v_cvt_pk_bf16_f32 v131, v100, v79
	v_lshlrev_b32_e32 v105, 16, v84
	v_add_f32_e32 v78, 1.0, v78
	v_rcp_f32_e32 v92, v78
	v_pk_mul_f32 v[78:79], v[94:95], v[132:133]
	v_lshlrev_b32_e32 v104, 16, v80
	v_add_f32_e32 v78, v10, v78
	v_pk_mov_b32 v[128:129], v[132:133], v[104:105] op_sel:[1,0]
	v_add_f32_e32 v93, v78, v79
	v_pk_mul_f32 v[78:79], v[98:99], v[128:129]
	v_mul_f32_e32 v234, v224, v92
	v_add_f32_e32 v78, v117, v78
	v_add_f32_e32 v100, v78, v79
	v_mul_f32_e32 v78, 0xbfb8aa3b, v100
	v_exp_f32_e32 v101, v78
	v_pk_mul_f32 v[78:79], v[98:99], v[104:105]
	s_nop 0
	v_add_f32_e32 v78, v93, v78
	v_add_f32_e32 v117, v78, v79
	v_mul_f32_e32 v78, 0xbfb8aa3b, v117
	v_exp_f32_e32 v78, v78
	v_add_f32_e32 v79, 1.0, v101
	v_rcp_f32_e32 v101, v79
	v_and_b32_e32 v79, 0xffff0000, v84
	v_add_f32_e32 v78, 1.0, v78
	v_rcp_f32_e32 v132, v78
	v_and_b32_e32 v78, 0xffff0000, v80
	v_pk_mov_b32 v[224:225], v[114:115], v[78:79] op_sel:[1,0]
	v_mul_f32_e32 v117, v117, v132
	v_pk_mul_f32 v[92:93], v[6:7], v[224:225]
	s_nop 0
	v_add_f32_e32 v80, v118, v92
	v_add_f32_e32 v80, v80, v93
	v_mul_f32_e32 v84, 0xbfb8aa3b, v80
	v_pk_mul_f32 v[92:93], v[2:3], v[114:115]
	v_exp_f32_e32 v84, v84
	v_add_f32_e32 v92, v11, v92
	v_add_f32_e32 v114, v92, v93
	v_pk_mul_f32 v[92:93], v[6:7], v[78:79]
	v_add_f32_e32 v84, 1.0, v84
	v_add_f32_e32 v92, v114, v92
	v_add_f32_e32 v114, v92, v93
	v_mul_f32_e32 v92, 0xbfb8aa3b, v114
	v_rcp_f32_e32 v84, v84
	v_exp_f32_e32 v92, v92
	v_lshlrev_b32_e32 v93, 16, v85
	v_mul_f32_e32 v115, v100, v101
	v_mul_f32_e32 v80, v80, v84
	v_add_f32_e32 v84, 1.0, v92
	v_lshlrev_b32_e32 v92, 16, v81
	v_pk_mov_b32 v[226:227], v[102:103], v[92:93] op_sel:[1,0]
	v_rcp_f32_e32 v84, v84
	v_pk_mul_f32 v[100:101], v[90:91], v[226:227]
	v_mul_f32_e32 v114, v114, v84
	v_add_f32_e32 v100, v228, v100
	v_add_f32_e32 v118, v100, v101
	v_mul_f32_e32 v100, 0xbfb8aa3b, v118
	v_exp_f32_e32 v132, v100
	v_pk_mul_f32 v[100:101], v[86:87], v[102:103]
	s_nop 0
	v_add_f32_e32 v100, v12, v100
	v_add_f32_e32 v102, v100, v101
	v_add_f32_e32 v100, 1.0, v132
	v_rcp_f32_e32 v103, v100
	v_pk_mul_f32 v[100:101], v[90:91], v[92:93]
	v_cvt_pk_bf16_f32 v132, v115, v80
	v_mul_f32_e32 v103, v118, v103
	v_add_f32_e32 v100, v102, v100
	v_add_f32_e32 v102, v100, v101
	v_mul_f32_e32 v100, 0xbfb8aa3b, v102
	v_exp_f32_e32 v100, v100
	s_nop 0
	v_add_f32_e32 v80, 1.0, v100
	v_pk_mul_f32 v[100:101], v[4:5], v[112:113]
	v_rcp_f32_e32 v115, v80
	v_add_f32_e32 v80, v13, v100
	v_add_f32_e32 v118, v80, v101
	v_and_b32_e32 v101, 0xffff0000, v85
	v_and_b32_e32 v100, 0xffff0000, v81
	v_pk_mov_b32 v[80:81], v[112:113], v[100:101] op_sel:[1,0]
	v_mul_f32_e32 v102, v102, v115
	v_pk_mul_f32 v[84:85], v[8:9], v[80:81]
	v_pk_mul_f32 v[80:81], v[4:5], v[80:81]
	v_add_f32_e32 v84, v229, v84
	v_add_f32_e32 v112, v84, v85
	v_mul_f32_e32 v84, 0xbfb8aa3b, v112
	v_exp_f32_e32 v113, v84
	v_pk_mul_f32 v[84:85], v[8:9], v[100:101]
	v_add_f32_e32 v80, v13, v80
	v_add_f32_e32 v84, v118, v84
	v_add_f32_e32 v84, v84, v85
	v_mul_f32_e32 v85, 0xbfb8aa3b, v84
	v_exp_f32_e32 v85, v85
	v_add_f32_e32 v113, 1.0, v113
	v_rcp_f32_e32 v113, v113
	v_add_f32_e32 v85, 1.0, v85
	v_rcp_f32_e32 v85, v85
	v_mul_f32_e32 v112, v112, v113
	v_cvt_pk_bf16_f32 v133, v103, v112
	ds_write_b128 v230, v[130:133] offset:256
	v_mul_f32_e32 v84, v84, v85
	v_cvt_pk_bf16_f32 v112, v231, v232
	v_cvt_pk_bf16_f32 v113, v233, v234
	v_cvt_pk_bf16_f32 v114, v117, v114
	v_cvt_pk_bf16_f32 v115, v102, v84
	v_xor_b32_e32 v84, 0x80, v116
	v_add3_u32 v84, v123, v84, v147
	ds_write_b128 v84, v[112:115] offset:512
	v_pk_mul_f32 v[84:85], v[124:125], v[136:137]
	v_add_f32_e32 v137, v80, v81
	v_add_f32_e32 v84, v22, v84
	v_add_f32_e32 v112, v84, v85
	v_pk_mul_f32 v[84:85], v[14:15], v[220:221]
	v_pk_mul_f32 v[80:81], v[124:125], v[108:109]
	v_add_f32_e32 v84, v23, v84
	v_add_f32_e32 v113, v84, v85
	v_pk_mul_f32 v[84:85], v[106:107], v[134:135]
	s_waitcnt vmcnt(11)
	v_lshlrev_b32_e32 v103, 16, v74
	v_add_f32_e32 v84, v24, v84
	v_add_f32_e32 v114, v84, v85
	v_pk_mul_f32 v[84:85], v[16:17], v[222:223]
	v_lshlrev_b32_e32 v102, 16, v70
	v_add_f32_e32 v84, v25, v84
	v_add_f32_e32 v115, v84, v85
	v_pk_mul_f32 v[84:85], v[94:95], v[128:129]
	v_add_f32_e32 v80, v22, v80
	v_add_f32_e32 v84, v10, v84
	v_add_f32_e32 v117, v84, v85
	v_pk_mul_f32 v[84:85], v[2:3], v[224:225]
	v_pk_mov_b32 v[108:109], v[108:109], v[102:103] op_sel:[1,0]
	v_add_f32_e32 v84, v11, v84
	v_add_f32_e32 v118, v84, v85
	v_pk_mul_f32 v[84:85], v[86:87], v[226:227]
	s_nop 0
	v_add_f32_e32 v84, v12, v84
	v_add_f32_e32 v136, v84, v85
	v_add_f32_e32 v85, v80, v81
	v_pk_mul_f32 v[80:81], v[126:127], v[108:109]
	v_xor_b32_e32 v84, 0xc0, v116
	v_add_f32_e32 v80, v112, v80
	v_add_f32_e32 v112, v80, v81
	v_mul_f32_e32 v80, 0xbfb8aa3b, v112
	v_exp_f32_e32 v128, v80
	v_pk_mul_f32 v[80:81], v[126:127], v[102:103]
	v_add3_u32 v220, v123, v84, v147
	v_add_f32_e32 v80, v85, v80
	v_add_f32_e32 v130, v80, v81
	v_mul_f32_e32 v80, 0xbfb8aa3b, v130
	v_exp_f32_e32 v80, v80
	v_add_f32_e32 v81, 1.0, v128
	v_rcp_f32_e32 v131, v81
	v_and_b32_e32 v81, 0xffff0000, v74
	v_add_f32_e32 v80, 1.0, v80
	v_rcp_f32_e32 v132, v80
	v_and_b32_e32 v80, 0xffff0000, v70
	v_pk_mov_b32 v[128:129], v[88:89], v[80:81] op_sel:[1,0]
	v_mul_f32_e32 v131, v112, v131
	v_pk_mul_f32 v[84:85], v[18:19], v[128:129]
	v_mul_f32_e32 v221, v130, v132
	v_add_f32_e32 v70, v113, v84
	v_add_f32_e32 v70, v70, v85
	v_mul_f32_e32 v74, 0xbfb8aa3b, v70
	v_pk_mul_f32 v[84:85], v[14:15], v[88:89]
	v_exp_f32_e32 v74, v74
	v_add_f32_e32 v84, v23, v84
	v_add_f32_e32 v88, v84, v85
	v_pk_mul_f32 v[84:85], v[18:19], v[80:81]
	v_add_f32_e32 v74, 1.0, v74
	v_add_f32_e32 v84, v88, v84
	v_add_f32_e32 v133, v84, v85
	v_mul_f32_e32 v84, 0xbfb8aa3b, v133
	v_rcp_f32_e32 v74, v74
	v_exp_f32_e32 v84, v84
	v_lshlrev_b32_e32 v85, 16, v75
	v_and_b32_e32 v75, 0xffff0000, v75
	v_mul_f32_e32 v70, v70, v74
	v_add_f32_e32 v74, 1.0, v84
	v_lshlrev_b32_e32 v84, 16, v71
	v_pk_mov_b32 v[88:89], v[96:97], v[84:85] op_sel:[1,0]
	v_pk_mul_f32 v[96:97], v[106:107], v[96:97]
	v_pk_mul_f32 v[112:113], v[110:111], v[88:89]
	v_add_f32_e32 v96, v24, v96
	v_add_f32_e32 v112, v114, v112
	v_add_f32_e32 v113, v112, v113
	v_mul_f32_e32 v112, 0xbfb8aa3b, v113
	v_exp_f32_e32 v112, v112
	v_add_f32_e32 v114, v96, v97
	v_rcp_f32_e32 v74, v74
	v_add_f32_e32 v96, 1.0, v112
	v_rcp_f32_e32 v130, v96
	v_pk_mul_f32 v[96:97], v[110:111], v[84:85]
	v_mul_f32_e32 v222, v133, v74
	v_add_f32_e32 v96, v114, v96
	v_add_f32_e32 v96, v96, v97
	v_mul_f32_e32 v97, 0xbfb8aa3b, v96
	v_exp_f32_e32 v97, v97
	v_and_b32_e32 v74, 0xffff0000, v71
	v_cvt_pk_bf16_f32 v112, v131, v70
	v_mul_f32_e32 v113, v113, v130
	v_add_f32_e32 v70, 1.0, v97
	v_pk_mov_b32 v[130:131], v[82:83], v[74:75] op_sel:[1,0]
	v_rcp_f32_e32 v97, v70
	v_pk_mul_f32 v[70:71], v[20:21], v[130:131]
	v_mul_f32_e32 v223, v96, v97
	v_add_f32_e32 v70, v115, v70
	v_add_f32_e32 v114, v70, v71
	v_mul_f32_e32 v70, 0xbfb8aa3b, v114
	v_exp_f32_e32 v115, v70
	v_pk_mul_f32 v[70:71], v[16:17], v[82:83]
	v_lshlrev_b32_e32 v97, 16, v76
	v_add_f32_e32 v70, v25, v70
	v_add_f32_e32 v82, v70, v71
	v_add_f32_e32 v70, 1.0, v115
	v_rcp_f32_e32 v83, v70
	v_pk_mul_f32 v[70:71], v[20:21], v[74:75]
	v_lshlrev_b32_e32 v96, 16, v72
	v_add_f32_e32 v70, v82, v70
	v_add_f32_e32 v82, v70, v71
	v_mul_f32_e32 v70, 0xbfb8aa3b, v82
	v_exp_f32_e32 v70, v70
	v_mul_f32_e32 v71, v114, v83
	v_cvt_pk_bf16_f32 v113, v113, v71
	v_add_f32_e32 v70, 1.0, v70
	v_rcp_f32_e32 v83, v70
	v_pk_mul_f32 v[70:71], v[94:95], v[104:105]
	v_pk_mov_b32 v[104:105], v[104:105], v[96:97] op_sel:[1,0]
	v_add_f32_e32 v70, v10, v70
	v_add_f32_e32 v114, v70, v71
	v_pk_mul_f32 v[70:71], v[98:99], v[104:105]
	v_mul_f32_e32 v224, v82, v83
	v_add_f32_e32 v70, v117, v70
	v_add_f32_e32 v115, v70, v71
	v_mul_f32_e32 v70, 0xbfb8aa3b, v115
	v_exp_f32_e32 v117, v70
	v_pk_mul_f32 v[70:71], v[98:99], v[96:97]
	s_nop 0
	v_add_f32_e32 v70, v114, v70
	v_add_f32_e32 v114, v70, v71
	v_mul_f32_e32 v70, 0xbfb8aa3b, v114
	v_exp_f32_e32 v70, v70
	v_add_f32_e32 v71, 1.0, v117
	v_rcp_f32_e32 v117, v71
	v_and_b32_e32 v71, 0xffff0000, v76
	v_add_f32_e32 v70, 1.0, v70
	v_rcp_f32_e32 v134, v70
	v_and_b32_e32 v70, 0xffff0000, v72
	v_pk_mov_b32 v[132:133], v[78:79], v[70:71] op_sel:[1,0]
	v_pk_mul_f32 v[78:79], v[2:3], v[78:79]
	v_pk_mul_f32 v[82:83], v[6:7], v[132:133]
	v_add_f32_e32 v78, v11, v78
	v_add_f32_e32 v72, v118, v82
	v_add_f32_e32 v72, v72, v83
	v_mul_f32_e32 v76, 0xbfb8aa3b, v72
	v_exp_f32_e32 v76, v76
	v_add_f32_e32 v82, v78, v79
	v_pk_mul_f32 v[78:79], v[6:7], v[70:71]
	v_mul_f32_e32 v115, v115, v117
	v_add_f32_e32 v78, v82, v78
	v_add_f32_e32 v118, v78, v79
	v_add_f32_e32 v76, 1.0, v76
	v_mul_f32_e32 v78, 0xbfb8aa3b, v118
	v_rcp_f32_e32 v76, v76
	v_exp_f32_e32 v78, v78
	v_lshlrev_b32_e32 v79, 16, v77
	v_mul_f32_e32 v117, v114, v134
	v_mul_f32_e32 v72, v72, v76
	v_add_f32_e32 v76, 1.0, v78
	v_lshlrev_b32_e32 v78, 16, v73
	v_pk_mov_b32 v[134:135], v[92:93], v[78:79] op_sel:[1,0]
	v_rcp_f32_e32 v76, v76
	v_pk_mul_f32 v[82:83], v[90:91], v[134:135]
	v_mul_f32_e32 v118, v118, v76
	v_add_f32_e32 v82, v136, v82
	v_add_f32_e32 v136, v82, v83
	v_mul_f32_e32 v82, 0xbfb8aa3b, v136
	v_exp_f32_e32 v114, v82
	v_pk_mul_f32 v[82:83], v[86:87], v[92:93]
	s_nop 0
	v_add_f32_e32 v82, v12, v82
	v_add_f32_e32 v92, v82, v83
	v_add_f32_e32 v82, 1.0, v114
	v_rcp_f32_e32 v93, v82
	v_pk_mul_f32 v[82:83], v[90:91], v[78:79]
	v_cvt_pk_bf16_f32 v114, v115, v72
	v_mul_f32_e32 v93, v136, v93
	v_add_f32_e32 v82, v92, v82
	v_add_f32_e32 v92, v82, v83
	v_mul_f32_e32 v82, 0xbfb8aa3b, v92
	v_exp_f32_e32 v82, v82
	s_nop 0
	v_add_f32_e32 v72, 1.0, v82
	v_pk_mul_f32 v[82:83], v[4:5], v[100:101]
	v_rcp_f32_e32 v115, v72
	v_add_f32_e32 v72, v13, v82
	v_add_f32_e32 v136, v72, v83
	v_and_b32_e32 v83, 0xffff0000, v77
	v_and_b32_e32 v82, 0xffff0000, v73
	v_pk_mov_b32 v[72:73], v[100:101], v[82:83] op_sel:[1,0]
	v_mul_f32_e32 v92, v92, v115
	v_pk_mul_f32 v[76:77], v[8:9], v[72:73]
	v_pk_mul_f32 v[72:73], v[4:5], v[72:73]
	v_add_f32_e32 v76, v137, v76
	v_add_f32_e32 v100, v76, v77
	v_mul_f32_e32 v76, 0xbfb8aa3b, v100
	v_exp_f32_e32 v101, v76
	v_pk_mul_f32 v[76:77], v[8:9], v[82:83]
	v_add_f32_e32 v72, v13, v72
	v_add_f32_e32 v76, v136, v76
	v_add_f32_e32 v76, v76, v77
	v_mul_f32_e32 v77, 0xbfb8aa3b, v76
	v_exp_f32_e32 v77, v77
	v_add_f32_e32 v101, 1.0, v101
	v_rcp_f32_e32 v101, v101
	v_add_f32_e32 v77, 1.0, v77
	v_rcp_f32_e32 v77, v77
	v_mul_f32_e32 v100, v100, v101
	v_cvt_pk_bf16_f32 v115, v93, v100
	ds_write_b128 v220, v[112:115] offset:768
	v_mul_f32_e32 v76, v76, v77
	v_cvt_pk_bf16_f32 v112, v221, v222
	v_cvt_pk_bf16_f32 v113, v223, v224
	v_cvt_pk_bf16_f32 v114, v117, v118
	v_cvt_pk_bf16_f32 v115, v92, v76
	v_xor_b32_e32 v76, 16, v116
	v_add3_u32 v76, v123, v76, v147
	ds_write_b128 v76, v[112:115] offset:1024
	v_pk_mul_f32 v[76:77], v[124:125], v[108:109]
	s_nop 0
	v_add_f32_e32 v76, v22, v76
	v_add_f32_e32 v100, v76, v77
	v_pk_mul_f32 v[76:77], v[14:15], v[128:129]
	s_nop 0
	v_add_f32_e32 v76, v23, v76
	v_add_f32_e32 v101, v76, v77
	v_pk_mul_f32 v[76:77], v[106:107], v[88:89]
	s_waitcnt vmcnt(9)
	v_lshlrev_b32_e32 v89, 16, v66
	v_add_f32_e32 v76, v24, v76
	v_add_f32_e32 v112, v76, v77
	v_pk_mul_f32 v[76:77], v[16:17], v[130:131]
	v_add_f32_e32 v130, v72, v73
	v_add_f32_e32 v76, v25, v76
	v_add_f32_e32 v114, v76, v77
	v_pk_mul_f32 v[76:77], v[94:95], v[104:105]
	v_pk_mul_f32 v[72:73], v[124:125], v[102:103]
	v_add_f32_e32 v76, v10, v76
	v_add_f32_e32 v115, v76, v77
	v_pk_mul_f32 v[76:77], v[2:3], v[132:133]
	v_lshlrev_b32_e32 v88, 16, v62
	v_add_f32_e32 v76, v11, v76
	v_add_f32_e32 v117, v76, v77
	v_pk_mul_f32 v[76:77], v[86:87], v[134:135]
	v_add_f32_e32 v72, v22, v72
	v_add_f32_e32 v76, v12, v76
	v_pk_mov_b32 v[92:93], v[102:103], v[88:89] op_sel:[1,0]
	v_add_f32_e32 v118, v76, v77
	v_add_f32_e32 v77, v72, v73
	v_pk_mul_f32 v[72:73], v[126:127], v[92:93]
	v_xor_b32_e32 v76, 0x50, v116
	v_add_f32_e32 v72, v100, v72
	v_add_f32_e32 v100, v72, v73
	v_mul_f32_e32 v72, 0xbfb8aa3b, v100
	v_exp_f32_e32 v102, v72
	v_pk_mul_f32 v[72:73], v[126:127], v[88:89]
	v_add3_u32 v131, v123, v76, v147
	v_add_f32_e32 v72, v77, v72
	v_add_f32_e32 v103, v72, v73
	v_mul_f32_e32 v72, 0xbfb8aa3b, v103
	v_exp_f32_e32 v72, v72
	v_add_f32_e32 v73, 1.0, v102
	v_rcp_f32_e32 v102, v73
	v_and_b32_e32 v73, 0xffff0000, v66
	v_add_f32_e32 v72, 1.0, v72
	v_rcp_f32_e32 v108, v72
	v_and_b32_e32 v72, 0xffff0000, v62
	v_pk_mov_b32 v[104:105], v[80:81], v[72:73] op_sel:[1,0]
	v_mul_f32_e32 v100, v100, v102
	v_pk_mul_f32 v[76:77], v[18:19], v[104:105]
	v_mul_f32_e32 v132, v103, v108
	v_add_f32_e32 v62, v101, v76
	v_add_f32_e32 v62, v62, v77
	v_mul_f32_e32 v66, 0xbfb8aa3b, v62
	v_pk_mul_f32 v[76:77], v[14:15], v[80:81]
	v_exp_f32_e32 v66, v66
	v_add_f32_e32 v76, v23, v76
	v_add_f32_e32 v80, v76, v77
	v_pk_mul_f32 v[76:77], v[18:19], v[72:73]
	v_add_f32_e32 v66, 1.0, v66
	v_add_f32_e32 v76, v80, v76
	v_add_f32_e32 v101, v76, v77
	v_mul_f32_e32 v76, 0xbfb8aa3b, v101
	v_rcp_f32_e32 v66, v66
	v_exp_f32_e32 v76, v76
	v_lshlrev_b32_e32 v77, 16, v67
	v_and_b32_e32 v67, 0xffff0000, v67
	v_mul_f32_e32 v62, v62, v66
	v_add_f32_e32 v66, 1.0, v76
	v_lshlrev_b32_e32 v76, 16, v63
	v_pk_mov_b32 v[108:109], v[84:85], v[76:77] op_sel:[1,0]
	v_rcp_f32_e32 v66, v66
	v_pk_mul_f32 v[80:81], v[110:111], v[108:109]
	v_cvt_pk_bf16_f32 v100, v100, v62
	s_nop 0
	v_add_f32_e32 v80, v112, v80
	v_add_f32_e32 v102, v80, v81
	v_mul_f32_e32 v80, 0xbfb8aa3b, v102
	v_exp_f32_e32 v103, v80
	v_pk_mul_f32 v[80:81], v[106:107], v[84:85]
	s_nop 0
	v_add_f32_e32 v80, v24, v80
	v_add_f32_e32 v84, v80, v81
	v_add_f32_e32 v80, 1.0, v103
	v_rcp_f32_e32 v85, v80
	v_pk_mul_f32 v[80:81], v[110:111], v[76:77]
	v_mul_f32_e32 v85, v102, v85
	v_add_f32_e32 v80, v84, v80
	v_add_f32_e32 v80, v80, v81
	v_mul_f32_e32 v81, 0xbfb8aa3b, v80
	v_exp_f32_e32 v81, v81
	v_mul_f32_e32 v84, v101, v66
	v_and_b32_e32 v66, 0xffff0000, v63
	v_pk_mov_b32 v[112:113], v[74:75], v[66:67] op_sel:[1,0]
	v_add_f32_e32 v62, 1.0, v81
	v_rcp_f32_e32 v81, v62
	v_pk_mul_f32 v[62:63], v[20:21], v[112:113]
	v_mul_f32_e32 v133, v80, v81
	v_add_f32_e32 v62, v114, v62
	v_add_f32_e32 v101, v62, v63
	v_mul_f32_e32 v62, 0xbfb8aa3b, v101
	v_exp_f32_e32 v102, v62
	v_pk_mul_f32 v[62:63], v[16:17], v[74:75]
	v_lshlrev_b32_e32 v81, 16, v68
	v_add_f32_e32 v62, v25, v62
	v_add_f32_e32 v74, v62, v63
	v_add_f32_e32 v62, 1.0, v102
	v_rcp_f32_e32 v75, v62
	v_pk_mul_f32 v[62:63], v[20:21], v[66:67]
	v_lshlrev_b32_e32 v80, 16, v64
	v_add_f32_e32 v62, v74, v62
	v_add_f32_e32 v74, v62, v63
	v_mul_f32_e32 v62, 0xbfb8aa3b, v74
	v_exp_f32_e32 v62, v62
	v_mul_f32_e32 v63, v101, v75
	v_cvt_pk_bf16_f32 v101, v85, v63
	v_add_f32_e32 v62, 1.0, v62
	v_rcp_f32_e32 v75, v62
	v_pk_mul_f32 v[62:63], v[94:95], v[96:97]
	v_pk_mov_b32 v[96:97], v[96:97], v[80:81] op_sel:[1,0]
	v_add_f32_e32 v62, v10, v62
	v_add_f32_e32 v85, v62, v63
	v_pk_mul_f32 v[62:63], v[98:99], v[96:97]
	v_mul_f32_e32 v134, v74, v75
	v_add_f32_e32 v62, v115, v62
	v_add_f32_e32 v102, v62, v63
	v_mul_f32_e32 v62, 0xbfb8aa3b, v102
	v_exp_f32_e32 v103, v62
	v_pk_mul_f32 v[62:63], v[98:99], v[80:81]
	s_nop 0
	v_add_f32_e32 v62, v85, v62
	v_add_f32_e32 v85, v62, v63
	v_mul_f32_e32 v62, 0xbfb8aa3b, v85
	v_exp_f32_e32 v62, v62
	v_add_f32_e32 v63, 1.0, v103
	v_rcp_f32_e32 v103, v63
	v_and_b32_e32 v63, 0xffff0000, v68
	v_add_f32_e32 v62, 1.0, v62
	v_rcp_f32_e32 v128, v62
	v_and_b32_e32 v62, 0xffff0000, v64
	v_pk_mov_b32 v[114:115], v[70:71], v[62:63] op_sel:[1,0]
	v_pk_mul_f32 v[70:71], v[2:3], v[70:71]
	v_pk_mul_f32 v[74:75], v[6:7], v[114:115]
	v_add_f32_e32 v70, v11, v70
	v_add_f32_e32 v64, v117, v74
	v_add_f32_e32 v64, v64, v75
	v_mul_f32_e32 v68, 0xbfb8aa3b, v64
	v_exp_f32_e32 v68, v68
	v_add_f32_e32 v74, v70, v71
	v_pk_mul_f32 v[70:71], v[6:7], v[62:63]
	v_mul_f32_e32 v85, v85, v128
	v_add_f32_e32 v70, v74, v70
	v_add_f32_e32 v117, v70, v71
	v_add_f32_e32 v68, 1.0, v68
	v_mul_f32_e32 v70, 0xbfb8aa3b, v117
	v_rcp_f32_e32 v68, v68
	v_exp_f32_e32 v70, v70
	v_lshlrev_b32_e32 v71, 16, v69
	v_mul_f32_e32 v102, v102, v103
	v_mul_f32_e32 v64, v64, v68
	v_add_f32_e32 v68, 1.0, v70
	v_lshlrev_b32_e32 v70, 16, v65
	v_pk_mov_b32 v[128:129], v[78:79], v[70:71] op_sel:[1,0]
	v_rcp_f32_e32 v68, v68
	v_pk_mul_f32 v[74:75], v[90:91], v[128:129]
	v_cvt_pk_bf16_f32 v102, v102, v64
	v_mul_f32_e32 v117, v117, v68
	v_add_f32_e32 v74, v118, v74
	v_add_f32_e32 v103, v74, v75
	v_mul_f32_e32 v74, 0xbfb8aa3b, v103
	v_exp_f32_e32 v118, v74
	v_pk_mul_f32 v[74:75], v[86:87], v[78:79]
	s_nop 0
	v_add_f32_e32 v74, v12, v74
	v_add_f32_e32 v78, v74, v75
	v_add_f32_e32 v74, 1.0, v118
	v_rcp_f32_e32 v79, v74
	v_pk_mul_f32 v[74:75], v[90:91], v[70:71]
	v_mul_f32_e32 v79, v103, v79
	v_add_f32_e32 v74, v78, v74
	v_add_f32_e32 v78, v74, v75
	v_mul_f32_e32 v74, 0xbfb8aa3b, v78
	v_exp_f32_e32 v74, v74
	s_nop 0
	v_add_f32_e32 v64, 1.0, v74
	v_pk_mul_f32 v[74:75], v[4:5], v[82:83]
	v_rcp_f32_e32 v103, v64
	v_add_f32_e32 v64, v13, v74
	v_add_f32_e32 v118, v64, v75
	v_and_b32_e32 v75, 0xffff0000, v69
	v_and_b32_e32 v74, 0xffff0000, v65
	v_pk_mov_b32 v[64:65], v[82:83], v[74:75] op_sel:[1,0]
	v_mul_f32_e32 v78, v78, v103
	v_pk_mul_f32 v[68:69], v[8:9], v[64:65]
	v_pk_mul_f32 v[64:65], v[4:5], v[64:65]
	v_add_f32_e32 v68, v130, v68
	v_add_f32_e32 v82, v68, v69
	v_mul_f32_e32 v68, 0xbfb8aa3b, v82
	v_exp_f32_e32 v83, v68
	v_pk_mul_f32 v[68:69], v[8:9], v[74:75]
	v_add_f32_e32 v64, v13, v64
	v_add_f32_e32 v68, v118, v68
	v_add_f32_e32 v68, v68, v69
	v_mul_f32_e32 v69, 0xbfb8aa3b, v68
	v_exp_f32_e32 v69, v69
	v_add_f32_e32 v83, 1.0, v83
	v_rcp_f32_e32 v83, v83
	v_add_f32_e32 v69, 1.0, v69
	v_rcp_f32_e32 v69, v69
	v_mul_f32_e32 v82, v82, v83
	v_cvt_pk_bf16_f32 v103, v79, v82
	ds_write_b128 v131, v[100:103] offset:1280
	v_mul_f32_e32 v68, v68, v69
	v_cvt_pk_bf16_f32 v82, v132, v84
	v_cvt_pk_bf16_f32 v83, v133, v134
	v_cvt_pk_bf16_f32 v84, v85, v117
	v_cvt_pk_bf16_f32 v85, v78, v68
	v_xor_b32_e32 v68, 0x90, v116
	v_add3_u32 v68, v123, v68, v147
	ds_write_b128 v68, v[82:85] offset:1536
	v_pk_mul_f32 v[68:69], v[124:125], v[92:93]
	s_waitcnt vmcnt(7)
	v_lshlrev_b32_e32 v79, 16, v58
	v_add_f32_e32 v68, v22, v68
	v_add_f32_e32 v82, v68, v69
	v_pk_mul_f32 v[68:69], v[14:15], v[104:105]
	v_add_f32_e32 v105, v64, v65
	v_add_f32_e32 v68, v23, v68
	v_add_f32_e32 v83, v68, v69
	v_pk_mul_f32 v[68:69], v[106:107], v[108:109]
	v_pk_mul_f32 v[64:65], v[124:125], v[88:89]
	v_add_f32_e32 v68, v24, v68
	v_add_f32_e32 v84, v68, v69
	v_pk_mul_f32 v[68:69], v[16:17], v[112:113]
	v_lshlrev_b32_e32 v78, 16, v54
	v_add_f32_e32 v68, v25, v68
	v_add_f32_e32 v85, v68, v69
	v_pk_mul_f32 v[68:69], v[94:95], v[96:97]
	v_add_f32_e32 v64, v22, v64
	v_add_f32_e32 v68, v10, v68
	v_add_f32_e32 v100, v68, v69
	v_pk_mul_f32 v[68:69], v[2:3], v[114:115]
	v_pk_mov_b32 v[88:89], v[88:89], v[78:79] op_sel:[1,0]
	v_add_f32_e32 v68, v11, v68
	v_add_f32_e32 v102, v68, v69
	v_pk_mul_f32 v[68:69], v[86:87], v[128:129]
	s_nop 0
	v_add_f32_e32 v68, v12, v68
	v_add_f32_e32 v104, v68, v69
	v_add_f32_e32 v69, v64, v65
	v_pk_mul_f32 v[64:65], v[126:127], v[88:89]
	v_xor_b32_e32 v68, 0xd0, v116
	v_add_f32_e32 v64, v82, v64
	v_add_f32_e32 v82, v64, v65
	v_mul_f32_e32 v64, 0xbfb8aa3b, v82
	v_exp_f32_e32 v92, v64
	v_pk_mul_f32 v[64:65], v[126:127], v[78:79]
	v_add3_u32 v108, v123, v68, v147
	v_add_f32_e32 v64, v69, v64
	v_add_f32_e32 v96, v64, v65
	v_mul_f32_e32 v64, 0xbfb8aa3b, v96
	v_exp_f32_e32 v64, v64
	v_add_f32_e32 v65, 1.0, v92
	v_rcp_f32_e32 v97, v65
	v_and_b32_e32 v65, 0xffff0000, v58
	v_add_f32_e32 v64, 1.0, v64
	v_rcp_f32_e32 v101, v64
	v_and_b32_e32 v64, 0xffff0000, v54
	v_pk_mov_b32 v[92:93], v[72:73], v[64:65] op_sel:[1,0]
	v_mul_f32_e32 v97, v82, v97
	v_pk_mul_f32 v[68:69], v[18:19], v[92:93]
	v_mul_f32_e32 v109, v96, v101
	v_add_f32_e32 v54, v83, v68
	v_add_f32_e32 v54, v54, v69
	v_mul_f32_e32 v58, 0xbfb8aa3b, v54
	v_pk_mul_f32 v[68:69], v[14:15], v[72:73]
	v_exp_f32_e32 v58, v58
	v_add_f32_e32 v68, v23, v68
	v_add_f32_e32 v72, v68, v69
	v_pk_mul_f32 v[68:69], v[18:19], v[64:65]
	v_add_f32_e32 v58, 1.0, v58
	v_add_f32_e32 v68, v72, v68
	v_add_f32_e32 v103, v68, v69
	v_mul_f32_e32 v68, 0xbfb8aa3b, v103
	v_rcp_f32_e32 v58, v58
	v_exp_f32_e32 v68, v68
	v_lshlrev_b32_e32 v69, 16, v59
	v_and_b32_e32 v59, 0xffff0000, v59
	v_mul_f32_e32 v54, v54, v58
	v_add_f32_e32 v58, 1.0, v68
	v_lshlrev_b32_e32 v68, 16, v55
	v_pk_mov_b32 v[72:73], v[76:77], v[68:69] op_sel:[1,0]
	v_pk_mul_f32 v[76:77], v[106:107], v[76:77]
	v_pk_mul_f32 v[82:83], v[110:111], v[72:73]
	v_add_f32_e32 v76, v24, v76
	v_add_f32_e32 v82, v84, v82
	v_add_f32_e32 v83, v82, v83
	v_mul_f32_e32 v82, 0xbfb8aa3b, v83
	v_exp_f32_e32 v82, v82
	v_add_f32_e32 v84, v76, v77
	v_rcp_f32_e32 v58, v58
	v_add_f32_e32 v76, 1.0, v82
	v_rcp_f32_e32 v96, v76
	v_pk_mul_f32 v[76:77], v[110:111], v[68:69]
	v_mul_f32_e32 v112, v103, v58
	v_add_f32_e32 v76, v84, v76
	v_add_f32_e32 v76, v76, v77
	v_mul_f32_e32 v77, 0xbfb8aa3b, v76
	v_exp_f32_e32 v77, v77
	v_and_b32_e32 v58, 0xffff0000, v55
	v_cvt_pk_bf16_f32 v82, v97, v54
	v_mul_f32_e32 v83, v83, v96
	v_add_f32_e32 v54, 1.0, v77
	v_pk_mov_b32 v[96:97], v[66:67], v[58:59] op_sel:[1,0]
	v_rcp_f32_e32 v77, v54
	v_pk_mul_f32 v[54:55], v[20:21], v[96:97]
	v_mul_f32_e32 v113, v76, v77
	v_add_f32_e32 v54, v85, v54
	v_add_f32_e32 v84, v54, v55
	v_mul_f32_e32 v54, 0xbfb8aa3b, v84
	v_exp_f32_e32 v85, v54
	v_pk_mul_f32 v[54:55], v[16:17], v[66:67]
	v_lshlrev_b32_e32 v77, 16, v60
	v_add_f32_e32 v54, v25, v54
	v_add_f32_e32 v66, v54, v55
	v_add_f32_e32 v54, 1.0, v85
	v_rcp_f32_e32 v67, v54
	v_pk_mul_f32 v[54:55], v[20:21], v[58:59]
	v_lshlrev_b32_e32 v76, 16, v56
	v_add_f32_e32 v54, v66, v54
	v_add_f32_e32 v66, v54, v55
	v_mul_f32_e32 v54, 0xbfb8aa3b, v66
	v_exp_f32_e32 v54, v54
	v_mul_f32_e32 v55, v84, v67
	v_cvt_pk_bf16_f32 v83, v83, v55
	v_add_f32_e32 v54, 1.0, v54
	v_rcp_f32_e32 v67, v54
	v_pk_mul_f32 v[54:55], v[94:95], v[80:81]
	v_pk_mov_b32 v[80:81], v[80:81], v[76:77] op_sel:[1,0]
	v_add_f32_e32 v54, v10, v54
	v_add_f32_e32 v84, v54, v55
	v_pk_mul_f32 v[54:55], v[98:99], v[80:81]
	v_mul_f32_e32 v114, v66, v67
	v_add_f32_e32 v54, v100, v54
	v_add_f32_e32 v85, v54, v55
	v_mul_f32_e32 v54, 0xbfb8aa3b, v85
	v_exp_f32_e32 v100, v54
	v_pk_mul_f32 v[54:55], v[98:99], v[76:77]
	s_nop 0
	v_add_f32_e32 v54, v84, v54
	v_add_f32_e32 v84, v54, v55
	v_mul_f32_e32 v54, 0xbfb8aa3b, v84
	v_exp_f32_e32 v54, v54
	v_add_f32_e32 v55, 1.0, v100
	v_rcp_f32_e32 v103, v55
	v_and_b32_e32 v55, 0xffff0000, v60
	v_add_f32_e32 v54, 1.0, v54
	v_rcp_f32_e32 v115, v54
	v_and_b32_e32 v54, 0xffff0000, v56
	v_pk_mov_b32 v[100:101], v[62:63], v[54:55] op_sel:[1,0]
	v_pk_mul_f32 v[62:63], v[2:3], v[62:63]
	v_pk_mul_f32 v[66:67], v[6:7], v[100:101]
	v_add_f32_e32 v62, v11, v62
	v_add_f32_e32 v56, v102, v66
	v_add_f32_e32 v56, v56, v67
	v_mul_f32_e32 v60, 0xbfb8aa3b, v56
	v_exp_f32_e32 v60, v60
	v_add_f32_e32 v66, v62, v63
	v_pk_mul_f32 v[62:63], v[6:7], v[54:55]
	v_lshlrev_b32_e32 v67, 16, v61
	v_add_f32_e32 v62, v66, v62
	v_add_f32_e32 v117, v62, v63
	v_add_f32_e32 v60, 1.0, v60
	v_mul_f32_e32 v62, 0xbfb8aa3b, v117
	v_rcp_f32_e32 v60, v60
	v_exp_f32_e32 v62, v62
	v_lshlrev_b32_e32 v66, 16, v57
	v_mul_f32_e32 v85, v85, v103
	v_pk_mov_b32 v[102:103], v[70:71], v[66:67] op_sel:[1,0]
	v_mul_f32_e32 v56, v56, v60
	v_add_f32_e32 v60, 1.0, v62
	v_pk_mul_f32 v[62:63], v[90:91], v[102:103]
	v_mul_f32_e32 v115, v84, v115
	v_add_f32_e32 v62, v104, v62
	v_add_f32_e32 v104, v62, v63
	v_mul_f32_e32 v62, 0xbfb8aa3b, v104
	v_exp_f32_e32 v84, v62
	v_pk_mul_f32 v[62:63], v[86:87], v[70:71]
	v_rcp_f32_e32 v60, v60
	v_add_f32_e32 v62, v12, v62
	v_add_f32_e32 v70, v62, v63
	v_add_f32_e32 v62, 1.0, v84
	v_rcp_f32_e32 v71, v62
	v_pk_mul_f32 v[62:63], v[90:91], v[66:67]
	v_cvt_pk_bf16_f32 v84, v85, v56
	v_mul_f32_e32 v117, v117, v60
	v_add_f32_e32 v62, v70, v62
	v_add_f32_e32 v118, v62, v63
	v_mul_f32_e32 v62, 0xbfb8aa3b, v118
	v_exp_f32_e32 v62, v62
	v_mul_f32_e32 v85, v104, v71
	v_and_b32_e32 v71, 0xffff0000, v61
	v_and_b32_e32 v70, 0xffff0000, v57
	v_add_f32_e32 v56, 1.0, v62
	v_pk_mul_f32 v[62:63], v[4:5], v[74:75]
	v_rcp_f32_e32 v104, v56
	v_add_f32_e32 v56, v13, v62
	v_add_f32_e32 v62, v56, v63
	v_pk_mov_b32 v[56:57], v[74:75], v[70:71] op_sel:[1,0]
	s_nop 0
	v_pk_mul_f32 v[60:61], v[8:9], v[56:57]
	v_pk_mul_f32 v[56:57], v[4:5], v[56:57]
	v_add_f32_e32 v60, v105, v60
	v_add_f32_e32 v63, v60, v61
	v_mul_f32_e32 v60, 0xbfb8aa3b, v63
	v_exp_f32_e32 v74, v60
	v_pk_mul_f32 v[60:61], v[8:9], v[70:71]
	v_add_f32_e32 v56, v13, v56
	v_add_f32_e32 v60, v62, v60
	v_add_f32_e32 v60, v60, v61
	v_mul_f32_e32 v61, 0xbfb8aa3b, v60
	v_exp_f32_e32 v61, v61
	v_add_f32_e32 v62, 1.0, v74
	v_rcp_f32_e32 v62, v62
	v_mul_f32_e32 v74, v118, v104
	v_add_f32_e32 v61, 1.0, v61
	v_rcp_f32_e32 v61, v61
	v_mul_f32_e32 v62, v63, v62
	v_cvt_pk_bf16_f32 v85, v85, v62
	ds_write_b128 v108, v[82:85] offset:1792
	v_mul_f32_e32 v63, v60, v61
	v_cvt_pk_bf16_f32 v60, v109, v112
	v_cvt_pk_bf16_f32 v61, v113, v114
	v_cvt_pk_bf16_f32 v62, v115, v117
	v_cvt_pk_bf16_f32 v63, v74, v63
	v_xor_b32_e32 v74, 32, v116
	v_add3_u32 v74, v123, v74, v147
	ds_write_b128 v74, v[60:63] offset:2048
	v_pk_mul_f32 v[60:61], v[124:125], v[88:89]
	v_add_f32_e32 v89, v56, v57
	v_add_f32_e32 v60, v22, v60
	v_add_f32_e32 v62, v60, v61
	v_pk_mul_f32 v[60:61], v[14:15], v[92:93]
	v_pk_mul_f32 v[56:57], v[124:125], v[78:79]
	v_add_f32_e32 v60, v23, v60
	v_add_f32_e32 v63, v60, v61
	v_pk_mul_f32 v[60:61], v[106:107], v[72:73]
	s_waitcnt vmcnt(5)
	v_lshlrev_b32_e32 v73, 16, v50
	v_add_f32_e32 v60, v24, v60
	v_add_f32_e32 v82, v60, v61
	v_pk_mul_f32 v[60:61], v[16:17], v[96:97]
	v_lshlrev_b32_e32 v72, 16, v46
	v_add_f32_e32 v60, v25, v60
	v_add_f32_e32 v83, v60, v61
	v_pk_mul_f32 v[60:61], v[94:95], v[80:81]
	v_add_f32_e32 v56, v22, v56
	v_add_f32_e32 v60, v10, v60
	v_add_f32_e32 v80, v60, v61
	v_pk_mul_f32 v[60:61], v[2:3], v[100:101]
	v_pk_mov_b32 v[74:75], v[78:79], v[72:73] op_sel:[1,0]
	v_add_f32_e32 v60, v11, v60
	v_add_f32_e32 v84, v60, v61
	v_pk_mul_f32 v[60:61], v[86:87], v[102:103]
	s_nop 0
	v_add_f32_e32 v60, v12, v60
	v_add_f32_e32 v88, v60, v61
	v_add_f32_e32 v61, v56, v57
	v_pk_mul_f32 v[56:57], v[126:127], v[74:75]
	v_xor_b32_e32 v60, 0x60, v116
	v_add_f32_e32 v56, v62, v56
	v_add_f32_e32 v62, v56, v57
	v_mul_f32_e32 v56, 0xbfb8aa3b, v62
	v_exp_f32_e32 v78, v56
	v_pk_mul_f32 v[56:57], v[126:127], v[72:73]
	v_add3_u32 v92, v123, v60, v147
	v_add_f32_e32 v56, v61, v56
	v_add_f32_e32 v81, v56, v57
	v_mul_f32_e32 v56, 0xbfb8aa3b, v81
	v_exp_f32_e32 v56, v56
	v_add_f32_e32 v57, 1.0, v78
	v_rcp_f32_e32 v85, v57
	v_and_b32_e32 v57, 0xffff0000, v50
	v_add_f32_e32 v56, 1.0, v56
	v_rcp_f32_e32 v93, v56
	v_and_b32_e32 v56, 0xffff0000, v46
	v_pk_mov_b32 v[78:79], v[64:65], v[56:57] op_sel:[1,0]
	v_mul_f32_e32 v85, v62, v85
	v_pk_mul_f32 v[60:61], v[18:19], v[78:79]
	v_lshlrev_b32_e32 v62, 16, v47
	v_add_f32_e32 v46, v63, v60
	v_add_f32_e32 v46, v46, v61
	v_mul_f32_e32 v50, 0xbfb8aa3b, v46
	v_pk_mul_f32 v[60:61], v[14:15], v[64:65]
	v_exp_f32_e32 v50, v50
	v_add_f32_e32 v60, v23, v60
	v_add_f32_e32 v63, v60, v61
	v_pk_mul_f32 v[60:61], v[18:19], v[56:57]
	v_add_f32_e32 v50, 1.0, v50
	v_add_f32_e32 v60, v63, v60
	v_add_f32_e32 v96, v60, v61
	v_mul_f32_e32 v60, 0xbfb8aa3b, v96
	v_rcp_f32_e32 v50, v50
	v_exp_f32_e32 v60, v60
	v_lshlrev_b32_e32 v63, 16, v51
	v_pk_mov_b32 v[64:65], v[68:69], v[62:63] op_sel:[1,0]
	v_mul_f32_e32 v46, v46, v50
	v_add_f32_e32 v50, 1.0, v60
	v_pk_mul_f32 v[60:61], v[110:111], v[64:65]
	v_mul_f32_e32 v93, v81, v93
	v_add_f32_e32 v60, v82, v60
	v_add_f32_e32 v81, v60, v61
	v_mul_f32_e32 v60, 0xbfb8aa3b, v81
	v_exp_f32_e32 v82, v60
	v_pk_mul_f32 v[60:61], v[106:107], v[68:69]
	v_rcp_f32_e32 v50, v50
	v_add_f32_e32 v60, v24, v60
	v_add_f32_e32 v68, v60, v61
	v_add_f32_e32 v60, 1.0, v82
	v_rcp_f32_e32 v69, v60
	v_pk_mul_f32 v[60:61], v[110:111], v[62:63]
	v_mul_f32_e32 v96, v96, v50
	v_add_f32_e32 v60, v68, v60
	v_add_f32_e32 v82, v60, v61
	v_mul_f32_e32 v60, 0xbfb8aa3b, v82
	v_exp_f32_e32 v60, v60
	v_and_b32_e32 v61, 0xffff0000, v51
	v_cvt_pk_bf16_f32 v46, v85, v46
	v_mul_f32_e32 v81, v81, v69
	v_add_f32_e32 v50, 1.0, v60
	v_and_b32_e32 v60, 0xffff0000, v47
	v_rcp_f32_e32 v85, v50
	v_pk_mov_b32 v[50:51], v[58:59], v[60:61] op_sel:[1,0]
	v_pk_mul_f32 v[58:59], v[16:17], v[58:59]
	v_pk_mul_f32 v[68:69], v[20:21], v[50:51]
	v_add_f32_e32 v58, v25, v58
	v_add_f32_e32 v47, v83, v68
	v_add_f32_e32 v47, v47, v69
	v_mul_f32_e32 v68, 0xbfb8aa3b, v47
	v_exp_f32_e32 v68, v68
	v_add_f32_e32 v69, v58, v59
	v_mul_f32_e32 v97, v82, v85
	v_add_f32_e32 v58, 1.0, v68
	v_rcp_f32_e32 v68, v58
	v_pk_mul_f32 v[58:59], v[20:21], v[60:61]
	v_mul_f32_e32 v47, v47, v68
	v_add_f32_e32 v58, v69, v58
	v_add_f32_e32 v83, v58, v59
	v_mul_f32_e32 v58, 0xbfb8aa3b, v83
	v_exp_f32_e32 v58, v58
	v_cvt_pk_bf16_f32 v47, v81, v47
	v_lshlrev_b32_e32 v69, 16, v52
	v_lshlrev_b32_e32 v68, 16, v48
	v_add_f32_e32 v58, 1.0, v58
	v_rcp_f32_e32 v81, v58
	v_pk_mul_f32 v[58:59], v[94:95], v[76:77]
	v_pk_mov_b32 v[76:77], v[76:77], v[68:69] op_sel:[1,0]
	v_add_f32_e32 v58, v10, v58
	v_add_f32_e32 v82, v58, v59
	v_pk_mul_f32 v[58:59], v[98:99], v[76:77]
	v_mul_f32_e32 v101, v83, v81
	v_add_f32_e32 v58, v80, v58
	v_add_f32_e32 v85, v58, v59
	v_mul_f32_e32 v58, 0xbfb8aa3b, v85
	v_exp_f32_e32 v80, v58
	v_pk_mul_f32 v[58:59], v[98:99], v[68:69]
	s_nop 0
	v_add_f32_e32 v58, v82, v58
	v_add_f32_e32 v100, v58, v59
	v_mul_f32_e32 v58, 0xbfb8aa3b, v100
	v_exp_f32_e32 v58, v58
	v_add_f32_e32 v59, 1.0, v80
	v_rcp_f32_e32 v102, v59
	v_and_b32_e32 v59, 0xffff0000, v52
	v_add_f32_e32 v58, 1.0, v58
	v_rcp_f32_e32 v103, v58
	v_and_b32_e32 v58, 0xffff0000, v48
	v_pk_mov_b32 v[80:81], v[54:55], v[58:59] op_sel:[1,0]
	v_pk_mul_f32 v[54:55], v[2:3], v[54:55]
	v_pk_mul_f32 v[82:83], v[6:7], v[80:81]
	v_add_f32_e32 v54, v11, v54
	v_add_f32_e32 v48, v84, v82
	v_add_f32_e32 v48, v48, v83
	v_mul_f32_e32 v52, 0xbfb8aa3b, v48
	v_exp_f32_e32 v52, v52
	v_add_f32_e32 v82, v54, v55
	v_pk_mul_f32 v[54:55], v[6:7], v[58:59]
	v_mul_f32_e32 v102, v85, v102
	v_add_f32_e32 v54, v82, v54
	v_add_f32_e32 v104, v54, v55
	v_add_f32_e32 v52, 1.0, v52
	v_mul_f32_e32 v54, 0xbfb8aa3b, v104
	v_rcp_f32_e32 v52, v52
	v_exp_f32_e32 v54, v54
	v_lshlrev_b32_e32 v55, 16, v53
	v_mul_f32_e32 v100, v100, v103
	v_mul_f32_e32 v48, v48, v52
	v_add_f32_e32 v52, 1.0, v54
	v_lshlrev_b32_e32 v54, 16, v49
	v_pk_mov_b32 v[82:83], v[66:67], v[54:55] op_sel:[1,0]
	v_pk_mul_f32 v[66:67], v[86:87], v[66:67]
	v_pk_mul_f32 v[84:85], v[90:91], v[82:83]
	v_add_f32_e32 v66, v12, v66
	v_add_f32_e32 v84, v88, v84
	v_add_f32_e32 v84, v84, v85
	v_mul_f32_e32 v85, 0xbfb8aa3b, v84
	v_exp_f32_e32 v85, v85
	v_add_f32_e32 v88, v66, v67
	v_rcp_f32_e32 v52, v52
	v_cvt_pk_bf16_f32 v48, v102, v48
	v_add_f32_e32 v66, 1.0, v85
	v_rcp_f32_e32 v85, v66
	v_pk_mul_f32 v[66:67], v[90:91], v[54:55]
	v_mul_f32_e32 v102, v104, v52
	v_add_f32_e32 v66, v88, v66
	v_add_f32_e32 v88, v66, v67
	v_mul_f32_e32 v66, 0xbfb8aa3b, v88
	v_exp_f32_e32 v66, v66
	v_mul_f32_e32 v84, v84, v85
	v_add_f32_e32 v52, 1.0, v66
	v_pk_mul_f32 v[66:67], v[4:5], v[70:71]
	v_rcp_f32_e32 v85, v52
	v_add_f32_e32 v52, v13, v66
	v_add_f32_e32 v103, v52, v67
	v_and_b32_e32 v67, 0xffff0000, v53
	v_and_b32_e32 v66, 0xffff0000, v49
	v_pk_mov_b32 v[52:53], v[70:71], v[66:67] op_sel:[1,0]
	v_mul_f32_e32 v85, v88, v85
	v_pk_mul_f32 v[70:71], v[8:9], v[52:53]
	s_nop 0
	v_add_f32_e32 v49, v89, v70
	v_add_f32_e32 v49, v49, v71
	v_mul_f32_e32 v70, 0xbfb8aa3b, v49
	v_exp_f32_e32 v89, v70
	v_pk_mul_f32 v[70:71], v[8:9], v[66:67]
	v_add_f32_e32 v89, 1.0, v89
	v_add_f32_e32 v70, v103, v70
	v_add_f32_e32 v70, v70, v71
	v_mul_f32_e32 v71, 0xbfb8aa3b, v70
	v_exp_f32_e32 v71, v71
	v_rcp_f32_e32 v89, v89
	v_add_f32_e32 v71, 1.0, v71
	v_rcp_f32_e32 v71, v71
	v_mul_f32_e32 v49, v49, v89
	v_cvt_pk_bf16_f32 v49, v84, v49
	ds_write_b128 v92, v[46:49] offset:2304
	v_mul_f32_e32 v49, v70, v71
	v_xor_b32_e32 v70, 0xa0, v116
	v_cvt_pk_bf16_f32 v46, v93, v96
	v_cvt_pk_bf16_f32 v47, v97, v101
	v_add3_u32 v70, v123, v70, v147
	v_cvt_pk_bf16_f32 v48, v100, v102
	v_cvt_pk_bf16_f32 v49, v85, v49
	ds_write_b128 v70, v[46:49] offset:2560
	v_pk_mul_f32 v[46:47], v[124:125], v[74:75]
	s_nop 0
	v_add_f32_e32 v46, v22, v46
	v_add_f32_e32 v48, v46, v47
	v_pk_mul_f32 v[46:47], v[14:15], v[78:79]
	s_nop 0
	v_add_f32_e32 v46, v23, v46
	v_add_f32_e32 v49, v46, v47
	v_pk_mul_f32 v[46:47], v[106:107], v[64:65]
	s_waitcnt vmcnt(3)
	v_lshlrev_b32_e32 v65, 16, v42
	v_add_f32_e32 v46, v24, v46
	v_add_f32_e32 v78, v46, v47
	v_pk_mul_f32 v[46:47], v[16:17], v[50:51]
	v_lshlrev_b32_e32 v64, 16, v38
	v_add_f32_e32 v46, v25, v46
	v_add_f32_e32 v79, v46, v47
	v_pk_mul_f32 v[46:47], v[94:95], v[76:77]
	v_pk_mov_b32 v[70:71], v[72:73], v[64:65] op_sel:[1,0]
	v_add_f32_e32 v46, v10, v46
	v_add_f32_e32 v76, v46, v47
	v_pk_mul_f32 v[46:47], v[2:3], v[80:81]
	v_xor_b32_e32 v50, 0xe0, v116
	v_add_f32_e32 v46, v11, v46
	v_add_f32_e32 v77, v46, v47
	v_pk_mul_f32 v[46:47], v[86:87], v[82:83]
	v_add3_u32 v82, v123, v50, v147
	v_add_f32_e32 v46, v12, v46
	v_add_f32_e32 v80, v46, v47
	v_pk_mul_f32 v[46:47], v[4:5], v[52:53]
	v_and_b32_e32 v50, 0xffff0000, v38
	v_add_f32_e32 v46, v13, v46
	v_add_f32_e32 v81, v46, v47
	v_pk_mul_f32 v[46:47], v[124:125], v[72:73]
	s_nop 0
	v_add_f32_e32 v46, v22, v46
	v_add_f32_e32 v51, v46, v47
	v_pk_mul_f32 v[46:47], v[126:127], v[70:71]
	s_nop 0
	v_add_f32_e32 v46, v48, v46
	v_add_f32_e32 v48, v46, v47
	v_mul_f32_e32 v46, 0xbfb8aa3b, v48
	v_exp_f32_e32 v52, v46
	v_pk_mul_f32 v[46:47], v[126:127], v[64:65]
	s_nop 0
	v_add_f32_e32 v46, v51, v46
	v_add_f32_e32 v53, v46, v47
	v_mul_f32_e32 v46, 0xbfb8aa3b, v53
	v_exp_f32_e32 v46, v46
	v_and_b32_e32 v51, 0xffff0000, v42
	v_add_f32_e32 v47, 1.0, v52
	v_pk_mov_b32 v[72:73], v[56:57], v[50:51] op_sel:[1,0]
	v_add_f32_e32 v46, 1.0, v46
	v_rcp_f32_e32 v52, v47
	v_rcp_f32_e32 v74, v46
	v_pk_mul_f32 v[46:47], v[18:19], v[72:73]
	v_mul_f32_e32 v52, v48, v52
	v_add_f32_e32 v38, v49, v46
	v_add_f32_e32 v38, v38, v47
	v_mul_f32_e32 v42, 0xbfb8aa3b, v38
	v_pk_mul_f32 v[46:47], v[14:15], v[56:57]
	v_exp_f32_e32 v42, v42
	v_add_f32_e32 v46, v23, v46
	v_add_f32_e32 v49, v46, v47
	v_pk_mul_f32 v[46:47], v[18:19], v[50:51]
	v_add_f32_e32 v42, 1.0, v42
	v_add_f32_e32 v46, v49, v46
	v_add_f32_e32 v57, v46, v47
	v_mul_f32_e32 v46, 0xbfb8aa3b, v57
	v_rcp_f32_e32 v42, v42
	v_exp_f32_e32 v46, v46
	v_lshlrev_b32_e32 v49, 16, v43
	v_lshlrev_b32_e32 v48, 16, v39
	v_mul_f32_e32 v83, v53, v74
	v_pk_mov_b32 v[74:75], v[62:63], v[48:49] op_sel:[1,0]
	v_mul_f32_e32 v38, v38, v42
	v_add_f32_e32 v42, 1.0, v46
	v_pk_mul_f32 v[46:47], v[110:111], v[74:75]
	v_rcp_f32_e32 v42, v42
	v_add_f32_e32 v46, v78, v46
	v_add_f32_e32 v53, v46, v47
	v_mul_f32_e32 v46, 0xbfb8aa3b, v53
	v_exp_f32_e32 v56, v46
	v_pk_mul_f32 v[46:47], v[106:107], v[62:63]
	v_mul_f32_e32 v84, v57, v42
	v_add_f32_e32 v46, v24, v46
	v_add_f32_e32 v62, v46, v47
	v_add_f32_e32 v46, 1.0, v56
	v_rcp_f32_e32 v63, v46
	v_pk_mul_f32 v[46:47], v[110:111], v[48:49]
	v_cvt_pk_bf16_f32 v56, v52, v38
	v_mul_f32_e32 v42, v53, v63
	v_add_f32_e32 v46, v62, v46
	v_add_f32_e32 v78, v46, v47
	v_mul_f32_e32 v46, 0xbfb8aa3b, v78
	v_exp_f32_e32 v46, v46
	v_and_b32_e32 v47, 0xffff0000, v43
	v_add_f32_e32 v38, 1.0, v46
	v_and_b32_e32 v46, 0xffff0000, v39
	v_pk_mov_b32 v[62:63], v[60:61], v[46:47] op_sel:[1,0]
	v_rcp_f32_e32 v52, v38
	v_pk_mul_f32 v[38:39], v[20:21], v[62:63]
	v_mul_f32_e32 v78, v78, v52
	v_add_f32_e32 v38, v79, v38
	v_add_f32_e32 v43, v38, v39
	v_mul_f32_e32 v38, 0xbfb8aa3b, v43
	v_exp_f32_e32 v53, v38
	v_pk_mul_f32 v[38:39], v[16:17], v[60:61]
	v_lshlrev_b32_e32 v52, 16, v40
	v_add_f32_e32 v38, v25, v38
	v_add_f32_e32 v57, v38, v39
	v_add_f32_e32 v38, 1.0, v53
	v_rcp_f32_e32 v53, v38
	v_pk_mul_f32 v[38:39], v[20:21], v[46:47]
	s_nop 0
	v_add_f32_e32 v38, v57, v38
	v_add_f32_e32 v79, v38, v39
	v_mul_f32_e32 v38, 0xbfb8aa3b, v79
	v_exp_f32_e32 v38, v38
	v_mul_f32_e32 v39, v43, v53
	v_cvt_pk_bf16_f32 v57, v42, v39
	v_lshlrev_b32_e32 v53, 16, v44
	v_add_f32_e32 v38, 1.0, v38
	v_rcp_f32_e32 v42, v38
	v_pk_mul_f32 v[38:39], v[94:95], v[68:69]
	v_pk_mov_b32 v[60:61], v[68:69], v[52:53] op_sel:[1,0]
	v_add_f32_e32 v38, v10, v38
	v_add_f32_e32 v43, v38, v39
	v_pk_mul_f32 v[38:39], v[98:99], v[60:61]
	v_mul_f32_e32 v79, v79, v42
	v_add_f32_e32 v38, v76, v38
	v_add_f32_e32 v76, v38, v39
	v_mul_f32_e32 v38, 0xbfb8aa3b, v76
	v_exp_f32_e32 v68, v38
	v_pk_mul_f32 v[38:39], v[98:99], v[52:53]
	v_and_b32_e32 v42, 0xffff0000, v40
	v_add_f32_e32 v38, v43, v38
	v_add_f32_e32 v85, v38, v39
	v_mul_f32_e32 v38, 0xbfb8aa3b, v85
	v_exp_f32_e32 v38, v38
	v_and_b32_e32 v43, 0xffff0000, v44
	v_add_f32_e32 v39, 1.0, v68
	v_pk_mov_b32 v[68:69], v[58:59], v[42:43] op_sel:[1,0]
	v_add_f32_e32 v38, 1.0, v38
	v_rcp_f32_e32 v88, v39
	v_rcp_f32_e32 v89, v38
	v_pk_mul_f32 v[38:39], v[6:7], v[68:69]
	v_mul_f32_e32 v88, v76, v88
	v_add_f32_e32 v38, v77, v38
	v_add_f32_e32 v40, v38, v39
	v_mul_f32_e32 v38, 0xbfb8aa3b, v40
	v_exp_f32_e32 v44, v38
	v_pk_mul_f32 v[38:39], v[2:3], v[58:59]
	v_mul_f32_e32 v85, v85, v89
	v_add_f32_e32 v38, v11, v38
	v_add_f32_e32 v58, v38, v39
	v_add_f32_e32 v38, 1.0, v44
	v_rcp_f32_e32 v44, v38
	v_pk_mul_f32 v[38:39], v[6:7], v[42:43]
	v_mul_f32_e32 v40, v40, v44
	v_add_f32_e32 v38, v58, v38
	v_add_f32_e32 v92, v38, v39
	v_mul_f32_e32 v38, 0xbfb8aa3b, v92
	v_exp_f32_e32 v38, v38
	v_lshlrev_b32_e32 v39, 16, v45
	v_and_b32_e32 v45, 0xffff0000, v45
	v_add_f32_e32 v38, 1.0, v38
	v_rcp_f32_e32 v44, v38
	v_lshlrev_b32_e32 v38, 16, v41
	v_pk_mov_b32 v[76:77], v[54:55], v[38:39] op_sel:[1,0]
	v_pk_mul_f32 v[54:55], v[86:87], v[54:55]
	v_pk_mul_f32 v[58:59], v[90:91], v[76:77]
	v_add_f32_e32 v54, v12, v54
	v_add_f32_e32 v58, v80, v58
	v_add_f32_e32 v59, v58, v59
	v_mul_f32_e32 v58, 0xbfb8aa3b, v59
	v_exp_f32_e32 v58, v58
	v_add_f32_e32 v80, v54, v55
	v_add_f32_e32 v54, 1.0, v58
	v_rcp_f32_e32 v89, v54
	v_pk_mul_f32 v[54:55], v[90:91], v[38:39]
	v_cvt_pk_bf16_f32 v58, v88, v40
	v_mul_f32_e32 v88, v92, v44
	v_add_f32_e32 v54, v80, v54
	v_add_f32_e32 v80, v54, v55
	v_mul_f32_e32 v54, 0xbfb8aa3b, v80
	v_exp_f32_e32 v54, v54
	v_mul_f32_e32 v59, v59, v89
	v_and_b32_e32 v44, 0xffff0000, v41
	v_add_f32_e32 v40, 1.0, v54
	v_pk_mul_f32 v[54:55], v[4:5], v[66:67]
	v_rcp_f32_e32 v89, v40
	v_add_f32_e32 v40, v13, v54
	v_add_f32_e32 v92, v40, v55
	v_pk_mov_b32 v[40:41], v[66:67], v[44:45] op_sel:[1,0]
	v_mul_f32_e32 v80, v80, v89
	v_pk_mul_f32 v[54:55], v[8:9], v[40:41]
	v_pk_mul_f32 v[40:41], v[4:5], v[40:41]
	v_add_f32_e32 v54, v81, v54
	v_add_f32_e32 v66, v54, v55
	v_mul_f32_e32 v54, 0xbfb8aa3b, v66
	v_exp_f32_e32 v67, v54
	v_pk_mul_f32 v[54:55], v[8:9], v[44:45]
	v_add_f32_e32 v40, v13, v40
	v_add_f32_e32 v54, v92, v54
	v_add_f32_e32 v54, v54, v55
	v_mul_f32_e32 v55, 0xbfb8aa3b, v54
	v_exp_f32_e32 v55, v55
	v_add_f32_e32 v67, 1.0, v67
	v_rcp_f32_e32 v67, v67
	v_add_f32_e32 v55, 1.0, v55
	v_rcp_f32_e32 v55, v55
	v_mul_f32_e32 v66, v66, v67
	v_cvt_pk_bf16_f32 v59, v59, v66
	ds_write_b128 v82, v[56:59] offset:2816
	v_xor_b32_e32 v58, 48, v116
	v_mul_f32_e32 v57, v54, v55
	v_cvt_pk_bf16_f32 v54, v83, v84
	v_cvt_pk_bf16_f32 v55, v78, v79
	v_add3_u32 v58, v123, v58, v147
	v_cvt_pk_bf16_f32 v56, v85, v88
	v_cvt_pk_bf16_f32 v57, v80, v57
	ds_write_b128 v58, v[54:57] offset:3072
	v_pk_mul_f32 v[54:55], v[124:125], v[70:71]
	v_xor_b32_e32 v59, 0x70, v116
	v_add_f32_e32 v54, v22, v54
	v_add_f32_e32 v58, v54, v55
	v_pk_mul_f32 v[54:55], v[14:15], v[72:73]
	v_add_f32_e32 v73, v40, v41
	v_add_f32_e32 v54, v23, v54
	v_add_f32_e32 v66, v54, v55
	v_pk_mul_f32 v[54:55], v[106:107], v[74:75]
	v_pk_mul_f32 v[40:41], v[124:125], v[64:65]
	v_add_f32_e32 v54, v24, v54
	v_add_f32_e32 v67, v54, v55
	v_pk_mul_f32 v[54:55], v[16:17], v[62:63]
	v_add_f32_e32 v40, v22, v40
	v_add_f32_e32 v54, v25, v54
	v_add_f32_e32 v70, v54, v55
	v_pk_mul_f32 v[54:55], v[94:95], v[60:61]
	v_add_f32_e32 v60, v40, v41
	v_add_f32_e32 v54, v10, v54
	v_add_f32_e32 v71, v54, v55
	v_pk_mul_f32 v[54:55], v[2:3], v[68:69]
	s_waitcnt vmcnt(2)
	v_lshlrev_b32_e32 v40, 16, v30
	v_add_f32_e32 v54, v11, v54
	v_add_f32_e32 v68, v54, v55
	v_pk_mul_f32 v[54:55], v[86:87], v[76:77]
	s_waitcnt vmcnt(1)
	v_lshlrev_b32_e32 v41, 16, v34
	v_add_f32_e32 v54, v12, v54
	v_add_f32_e32 v72, v54, v55
	v_pk_mov_b32 v[54:55], v[64:65], v[40:41] op_sel:[1,0]
	v_add3_u32 v74, v123, v59, v147
	v_pk_mul_f32 v[56:57], v[126:127], v[54:55]
	v_pk_mul_f32 v[54:55], v[124:125], v[54:55]
	v_add_f32_e32 v56, v58, v56
	v_add_f32_e32 v62, v56, v57
	v_mul_f32_e32 v56, 0xbfb8aa3b, v62
	v_exp_f32_e32 v58, v56
	v_pk_mul_f32 v[56:57], v[126:127], v[40:41]
	v_add_f32_e32 v22, v22, v54
	v_add_f32_e32 v40, v60, v56
	v_add_f32_e32 v40, v40, v57
	v_mul_f32_e32 v56, 0xbfb8aa3b, v40
	v_exp_f32_e32 v56, v56
	v_add_f32_e32 v57, 1.0, v58
	v_rcp_f32_e32 v63, v57
	v_and_b32_e32 v57, 0xffff0000, v34
	v_add_f32_e32 v56, 1.0, v56
	v_rcp_f32_e32 v64, v56
	v_and_b32_e32 v56, 0xffff0000, v30
	v_pk_mov_b32 v[58:59], v[50:51], v[56:57] op_sel:[1,0]
	v_pk_mul_f32 v[50:51], v[14:15], v[50:51]
	v_pk_mul_f32 v[60:61], v[18:19], v[58:59]
	v_add_f32_e32 v50, v23, v50
	v_add_f32_e32 v30, v66, v60
	v_add_f32_e32 v30, v30, v61
	v_mul_f32_e32 v34, 0xbfb8aa3b, v30
	v_exp_f32_e32 v34, v34
	v_add_f32_e32 v60, v50, v51
	v_pk_mul_f32 v[50:51], v[18:19], v[56:57]
	v_mul_f32_e32 v65, v62, v63
	v_add_f32_e32 v50, v60, v50
	v_add_f32_e32 v56, v50, v51
	v_add_f32_e32 v34, 1.0, v34
	v_mul_f32_e32 v50, 0xbfb8aa3b, v56
	v_rcp_f32_e32 v34, v34
	v_exp_f32_e32 v50, v50
	v_lshlrev_b32_e32 v51, 16, v35
	v_mul_f32_e32 v40, v40, v64
	v_mul_f32_e32 v30, v30, v34
	v_add_f32_e32 v34, 1.0, v50
	v_lshlrev_b32_e32 v50, 16, v31
	v_pk_mov_b32 v[60:61], v[48:49], v[50:51] op_sel:[1,0]
	v_pk_mul_f32 v[48:49], v[106:107], v[48:49]
	v_pk_mul_f32 v[62:63], v[110:111], v[60:61]
	v_add_f32_e32 v48, v24, v48
	v_add_f32_e32 v62, v67, v62
	v_add_f32_e32 v62, v62, v63
	v_mul_f32_e32 v63, 0xbfb8aa3b, v62
	v_exp_f32_e32 v63, v63
	v_add_f32_e32 v64, v48, v49
	v_rcp_f32_e32 v34, v34
	v_cvt_pk_bf16_f32 v30, v65, v30
	v_add_f32_e32 v48, 1.0, v63
	v_rcp_f32_e32 v63, v48
	v_pk_mul_f32 v[48:49], v[110:111], v[50:51]
	v_mul_f32_e32 v56, v56, v34
	v_add_f32_e32 v48, v64, v48
	v_add_f32_e32 v50, v48, v49
	v_mul_f32_e32 v48, 0xbfb8aa3b, v50
	v_exp_f32_e32 v48, v48
	v_and_b32_e32 v35, 0xffff0000, v35
	v_mul_f32_e32 v64, v62, v63
	v_pk_mul_f32 v[14:15], v[14:15], v[58:59]
	v_add_f32_e32 v34, 1.0, v48
	v_rcp_f32_e32 v65, v34
	v_and_b32_e32 v34, 0xffff0000, v31
	v_pk_mov_b32 v[48:49], v[46:47], v[34:35] op_sel:[1,0]
	v_pk_mul_f32 v[46:47], v[16:17], v[46:47]
	v_pk_mul_f32 v[62:63], v[20:21], v[48:49]
	v_add_f32_e32 v46, v25, v46
	v_add_f32_e32 v31, v70, v62
	v_add_f32_e32 v31, v31, v63
	v_mul_f32_e32 v62, 0xbfb8aa3b, v31
	v_exp_f32_e32 v62, v62
	v_add_f32_e32 v63, v46, v47
	v_mul_f32_e32 v50, v50, v65
	v_add_f32_e32 v14, v23, v14
	v_add_f32_e32 v46, 1.0, v62
	v_rcp_f32_e32 v62, v46
	v_pk_mul_f32 v[46:47], v[20:21], v[34:35]
	v_add_f32_e32 v23, v14, v15
	v_add_f32_e32 v34, v63, v46
	v_add_f32_e32 v34, v34, v47
	v_mul_f32_e32 v46, 0xbfb8aa3b, v34
	v_exp_f32_e32 v46, v46
	v_mul_f32_e32 v31, v31, v62
	v_cvt_pk_bf16_f32 v31, v64, v31
	v_add_f32_e32 v22, v22, v55
	v_add_f32_e32 v46, 1.0, v46
	v_rcp_f32_e32 v64, v46
	v_pk_mul_f32 v[46:47], v[94:95], v[52:53]
	v_mul_f32_e32 v34, v34, v64
	v_add_f32_e32 v46, v10, v46
	v_add_f32_e32 v65, v46, v47
	v_lshlrev_b32_e32 v46, 16, v32
	v_lshlrev_b32_e32 v47, 16, v36
	v_pk_mov_b32 v[52:53], v[52:53], v[46:47] op_sel:[1,0]
	s_nop 0
	v_pk_mul_f32 v[62:63], v[98:99], v[52:53]
	s_nop 0
	v_add_f32_e32 v62, v71, v62
	v_add_f32_e32 v69, v62, v63
	v_mul_f32_e32 v62, 0xbfb8aa3b, v69
	v_exp_f32_e32 v66, v62
	v_pk_mul_f32 v[62:63], v[98:99], v[46:47]
	s_nop 0
	v_add_f32_e32 v46, v65, v62
	v_add_f32_e32 v46, v46, v63
	v_mul_f32_e32 v62, 0xbfb8aa3b, v46
	v_exp_f32_e32 v62, v62
	v_add_f32_e32 v63, 1.0, v66
	v_rcp_f32_e32 v70, v63
	v_and_b32_e32 v63, 0xffff0000, v36
	v_add_f32_e32 v62, 1.0, v62
	v_rcp_f32_e32 v71, v62
	v_and_b32_e32 v62, 0xffff0000, v32
	v_pk_mov_b32 v[64:65], v[42:43], v[62:63] op_sel:[1,0]
	v_pk_mul_f32 v[42:43], v[2:3], v[42:43]
	v_pk_mul_f32 v[66:67], v[6:7], v[64:65]
	v_add_f32_e32 v42, v11, v42
	v_add_f32_e32 v32, v68, v66
	v_add_f32_e32 v32, v32, v67
	v_mul_f32_e32 v36, 0xbfb8aa3b, v32
	v_exp_f32_e32 v36, v36
	v_add_f32_e32 v66, v42, v43
	v_pk_mul_f32 v[42:43], v[6:7], v[62:63]
	v_mul_f32_e32 v70, v69, v70
	v_add_f32_e32 v42, v66, v42
	v_add_f32_e32 v62, v42, v43
	v_add_f32_e32 v36, 1.0, v36
	v_mul_f32_e32 v42, 0xbfb8aa3b, v62
	v_rcp_f32_e32 v36, v36
	v_exp_f32_e32 v42, v42
	v_lshlrev_b32_e32 v43, 16, v37
	v_mul_f32_e32 v46, v46, v71
	v_mul_f32_e32 v32, v32, v36
	v_add_f32_e32 v36, 1.0, v42
	v_lshlrev_b32_e32 v42, 16, v33
	v_pk_mov_b32 v[66:67], v[38:39], v[42:43] op_sel:[1,0]
	v_pk_mul_f32 v[38:39], v[86:87], v[38:39]
	v_pk_mul_f32 v[68:69], v[90:91], v[66:67]
	v_add_f32_e32 v38, v12, v38
	v_add_f32_e32 v68, v72, v68
	v_add_f32_e32 v68, v68, v69
	v_mul_f32_e32 v69, 0xbfb8aa3b, v68
	v_exp_f32_e32 v69, v69
	v_add_f32_e32 v71, v38, v39
	v_rcp_f32_e32 v36, v36
	v_cvt_pk_bf16_f32 v32, v70, v32
	v_add_f32_e32 v38, 1.0, v69
	v_rcp_f32_e32 v69, v38
	v_pk_mul_f32 v[38:39], v[90:91], v[42:43]
	v_mul_f32_e32 v62, v62, v36
	v_add_f32_e32 v38, v71, v38
	v_add_f32_e32 v42, v38, v39
	v_mul_f32_e32 v38, 0xbfb8aa3b, v42
	v_exp_f32_e32 v38, v38
	v_mul_f32_e32 v68, v68, v69
	v_and_b32_e32 v37, 0xffff0000, v37
	v_pk_mul_f32 v[2:3], v[2:3], v[64:65]
	v_add_f32_e32 v36, 1.0, v38
	v_pk_mul_f32 v[38:39], v[4:5], v[44:45]
	v_rcp_f32_e32 v69, v36
	v_add_f32_e32 v36, v13, v38
	v_add_f32_e32 v70, v36, v39
	v_and_b32_e32 v36, 0xffff0000, v33
	v_pk_mov_b32 v[38:39], v[44:45], v[36:37] op_sel:[1,0]
	v_mul_f32_e32 v42, v42, v69
	v_pk_mul_f32 v[44:45], v[8:9], v[38:39]
	s_waitcnt vmcnt(0)
	v_lshlrev_b32_e32 v69, 16, v28
	v_add_f32_e32 v33, v73, v44
	v_add_f32_e32 v33, v33, v45
	v_mul_f32_e32 v44, 0xbfb8aa3b, v33
	v_exp_f32_e32 v71, v44
	v_pk_mul_f32 v[44:45], v[8:9], v[36:37]
	v_add_f32_e32 v2, v11, v2
	v_add_f32_e32 v36, v70, v44
	v_add_f32_e32 v36, v36, v45
	v_mul_f32_e32 v44, 0xbfb8aa3b, v36
	v_exp_f32_e32 v44, v44
	v_add_f32_e32 v45, 1.0, v71
	v_rcp_f32_e32 v45, v45
	v_add_f32_e32 v11, v2, v3
	v_add_f32_e32 v44, 1.0, v44
	v_rcp_f32_e32 v44, v44
	v_mul_f32_e32 v33, v33, v45
	v_cvt_pk_bf16_f32 v33, v68, v33
	ds_write_b128 v74, v[30:33] offset:3328
	v_mul_f32_e32 v33, v36, v44
	v_cvt_pk_bf16_f32 v30, v40, v56
	v_cvt_pk_bf16_f32 v31, v50, v34
	v_xor_b32_e32 v34, 0xb0, v116
	v_cvt_pk_bf16_f32 v32, v46, v62
	v_cvt_pk_bf16_f32 v33, v42, v33
	v_add3_u32 v34, v123, v34, v147
	ds_write_b128 v34, v[30:33] offset:3584
	v_and_b32_e32 v33, 0xffff0000, v26
	v_mov_b32_e32 v32, v57
	v_pk_mul_f32 v[14:15], v[18:19], v[32:33]
	v_lshlrev_b32_e32 v45, 16, v27
	v_add_f32_e32 v14, v23, v14
	v_add_f32_e32 v18, v14, v15
	v_mul_f32_e32 v14, 0xbfb8aa3b, v18
	v_exp_f32_e32 v19, v14
	v_pk_mul_f32 v[14:15], v[106:107], v[60:61]
	v_mov_b32_e32 v44, v51
	v_add_f32_e32 v14, v24, v14
	v_lshlrev_b32_e32 v31, 16, v26
	v_mov_b32_e32 v30, v41
	v_add_f32_e32 v23, v14, v15
	v_pk_mul_f32 v[14:15], v[110:111], v[44:45]
	v_pk_mul_f32 v[30:31], v[126:127], v[30:31]
	v_add_f32_e32 v14, v23, v14
	v_add_f32_e32 v22, v22, v30
	v_add_f32_e32 v23, v14, v15
	v_add_f32_e32 v22, v22, v31
	v_mul_f32_e32 v14, 0xbfb8aa3b, v23
	v_mul_f32_e32 v26, 0xbfb8aa3b, v22
	v_exp_f32_e32 v14, v14
	v_exp_f32_e32 v26, v26
	v_add_f32_e32 v15, 1.0, v19
	v_and_b32_e32 v31, 0xffff0000, v28
	v_add_f32_e32 v14, 1.0, v14
	v_add_f32_e32 v26, 1.0, v26
	v_rcp_f32_e32 v19, v15
	v_rcp_f32_e32 v28, v14
	v_pk_mul_f32 v[14:15], v[16:17], v[48:49]
	v_and_b32_e32 v27, 0xffff0000, v27
	v_rcp_f32_e32 v24, v26
	v_add_f32_e32 v14, v25, v14
	v_mov_b32_e32 v26, v35
	v_add_f32_e32 v16, v14, v15
	v_pk_mul_f32 v[14:15], v[20:21], v[26:27]
	v_mov_b32_e32 v68, v47
	v_add_f32_e32 v14, v16, v14
	v_add_f32_e32 v16, v14, v15
	v_mul_f32_e32 v14, 0xbfb8aa3b, v16
	v_exp_f32_e32 v14, v14
	v_mov_b32_e32 v30, v63
	v_pk_mul_f32 v[2:3], v[6:7], v[30:31]
	v_lshlrev_b32_e32 v41, 16, v29
	v_add_f32_e32 v14, 1.0, v14
	v_rcp_f32_e32 v20, v14
	v_pk_mul_f32 v[14:15], v[94:95], v[52:53]
	v_add_f32_e32 v2, v11, v2
	v_add_f32_e32 v10, v10, v14
	v_add_f32_e32 v10, v10, v15
	v_pk_mul_f32 v[14:15], v[98:99], v[68:69]
	v_add_f32_e32 v6, v2, v3
	v_add_f32_e32 v10, v10, v14
	v_add_f32_e32 v10, v10, v15
	v_mul_f32_e32 v14, 0xbfb8aa3b, v10
	v_exp_f32_e32 v14, v14
	v_mul_f32_e32 v2, 0xbfb8aa3b, v6
	v_exp_f32_e32 v2, v2
	v_mov_b32_e32 v40, v43
	v_add_f32_e32 v3, 1.0, v14
	v_rcp_f32_e32 v11, v3
	v_add_f32_e32 v14, 1.0, v2
	v_pk_mul_f32 v[2:3], v[86:87], v[66:67]
	v_and_b32_e32 v29, 0xffff0000, v29
	v_add_f32_e32 v2, v12, v2
	v_add_f32_e32 v12, v2, v3
	v_pk_mul_f32 v[2:3], v[90:91], v[40:41]
	v_mul_f32_e32 v18, v18, v19
	v_add_f32_e32 v2, v12, v2
	v_add_f32_e32 v12, v2, v3
	v_mul_f32_e32 v2, 0xbfb8aa3b, v12
	v_exp_f32_e32 v15, v2
	v_pk_mul_f32 v[2:3], v[4:5], v[38:39]
	v_mul_f32_e32 v19, v23, v28
	v_add_f32_e32 v2, v13, v2
	v_mov_b32_e32 v28, v37
	v_add_f32_e32 v4, v2, v3
	v_pk_mul_f32 v[2:3], v[8:9], v[28:29]
	v_add_f32_e32 v5, 1.0, v15
	v_add_f32_e32 v2, v4, v2
	v_add_f32_e32 v2, v2, v3
	v_mul_f32_e32 v3, 0xbfb8aa3b, v2
	v_exp_f32_e32 v3, v3
	v_rcp_f32_e32 v4, v14
	v_rcp_f32_e32 v5, v5
	v_mul_f32_e32 v17, v22, v24
	v_add_f32_e32 v3, 1.0, v3
	v_rcp_f32_e32 v3, v3
	v_mul_f32_e32 v4, v6, v4
	v_mul_f32_e32 v5, v12, v5
	v_mul_f32_e32 v7, v16, v20
	v_mul_f32_e32 v6, v2, v3
	v_mul_f32_e32 v8, v10, v11
	v_cvt_pk_bf16_f32 v2, v17, v18
	v_cvt_pk_bf16_f32 v3, v19, v7
	v_cvt_pk_bf16_f32 v4, v8, v4
	v_cvt_pk_bf16_f32 v5, v5, v6
	v_or_b32_e32 v6, s1, v149
	v_lshlrev_b32_e32 v118, 2, v6
	global_load_dword v8, v118, s[30:31]
	v_add_u32_e32 v98, s90, v144
	v_ashrrev_i32_e32 v99, 31, v98
	v_lshlrev_b64 v[6:7], 7, v[98:99]
	v_lshl_add_u64 v[6:7], s[36:37], 0, v[6:7]
	v_lshl_add_u64 v[6:7], v[6:7], 0, v[118:119]
	global_load_dword v6, v[6:7], off
	s_waitcnt vmcnt(1)
	v_mul_f32_e32 v7, 0x3fb8aa3b, v8
	v_fma_f32 v9, v8, s84, -v7
	v_rndne_f32_e32 v10, v7
	v_fmac_f32_e32 v9, 0x32a5705f, v8
	v_sub_f32_e32 v7, v7, v10
	v_add_f32_e32 v7, v7, v9
	v_exp_f32_e32 v7, v7
	v_cvt_i32_f32_e32 v9, v10
	v_xor_b32_e32 v10, 0xf0, v116
	v_add3_u32 v10, v123, v10, v148
	ds_write_b128 v10, v[2:5]
	v_ldexp_f32 v2, v7, v9
	v_cmp_ngt_f32_e32 vcc, s85, v8
	s_waitcnt vmcnt(0)
	ds_write_b32 v150, v6
	v_cndmask_b32_e32 v2, 0, v2, vcc
	v_cmp_nlt_f32_e32 vcc, s86, v8
	s_nop 1
	v_cndmask_b32_e32 v2, v218, v2, vcc
	v_mul_f32_e64 v2, v6, -v2
	s_andn2_b64 vcc, exec, s[44:45]
	ds_write_b32 v151, v2
	s_waitcnt lgkmcnt(0)
	s_barrier
	s_cbranch_vccnz .LBB0_1052
	v_add_u32_e32 v4, s60, v141
	ds_read_b64 v[2:3], v4
	v_and_b32_e32 v5, 64, v219
	v_add_u32_e32 v6, -1, v219
	v_cmp_lt_i32_e32 vcc, v6, v5
	v_add_u32_e32 v8, -4, v219
	s_waitcnt lgkmcnt(0)
	v_add_f32_e32 v7, v2, v3
	v_cndmask_b32_e32 v6, v6, v219, vcc
	v_lshlrev_b32_e32 v3, 2, v6
	ds_bpermute_b32 v3, v3, v7
	v_add_u32_e32 v6, -2, v219
	v_cmp_lt_i32_e32 vcc, v6, v5
	s_waitcnt lgkmcnt(0)
	v_add_f32_e32 v3, v7, v3
	v_cndmask_b32_e32 v6, v6, v219, vcc
	v_cndmask_b32_e64 v3, v3, v7, s[8:9]
	v_lshlrev_b32_e32 v6, 2, v6
	ds_bpermute_b32 v6, v6, v3
	v_cmp_lt_i32_e32 vcc, v8, v5
	s_waitcnt lgkmcnt(0)
	v_add_f32_e32 v6, v3, v6
	v_cndmask_b32_e32 v8, v8, v219, vcc
	v_cndmask_b32_e64 v3, v6, v3, s[10:11]
	v_lshlrev_b32_e32 v6, 2, v8
	ds_bpermute_b32 v6, v6, v3
	v_add_u32_e32 v8, -8, v219
	v_cmp_lt_i32_e32 vcc, v8, v5
	s_waitcnt lgkmcnt(0)
	v_add_f32_e32 v6, v3, v6
	v_cndmask_b32_e32 v8, v8, v219, vcc
	v_cndmask_b32_e64 v3, v6, v3, s[12:13]
	v_lshlrev_b32_e32 v6, 2, v8
	ds_bpermute_b32 v6, v6, v3
	v_add_u32_e32 v8, -16, v219
	v_cmp_lt_i32_e32 vcc, v8, v5
	s_waitcnt lgkmcnt(0)
	v_add_f32_e32 v6, v3, v6
	v_cndmask_b32_e32 v8, v8, v219, vcc
	v_cndmask_b32_e64 v3, v6, v3, s[14:15]
	v_lshlrev_b32_e32 v6, 2, v8
	ds_bpermute_b32 v6, v6, v3
	v_subrev_u32_e32 v8, 32, v219
	v_cmp_lt_i32_e32 vcc, v8, v5
	s_waitcnt lgkmcnt(0)
	v_add_f32_e32 v6, v3, v6
	v_cndmask_b32_e32 v5, v8, v219, vcc
	v_cndmask_b32_e64 v3, v6, v3, s[16:17]
	v_lshlrev_b32_e32 v5, 2, v5
	ds_bpermute_b32 v5, v5, v3
	s_waitcnt lgkmcnt(0)
	v_add_f32_e32 v5, v3, v5
	v_cndmask_b32_e64 v3, v5, v3, s[6:7]
	v_sub_f32_e32 v5, v3, v7
	v_add_f32_e32 v2, v2, v5
	ds_write_b64 v4, v[2:3]
.LBB0_1052:
	s_waitcnt lgkmcnt(0)
	s_barrier
	s_load_dwordx2 s[4:5], s[28:29], 0x50
	s_add_i32 s58, s1, s61
	s_ashr_i32 s59, s58, 31
	s_lshl_b64 s[20:21], s[58:59], 2
	v_add_u32_e32 v101, v153, v154
	s_waitcnt lgkmcnt(0)
	s_add_u32 s20, s4, s20
	s_addc_u32 s21, s5, s21
	s_lshl_b32 s1, s89, 5
	s_add_i32 s4, s58, s1
	s_ashr_i32 s5, s4, 31
	s_lshl_b64 s[4:5], s[4:5], 14
	v_lshl_add_u64 v[108:109], v[120:121], 0, s[4:5]
	v_add_co_u32_e32 v136, vcc, s87, v108
	global_load_dwordx4 v[2:5], v[108:109], off nt
	s_nop 0
	v_addc_co_u32_e32 v137, vcc, 0, v109, vcc
	global_load_dwordx4 v[34:37], v[136:137], off nt
	global_load_dwordx4 v[66:69], v[108:109], off offset:32 nt
	global_load_dwordx4 v[78:81], v[136:137], off offset:32 nt
	global_load_dwordx4 v[86:89], v[136:137], off offset:64 nt
	global_load_dwordx4 v[82:85], v[108:109], off offset:64 nt
	global_load_dwordx4 v[90:93], v[108:109], off offset:96 nt
	global_load_dwordx4 v[110:113], v[136:137], off offset:96 nt
	global_load_dwordx4 v[114:117], v[136:137], off offset:128 nt
	v_add_u32_e32 v10, v163, v154
	ds_read_b128 v[6:9], v101
	ds_read_b128 v[38:41], v10
	v_add_u32_e32 v102, v153, v155
	ds_read_b128 v[70:73], v102
	v_add_u32_e32 v10, v163, v155
	ds_read_b128 v[74:77], v10
	v_add_u32_e32 v103, v153, v156
	v_add_u32_e32 v104, v153, v157
	global_load_dwordx4 v[132:135], v[136:137], off offset:160 nt
	global_load_dwordx4 v[220:223], v[136:137], off offset:192 nt
	v_add_u32_e32 v105, v153, v158
	ds_read_b128 v[124:127], v105
	v_add_u32_e32 v106, v153, v159
	ds_read_b128 v[128:131], v106
	global_load_dwordx4 v[232:235], v[136:137], off offset:224 nt
	v_add_u32_e32 v107, v153, v160
	ds_read_b128 v[224:227], v107
	v_mov_b32_e32 v118, v174
	v_mov_b32_e32 v123, v173
	s_waitcnt vmcnt(11) lgkmcnt(6)
	v_mfma_f32_32x32x16_bf16 v[18:33], v[6:9], v[2:5], 0
	ds_read_b128 v[94:97], v104
	s_waitcnt lgkmcnt(6)
	v_mfma_f32_32x32x16_bf16 v[50:65], v[38:41], v[2:5], 0
	s_waitcnt vmcnt(10)
	v_mfma_f32_32x32x16_bf16 v[2:17], v[6:9], v[34:37], 0
	s_waitcnt vmcnt(9) lgkmcnt(5)
	v_mfma_f32_32x32x16_bf16 v[18:33], v[70:73], v[66:69], v[18:33]
	s_waitcnt vmcnt(8)
	v_mfma_f32_32x32x16_bf16 v[2:17], v[70:73], v[78:81], v[2:17]
	ds_read_b128 v[70:73], v103
	s_waitcnt vmcnt(6) lgkmcnt(0)
	v_mfma_f32_32x32x16_bf16 v[18:33], v[70:73], v[82:85], v[18:33]
	v_mfma_f32_32x32x16_bf16 v[2:17], v[70:73], v[86:89], v[2:17]
	global_load_dwordx4 v[70:73], v[108:109], off offset:128 nt
	s_waitcnt vmcnt(6)
	v_mfma_f32_32x32x16_bf16 v[18:33], v[94:97], v[90:93], v[18:33]
	s_waitcnt vmcnt(5)
	v_mfma_f32_32x32x16_bf16 v[2:17], v[94:97], v[110:113], v[2:17]
	global_load_dwordx4 v[94:97], v[108:109], off offset:160 nt
	s_waitcnt vmcnt(5)
	v_mfma_f32_32x32x16_bf16 v[2:17], v[124:127], v[114:117], v[2:17]
	s_waitcnt vmcnt(4)
	v_mfma_f32_32x32x16_bf16 v[2:17], v[128:131], v[132:135], v[2:17]
	v_mfma_f32_32x32x16_bf16 v[34:49], v[38:41], v[34:37], 0
	s_waitcnt vmcnt(1)
	v_mfma_f32_32x32x16_bf16 v[18:33], v[124:127], v[70:73], v[18:33]
	global_load_dwordx4 v[124:127], v[108:109], off offset:192 nt
	s_waitcnt vmcnt(1)
	v_mfma_f32_32x32x16_bf16 v[18:33], v[128:131], v[94:97], v[18:33]
	global_load_dwordx4 v[128:131], v[108:109], off offset:224 nt
	v_add_u32_e32 v108, v153, v161
	ds_read_b128 v[228:231], v108
	v_mfma_f32_32x32x16_bf16 v[50:65], v[74:77], v[66:69], v[50:65]
	v_add_u32_e32 v66, v163, v156
	v_mfma_f32_32x32x16_bf16 v[34:49], v[74:77], v[78:81], v[34:49]
	ds_read_b128 v[66:69], v66
	ds_read_b128 v[74:77], v162
	global_load_dword v100, v119, s[20:21]
	v_add_u32_e32 v78, v163, v157
	ds_read_b128 v[78:81], v78
	s_mov_b32 s20, 0
	s_waitcnt lgkmcnt(1)
	v_mul_f32_e32 v74, 0x3fb8aa3b, v74
	v_exp_f32_e32 v136, v74
	v_mfma_f32_32x32x16_bf16 v[50:65], v[66:69], v[82:85], v[50:65]
	ds_read_b128 v[82:85], v162 offset:32
	v_mul_f32_e32 v74, 0x3fb8aa3b, v75
	v_exp_f32_e32 v137, v74
	v_add_u32_e32 v74, v163, v158
	v_mfma_f32_32x32x16_bf16 v[34:49], v[66:69], v[86:89], v[34:49]
	v_mul_f32_e32 v66, 0x3fb8aa3b, v76
	v_exp_f32_e32 v86, v66
	v_mul_f32_e32 v66, 0x3fb8aa3b, v77
	v_exp_f32_e32 v87, v66
	ds_read_b128 v[74:77], v74
	s_waitcnt lgkmcnt(2)
	v_mfma_f32_32x32x16_bf16 v[50:65], v[78:81], v[90:93], v[50:65]
	v_mfma_f32_32x32x16_bf16 v[34:49], v[78:81], v[110:113], v[34:49]
	ds_read_b128 v[78:81], v162 offset:96
	s_waitcnt lgkmcnt(2)
	v_mul_f32_e32 v66, 0x3fb8aa3b, v82
	v_exp_f32_e32 v88, v66
	v_mul_f32_e32 v66, 0x3fb8aa3b, v83
	v_exp_f32_e32 v89, v66
	v_mul_f32_e32 v66, 0x3fb8aa3b, v84
	v_exp_f32_e32 v90, v66
	ds_read_b128 v[66:69], v162 offset:64
	s_waitcnt vmcnt(2)
	v_mfma_f32_32x32x16_bf16 v[18:33], v[224:227], v[124:127], v[18:33]
	s_waitcnt lgkmcnt(0)
	v_mul_f32_e32 v66, 0x3fb8aa3b, v66
	v_mul_f32_e32 v82, 0x3fb8aa3b, v85
	v_exp_f32_e32 v92, v66
	v_mul_f32_e32 v66, 0x3fb8aa3b, v67
	v_add_u32_e32 v67, v163, v159
	v_exp_f32_e32 v91, v82
	ds_read_b128 v[82:85], v67
	v_mfma_f32_32x32x16_bf16 v[2:17], v[224:227], v[220:223], v[2:17]
	v_mul_f32_e32 v67, 0x3fb8aa3b, v78
	v_exp_f32_e32 v93, v66
	v_mul_f32_e32 v66, 0x3fb8aa3b, v68
	v_mov_b32_e32 v110, v198
	v_mov_b32_e32 v111, v181
	v_mov_b32_e32 v112, v180
	v_mov_b32_e32 v113, v179
	v_mfma_f32_32x32x16_bf16 v[50:65], v[74:77], v[70:73], v[50:65]
	v_exp_f32_e32 v72, v67
	v_mul_f32_e32 v67, 0x3fb8aa3b, v80
	v_exp_f32_e32 v70, v66
	v_mul_f32_e32 v66, 0x3fb8aa3b, v69
	v_exp_f32_e32 v71, v66
	v_add_u32_e32 v66, v163, v160
	v_mfma_f32_32x32x16_bf16 v[34:49], v[74:77], v[114:117], v[34:49]
	v_exp_f32_e32 v74, v67
	v_mul_f32_e32 v67, 0x3fb8aa3b, v81
	v_exp_f32_e32 v75, v67
	v_mul_f32_e32 v67, 0x3fb8aa3b, v79
	v_exp_f32_e32 v73, v67
	ds_read_b128 v[66:69], v66
	v_mov_b32_e32 v114, v178
	s_waitcnt vmcnt(1)
	v_mfma_f32_32x32x16_bf16 v[18:33], v[228:231], v[128:131], v[18:33]
	v_mov_b32_e32 v115, v177
	v_mov_b32_e32 v116, v176
	v_mov_b32_e32 v117, v175
	v_mfma_f32_32x32x16_bf16 v[2:17], v[228:231], v[232:235], v[2:17]
	s_nop 7
	v_mul_f32_e64 v28, v28, v70
	v_mul_f32_e64 v29, v29, v71
	v_mul_f32_e64 v30, v30, v72
	v_mul_f32_e64 v31, v31, v73
	v_mul_f32_e64 v26, v26, v92
	v_mul_f32_e64 v27, v27, v93
	v_pk_mul_f32 v[24:25], v[24:25], v[90:91]
	v_pk_mul_f32 v[22:23], v[22:23], v[88:89]
	v_pk_mul_f32 v[20:21], v[20:21], v[86:87]
	v_pk_mul_f32 v[32:33], v[32:33], v[74:75]
	s_waitcnt lgkmcnt(1)
	v_mfma_f32_32x32x16_bf16 v[50:65], v[82:85], v[94:97], v[50:65]
	v_mul_f32_e64 v12, v12, v70
	v_mul_f32_e64 v13, v13, v71
	v_add_u32_e32 v70, v163, v161
	v_mul_f32_e64 v14, v14, v72
	v_mul_f32_e64 v15, v15, v73
	ds_read_b128 v[70:73], v70
	v_pk_mul_f32 v[10:11], v[10:11], v[92:93]
	v_pk_mul_f32 v[8:9], v[8:9], v[90:91]
	v_pk_mul_f32 v[6:7], v[6:7], v[88:89]
	v_mfma_f32_32x32x16_bf16 v[34:49], v[82:85], v[132:135], v[34:49]
	v_mul_f32_e64 v4, v4, v86
	v_mul_f32_e64 v5, v5, v87
	ds_read_b128 v[94:97], v164 offset:256
	ds_read_b128 v[90:93], v164 offset:288
	ds_read_b128 v[86:89], v164 offset:320
	ds_read_b128 v[82:85], v164 offset:352
	ds_read_b32 v109, v166
	v_pk_mul_f32 v[18:19], v[18:19], v[136:137]
	v_pk_mul_f32 v[16:17], v[16:17], v[74:75]
	v_pk_mul_f32 v[2:3], v[2:3], v[136:137]
	s_waitcnt lgkmcnt(6)
	v_mfma_f32_32x32x16_bf16 v[50:65], v[66:69], v[124:127], v[50:65]
	v_mov_b32_e32 v124, v172
	v_mov_b32_e32 v125, v171
	v_mov_b32_e32 v126, v170
	v_mfma_f32_32x32x16_bf16 v[34:49], v[66:69], v[220:223], v[34:49]
	s_waitcnt lgkmcnt(5)
	v_mfma_f32_32x32x16_bf16 v[50:65], v[70:73], v[128:131], v[50:65]
	v_mfma_f32_32x32x16_bf16 v[34:49], v[70:73], v[232:235], v[34:49]

.LBB0_1055:
	v_add_u32_e32 v66, 0, v88
	ds_read_b128 v[66:69], v66
	v_add_u32_e32 v70, v169, v154
	ds_read_b128 v[70:73], v70
	v_add_u32_e32 v96, 0, v89
	ds_read_b128 v[102:105], v96
	v_add_u32_e32 v96, v169, v155
	ds_read_b128 v[106:109], v96
	v_add_u32_e32 v96, 0, v90
	v_add_u32_e32 v97, 0, v83
	s_waitcnt lgkmcnt(2)
	v_mfma_f32_32x32x16_bf16 v[66:81], v[66:69], v[70:73], 0
	v_add_u32_e32 v101, 0x20c00, v97
	v_add_u32_e32 v90, 0x2000, v90
	v_add_u32_e32 v89, 0x2000, v89
	v_add_u32_e32 v88, 0x2000, v88
	v_add_u32_e32 v83, 0x80, v83
	s_waitcnt lgkmcnt(0)
	v_mfma_f32_32x32x16_bf16 v[66:81], v[102:105], v[106:109], v[66:81]
	ds_read_b128 v[102:105], v96
	v_add_u32_e32 v96, v169, v156
	ds_read_b128 v[106:109], v96
	v_add_u32_e32 v96, 0, v91
	v_add_u32_e32 v91, 0x2000, v91
	s_waitcnt lgkmcnt(0)
	v_mfma_f32_32x32x16_bf16 v[66:81], v[102:105], v[106:109], v[66:81]
	ds_read_b128 v[102:105], v96
	v_add_u32_e32 v96, v169, v157
	ds_read_b128 v[106:109], v96
	v_add_u32_e32 v96, 0, v92
	v_add_u32_e32 v92, 0x2000, v92
	s_waitcnt lgkmcnt(0)
	v_mfma_f32_32x32x16_bf16 v[66:81], v[102:105], v[106:109], v[66:81]
	ds_read_b128 v[102:105], v96
	v_add_u32_e32 v96, v169, v158
	ds_read_b128 v[106:109], v96
	v_add_u32_e32 v96, 0, v93
	v_add_u32_e32 v93, 0x2000, v93
	s_waitcnt lgkmcnt(0)
	v_mfma_f32_32x32x16_bf16 v[66:81], v[102:105], v[106:109], v[66:81]
	ds_read_b128 v[102:105], v96
	v_add_u32_e32 v96, v169, v159
	ds_read_b128 v[106:109], v96
	v_add_u32_e32 v96, 0, v94
	v_add_u32_e32 v94, 0x2000, v94
	s_waitcnt lgkmcnt(0)
	v_mfma_f32_32x32x16_bf16 v[66:81], v[102:105], v[106:109], v[66:81]
	ds_read_b128 v[102:105], v96
	v_add_u32_e32 v96, v169, v160
	ds_read_b128 v[106:109], v96
	v_add_u32_e32 v96, 0, v95
	v_add_u32_e32 v95, 0x2000, v95
	s_waitcnt lgkmcnt(0)
	v_mfma_f32_32x32x16_bf16 v[66:81], v[102:105], v[106:109], v[66:81]
	ds_read_b128 v[102:105], v96
	v_add_u32_e32 v96, v169, v161
	ds_read_b128 v[106:109], v96
	v_add_u32_e32 v96, s20, v165
	v_cmp_le_u32_e32 vcc, v96, v167
	v_add_u32_e32 v110, 8, v96
	s_waitcnt lgkmcnt(0)
	v_mfma_f32_32x32x16_bf16 v[66:81], v[102:105], v[106:109], v[66:81]
	ds_read_b128 v[102:105], v101
	v_add_u32_e32 v101, 0x20400, v97
	ds_read_b128 v[106:109], v101
	s_waitcnt lgkmcnt(1)
	v_sub_f32_e32 v101, v82, v102
	v_min_f32_e32 v101, 0, v101
	v_mul_f32_e32 v101, 0x3fb8aa3b, v101
	v_exp_f32_e32 v101, v101
	v_sub_f32_e32 v102, v82, v103
	v_min_f32_e32 v102, 0, v102
	v_sub_f32_e32 v103, v82, v104
	v_mul_f32_e32 v102, 0x3fb8aa3b, v102
	v_min_f32_e32 v103, 0, v103
	v_exp_f32_e32 v102, v102
	v_mul_f32_e32 v103, 0x3fb8aa3b, v103
	v_mul_f32_e32 v66, v66, v101
	v_exp_f32_e32 v103, v103
	s_waitcnt lgkmcnt(0)
	v_mul_f32_e32 v66, v106, v66
	v_cndmask_b32_e32 v66, 0, v66, vcc
	v_cmp_eq_u32_e32 vcc, s20, v214
	v_add_f32_e32 v101, v100, v66
	v_mul_f32_e32 v67, v67, v102
	v_cndmask_b32_e32 v66, v66, v101, vcc
	v_mul_f32_e32 v67, v107, v67
	v_cmp_lt_u32_e32 vcc, v96, v167
	v_mul_f32_e32 v68, v68, v103
	v_sub_f32_e32 v103, v82, v105
	v_add_u32_e32 v101, s20, v213
	v_cndmask_b32_e32 v67, 0, v67, vcc
	v_min_f32_e32 v103, 0, v103
	v_cmp_eq_u32_e32 vcc, 0, v101
	v_add_f32_e32 v101, v100, v67
	v_add_u32_e32 v102, 2, v96
	v_mul_f32_e32 v103, 0x3fb8aa3b, v103
	v_cndmask_b32_e32 v67, v67, v101, vcc
	v_mul_f32_e32 v68, v108, v68
	v_cmp_le_u32_e32 vcc, v102, v167
	v_exp_f32_e32 v103, v103
	v_add_u32_e32 v101, s20, v212
	v_cndmask_b32_e32 v68, 0, v68, vcc
	v_cmp_eq_u32_e32 vcc, 0, v101
	v_add_f32_e32 v101, v100, v68
	v_add_u32_e32 v102, 3, v96
	v_cndmask_b32_e32 v68, v68, v101, vcc
	v_cmp_le_u32_e32 vcc, v102, v167
	v_add_u32_e32 v102, 0x20c20, v97
	v_mul_f32_e32 v69, v69, v103
	ds_read_b128 v[102:105], v102
	v_add_u32_e32 v106, 0x20420, v97
	v_mul_f32_e32 v69, v109, v69
	ds_read_b128 v[106:109], v106
	v_add_u32_e32 v101, s20, v211
	s_waitcnt lgkmcnt(1)
	v_sub_f32_e32 v103, v82, v103
	v_min_f32_e32 v103, 0, v103
	v_mul_f32_e32 v103, 0x3fb8aa3b, v103
	v_sub_f32_e32 v102, v82, v102
	v_exp_f32_e32 v103, v103
	v_min_f32_e32 v102, 0, v102
	v_mul_f32_e32 v102, 0x3fb8aa3b, v102
	v_exp_f32_e32 v102, v102
	v_mul_f32_e32 v71, v71, v103
	v_sub_f32_e32 v103, v82, v104
	v_min_f32_e32 v103, 0, v103
	v_cndmask_b32_e32 v69, 0, v69, vcc
	v_mul_f32_e32 v103, 0x3fb8aa3b, v103
	v_cmp_eq_u32_e32 vcc, 0, v101
	v_add_f32_e32 v101, v100, v69
	v_mul_f32_e32 v70, v70, v102
	v_exp_f32_e32 v103, v103
	v_cndmask_b32_e32 v69, v69, v101, vcc
	s_waitcnt lgkmcnt(0)
	v_mul_f32_e32 v70, v106, v70
	v_cmp_le_u32_e32 vcc, v110, v167
	v_add_u32_e32 v101, s20, v210
	v_add_u32_e32 v102, 9, v96
	v_cndmask_b32_e32 v70, 0, v70, vcc
	v_cmp_eq_u32_e32 vcc, 0, v101
	v_add_f32_e32 v101, v100, v70
	v_mul_f32_e32 v71, v107, v71
	v_cndmask_b32_e32 v70, v70, v101, vcc
	v_cmp_le_u32_e32 vcc, v102, v167
	v_mul_f32_e32 v72, v72, v103
	v_sub_f32_e32 v103, v82, v105
	v_add_u32_e32 v101, s20, v209
	v_cndmask_b32_e32 v71, 0, v71, vcc
	v_min_f32_e32 v103, 0, v103
	v_cmp_eq_u32_e32 vcc, 0, v101
	v_add_f32_e32 v101, v100, v71
	v_add_u32_e32 v102, 10, v96
	v_mul_f32_e32 v103, 0x3fb8aa3b, v103
	v_cndmask_b32_e32 v71, v71, v101, vcc
	v_mul_f32_e32 v72, v108, v72
	v_cmp_le_u32_e32 vcc, v102, v167
	v_exp_f32_e32 v103, v103
	v_add_u32_e32 v101, s20, v208
	v_cndmask_b32_e32 v72, 0, v72, vcc
	v_cmp_eq_u32_e32 vcc, 0, v101
	v_add_f32_e32 v101, v100, v72
	v_add_u32_e32 v102, 11, v96
	v_cndmask_b32_e32 v101, v72, v101, vcc
	v_cmp_le_u32_e32 vcc, v102, v167
	v_add_u32_e32 v102, 0x20c40, v97
	v_mul_f32_e32 v73, v73, v103
	ds_read_b128 v[102:105], v102
	v_add_u32_e32 v106, 0x20440, v97
	v_mul_f32_e32 v73, v109, v73
	ds_read_b128 v[106:109], v106
	v_add_u32_e32 v72, s20, v207
	s_waitcnt lgkmcnt(1)
	v_sub_f32_e32 v102, v82, v102
	v_min_f32_e32 v102, 0, v102
	v_mul_f32_e32 v102, 0x3fb8aa3b, v102
	v_exp_f32_e32 v102, v102
	v_cndmask_b32_e32 v73, 0, v73, vcc
	v_cmp_eq_u32_e32 vcc, 0, v72
	v_add_f32_e32 v72, v100, v73
	v_mul_f32_e32 v74, v74, v102
	v_cndmask_b32_e32 v110, v73, v72, vcc
	v_add_u32_e32 v73, 16, v96
	s_waitcnt lgkmcnt(0)
	v_mul_f32_e32 v74, v106, v74
	v_cmp_le_u32_e32 vcc, v73, v167
	v_add_u32_e32 v72, s20, v206
	s_nop 0
	v_cndmask_b32_e32 v73, 0, v74, vcc
	v_sub_f32_e32 v74, v82, v103
	v_min_f32_e32 v74, 0, v74
	v_mul_f32_e32 v74, 0x3fb8aa3b, v74
	v_exp_f32_e32 v74, v74
	v_cmp_eq_u32_e32 vcc, 0, v72
	v_add_f32_e32 v72, v100, v73
	v_mul_f32_e32 v74, v75, v74
	v_cndmask_b32_e32 v106, v73, v72, vcc
	v_add_u32_e32 v73, 17, v96
	v_mul_f32_e32 v74, v107, v74
	v_cmp_le_u32_e32 vcc, v73, v167
	v_add_u32_e32 v72, s20, v205
	s_nop 0
	v_cndmask_b32_e32 v73, 0, v74, vcc
	v_sub_f32_e32 v74, v82, v104
	v_min_f32_e32 v74, 0, v74
	v_mul_f32_e32 v74, 0x3fb8aa3b, v74
	v_exp_f32_e32 v74, v74
	v_cmp_eq_u32_e32 vcc, 0, v72
	v_add_f32_e32 v72, v100, v73
	v_mul_f32_e32 v74, v76, v74
	v_cndmask_b32_e32 v107, v73, v72, vcc
	v_add_u32_e32 v73, 18, v96
	v_mul_f32_e32 v74, v108, v74
	v_cmp_le_u32_e32 vcc, v73, v167
	v_add_u32_e32 v72, s20, v204
	v_add_u32_e32 v108, s20, v202
	v_cndmask_b32_e32 v73, 0, v74, vcc
	v_sub_f32_e32 v74, v82, v105
	v_min_f32_e32 v74, 0, v74
	v_mul_f32_e32 v74, 0x3fb8aa3b, v74
	v_exp_f32_e32 v74, v74
	v_cmp_eq_u32_e32 vcc, 0, v72
	v_add_f32_e32 v72, v100, v73
	v_mul_f32_e32 v74, v77, v74
	v_cndmask_b32_e32 v76, v73, v72, vcc
	v_add_u32_e32 v73, 19, v96
	v_mul_f32_e32 v74, v109, v74
	v_cmp_le_u32_e32 vcc, v73, v167
	v_add_u32_e32 v72, s20, v203
	v_add_u32_e32 v109, 24, v96
	v_cndmask_b32_e32 v73, 0, v74, vcc
	v_cmp_eq_u32_e32 vcc, 0, v72
	v_add_f32_e32 v72, v100, v73
	s_nop 0
	v_cndmask_b32_e32 v77, v73, v72, vcc
	v_add_u32_e32 v72, 0x20c60, v97
	ds_read_b128 v[72:75], v72
	v_add_u32_e32 v97, 0x20460, v97
	ds_read_b128 v[102:105], v97
	v_cmp_le_u32_e32 vcc, v109, v167
	v_add_u32_e32 v97, 25, v96
	s_waitcnt lgkmcnt(1)
	v_sub_f32_e32 v72, v82, v72
	v_min_f32_e32 v72, 0, v72
	v_mul_f32_e32 v72, 0x3fb8aa3b, v72
	v_exp_f32_e32 v72, v72
	v_sub_f32_e32 v73, v82, v73
	v_min_f32_e32 v73, 0, v73
	v_mul_f32_e32 v73, 0x3fb8aa3b, v73
	v_exp_f32_e32 v73, v73
	v_mul_f32_e32 v72, v78, v72
	v_sub_f32_e32 v74, v82, v74
	s_waitcnt lgkmcnt(0)
	v_mul_f32_e32 v72, v102, v72
	v_min_f32_e32 v74, 0, v74
	v_cndmask_b32_e32 v72, 0, v72, vcc
	v_mul_f32_e32 v74, 0x3fb8aa3b, v74
	v_cmp_eq_u32_e32 vcc, 0, v108
	v_add_f32_e32 v78, v100, v72
	v_mul_f32_e32 v73, v79, v73
	v_exp_f32_e32 v74, v74
	v_cndmask_b32_e32 v78, v72, v78, vcc
	v_mul_f32_e32 v73, v103, v73
	v_cmp_le_u32_e32 vcc, v97, v167
	v_sub_f32_e32 v75, v82, v75
	v_add_u32_e32 v72, s20, v201
	v_cndmask_b32_e32 v73, 0, v73, vcc
	v_min_f32_e32 v75, 0, v75
	v_cmp_eq_u32_e32 vcc, 0, v72
	v_add_f32_e32 v72, v100, v73
	v_mul_f32_e32 v75, 0x3fb8aa3b, v75
	v_cndmask_b32_e32 v79, v73, v72, vcc
	v_add_u32_e32 v73, 26, v96
	v_mul_f32_e32 v74, v80, v74
	v_exp_f32_e32 v75, v75
	v_mul_f32_e32 v74, v104, v74
	v_cmp_le_u32_e32 vcc, v73, v167
	v_add_u32_e32 v72, s20, v200
	v_mul_f32_e32 v75, v81, v75
	v_cndmask_b32_e32 v73, 0, v74, vcc
	v_cmp_eq_u32_e32 vcc, 0, v72
	v_add_f32_e32 v72, v100, v73
	v_mul_f32_e32 v75, v105, v75
	v_cndmask_b32_e32 v74, v73, v72, vcc
	v_add_u32_e32 v73, 27, v96
	v_cmp_le_u32_e32 vcc, v73, v167
	v_add_u32_e32 v72, s20, v199
	v_add_u32_e32 v80, 0, v84
	v_cndmask_b32_e32 v73, 0, v75, vcc
	v_cmp_eq_u32_e32 vcc, 0, v72
	v_add_f32_e32 v72, v100, v73
	v_add_u32_e32 v81, 0, v86
	v_cndmask_b32_e32 v75, v73, v72, vcc
	v_cvt_pk_bf16_f32 v66, v66, v67
	v_cvt_pk_bf16_f32 v67, v68, v69
	v_cvt_pk_bf16_f32 v68, v70, v71
	v_cvt_pk_bf16_f32 v69, v101, v110
	ds_read_b64_tr_b16 v[70:71], v80
	ds_read_b64_tr_b16 v[72:73], v81 offset:2048
	v_add_u32_e32 v96, 0, v85
	v_add_u32_e32 v97, 0, v87
	s_waitcnt lgkmcnt(0)
	v_mfma_f32_32x32x16_bf16 v[50:65], v[66:69], v[70:73], v[50:65]
	ds_read_b64_tr_b16 v[70:71], v96
	ds_read_b64_tr_b16 v[72:73], v97 offset:2048
	s_add_i32 s20, s20, 32
	s_add_i32 s1, s66, s20
	v_add_u32_e32 v87, 0x2000, v87
	v_add_u32_e32 v86, 0x2000, v86
	v_add_u32_e32 v85, 0x2000, v85
	s_waitcnt lgkmcnt(0)
	v_mfma_f32_32x32x16_bf16 v[34:49], v[66:69], v[70:73], v[34:49]
	v_cvt_pk_bf16_f32 v66, v106, v107
	v_cvt_pk_bf16_f32 v67, v76, v77
	v_cvt_pk_bf16_f32 v68, v78, v79
	v_cvt_pk_bf16_f32 v69, v74, v75
	ds_read_b64_tr_b16 v[70:71], v80 offset:4096
	ds_read_b64_tr_b16 v[72:73], v81 offset:6144
	v_add_u32_e32 v84, 0x2000, v84
	s_cmp_lg_u32 s1, 0
	s_waitcnt lgkmcnt(0)
	v_mfma_f32_32x32x16_bf16 v[50:65], v[66:69], v[70:73], v[50:65]
	ds_read_b64_tr_b16 v[70:71], v96 offset:4096
	ds_read_b64_tr_b16 v[72:73], v97 offset:6144
	s_waitcnt lgkmcnt(0)
	v_mfma_f32_32x32x16_bf16 v[34:49], v[66:69], v[70:73], v[34:49]
	s_cbranch_scc1 .LBB0_1055
	v_lshlrev_b64 v[66:67], 12, v[98:99]
	v_lshl_add_u64 v[66:67], s[46:47], 0, v[66:67]
	s_lshl_b32 s42, s42, 9
	v_lshl_add_u64 v[66:67], v[66:67], 0, s[42:43]
	v_mov_b32_e32 v123, v119
	v_lshl_add_u64 v[94:95], v[66:67], 0, v[122:123]
	s_barrier
	global_load_dwordx4 v[66:69], v[94:95], off nt
	global_load_dwordx4 v[70:73], v[94:95], off offset:16 nt
	global_load_dwordx4 v[74:77], v[94:95], off offset:32 nt
	global_load_dwordx4 v[78:81], v[94:95], off offset:48 nt
	global_load_dwordx4 v[82:85], v[94:95], off offset:64 nt
	global_load_dwordx4 v[86:89], v[94:95], off offset:80 nt
	global_load_dwordx4 v[90:93], v[94:95], off offset:96 nt
	s_nop 0
	global_load_dwordx4 v[94:97], v[94:95], off offset:112 nt
	s_waitcnt vmcnt(7)
	ds_write_b128 v215, v[66:69]
	s_waitcnt vmcnt(6)
	ds_write_b128 v215, v[70:73] offset:16
	s_waitcnt vmcnt(5)
	ds_write_b128 v215, v[74:77] offset:32
	s_waitcnt vmcnt(4)
	ds_write_b128 v215, v[78:81] offset:48
	s_waitcnt vmcnt(3)
	ds_write_b128 v215, v[82:85] offset:64
	s_waitcnt vmcnt(2)
	ds_write_b128 v215, v[86:89] offset:80
	s_waitcnt vmcnt(1)
	ds_write_b128 v215, v[90:93] offset:96
	s_waitcnt vmcnt(0)
	ds_write_b128 v215, v[94:97] offset:112
	s_waitcnt lgkmcnt(0)
	s_barrier
	ds_read_u16 v66, v216
	s_waitcnt lgkmcnt(0)
	v_lshlrev_b32_e32 v66, 16, v66
	v_mul_f32_e32 v67, 0xbfb8aa3b, v66
	v_exp_f32_e32 v67, v67
	s_nop 0
	v_add_f32_e32 v67, 1.0, v67
	v_rcp_f32_e32 v67, v67
	s_nop 0
	v_mul_f32_e32 v66, v67, v66
	v_mul_f32_e32 v18, v18, v66
	v_cvt_pk_bf16_f32 v18, v18, v119
	ds_read_u16 v66, v216 offset:512
	ds_write_b16 v216, v18
	s_waitcnt lgkmcnt(1)
	v_lshlrev_b32_e32 v66, 16, v66
	v_mul_f32_e32 v67, 0xbfb8aa3b, v66
	v_exp_f32_e32 v67, v67
	s_nop 0
	v_add_f32_e32 v67, 1.0, v67
	v_rcp_f32_e32 v67, v67
	s_nop 0
	v_mul_f32_e32 v18, v67, v66
	v_mul_f32_e32 v18, v19, v18
	v_cvt_pk_bf16_f32 v18, v18, v119
	ds_read_u16 v19, v216 offset:1024
	ds_write_b16 v216, v18 offset:512
	s_waitcnt lgkmcnt(1)
	v_lshlrev_b32_e32 v19, 16, v19
	v_mul_f32_e32 v66, 0xbfb8aa3b, v19
	v_exp_f32_e32 v66, v66
	s_nop 0
	v_add_f32_e32 v66, 1.0, v66
	v_rcp_f32_e32 v66, v66
	s_nop 0
	v_mul_f32_e32 v18, v66, v19
	v_mul_f32_e32 v18, v20, v18
	v_cvt_pk_bf16_f32 v18, v18, v119
	ds_read_u16 v19, v216 offset:1536
	ds_write_b16 v216, v18 offset:1024
	s_waitcnt lgkmcnt(1)
	v_lshlrev_b32_e32 v19, 16, v19
	v_mul_f32_e32 v20, 0xbfb8aa3b, v19
	v_exp_f32_e32 v20, v20
	s_nop 0
	v_add_f32_e32 v20, 1.0, v20
	v_rcp_f32_e32 v20, v20
	s_nop 0
	v_mul_f32_e32 v18, v20, v19
	v_mul_f32_e32 v18, v21, v18
	v_cvt_pk_bf16_f32 v18, v18, v119
	ds_read_u16 v19, v216 offset:4096
	ds_write_b16 v216, v18 offset:1536
	s_waitcnt lgkmcnt(1)
	v_lshlrev_b32_e32 v19, 16, v19
	v_mul_f32_e32 v20, 0xbfb8aa3b, v19
	v_exp_f32_e32 v20, v20
	s_nop 0
	v_add_f32_e32 v20, 1.0, v20
	v_rcp_f32_e32 v20, v20
	s_nop 0
	v_mul_f32_e32 v18, v20, v19
	v_mul_f32_e32 v18, v22, v18
	v_cvt_pk_bf16_f32 v18, v18, v119
	ds_read_u16 v19, v216 offset:4608
	ds_write_b16 v216, v18 offset:4096
	s_waitcnt lgkmcnt(1)
	v_lshlrev_b32_e32 v19, 16, v19
	v_mul_f32_e32 v20, 0xbfb8aa3b, v19
	v_exp_f32_e32 v20, v20
	s_nop 0
	v_add_f32_e32 v20, 1.0, v20
	v_rcp_f32_e32 v20, v20
	s_nop 0
	v_mul_f32_e32 v18, v20, v19
	v_mul_f32_e32 v18, v23, v18
	v_cvt_pk_bf16_f32 v18, v18, v119
	ds_read_u16 v19, v216 offset:5120
	ds_write_b16 v216, v18 offset:4608
	s_waitcnt lgkmcnt(1)
	v_lshlrev_b32_e32 v19, 16, v19
	v_mul_f32_e32 v20, 0xbfb8aa3b, v19
	v_exp_f32_e32 v20, v20
	s_nop 0
	v_add_f32_e32 v20, 1.0, v20
	v_rcp_f32_e32 v20, v20
	s_nop 0
	v_mul_f32_e32 v18, v20, v19
	v_mul_f32_e32 v18, v24, v18
	v_cvt_pk_bf16_f32 v18, v18, v119
	ds_read_u16 v19, v216 offset:5632
	ds_write_b16 v216, v18 offset:5120
	s_waitcnt lgkmcnt(1)
	v_lshlrev_b32_e32 v19, 16, v19
	v_mul_f32_e32 v20, 0xbfb8aa3b, v19
	v_exp_f32_e32 v20, v20
	s_nop 0
	v_add_f32_e32 v20, 1.0, v20
	v_rcp_f32_e32 v20, v20
	s_nop 0
	v_mul_f32_e32 v18, v20, v19
	v_mul_f32_e32 v18, v25, v18
	v_cvt_pk_bf16_f32 v18, v18, v119
	ds_read_u16 v19, v216 offset:8192
	ds_write_b16 v216, v18 offset:5632
	s_waitcnt lgkmcnt(1)
	v_lshlrev_b32_e32 v19, 16, v19
	v_mul_f32_e32 v20, 0xbfb8aa3b, v19
	v_exp_f32_e32 v20, v20
	s_nop 0
	v_add_f32_e32 v20, 1.0, v20
	v_rcp_f32_e32 v20, v20
	s_nop 0
	v_mul_f32_e32 v18, v20, v19
	v_mul_f32_e32 v18, v26, v18
	v_cvt_pk_bf16_f32 v18, v18, v119
	ds_read_u16 v19, v216 offset:8704
	ds_write_b16 v216, v18 offset:8192
	s_waitcnt lgkmcnt(1)
	v_lshlrev_b32_e32 v19, 16, v19
	v_mul_f32_e32 v20, 0xbfb8aa3b, v19
	v_exp_f32_e32 v20, v20
	s_nop 0
	v_add_f32_e32 v20, 1.0, v20
	v_rcp_f32_e32 v20, v20
	s_nop 0
	v_mul_f32_e32 v18, v20, v19
	v_mul_f32_e32 v18, v27, v18
	v_cvt_pk_bf16_f32 v18, v18, v119
	ds_read_u16 v19, v216 offset:9216
	ds_write_b16 v216, v18 offset:8704
	s_waitcnt lgkmcnt(1)
	v_lshlrev_b32_e32 v19, 16, v19
	v_mul_f32_e32 v20, 0xbfb8aa3b, v19
	v_exp_f32_e32 v20, v20
	s_nop 0
	v_add_f32_e32 v20, 1.0, v20
	v_rcp_f32_e32 v20, v20
	s_nop 0
	v_mul_f32_e32 v18, v20, v19
	v_mul_f32_e32 v18, v28, v18
	v_cvt_pk_bf16_f32 v18, v18, v119
	ds_read_u16 v19, v216 offset:9728
	ds_write_b16 v216, v18 offset:9216
	s_waitcnt lgkmcnt(1)
	v_lshlrev_b32_e32 v19, 16, v19
	v_mul_f32_e32 v20, 0xbfb8aa3b, v19
	v_exp_f32_e32 v20, v20
	s_nop 0
	v_add_f32_e32 v20, 1.0, v20
	v_rcp_f32_e32 v20, v20
	s_nop 0
	v_mul_f32_e32 v18, v20, v19
	v_mul_f32_e32 v18, v29, v18
	v_cvt_pk_bf16_f32 v18, v18, v119
	ds_read_u16 v19, v216 offset:12288
	ds_write_b16 v216, v18 offset:9728
	s_waitcnt lgkmcnt(1)
	v_lshlrev_b32_e32 v19, 16, v19
	v_mul_f32_e32 v20, 0xbfb8aa3b, v19
	v_exp_f32_e32 v20, v20
	s_nop 0
	v_add_f32_e32 v20, 1.0, v20
	v_rcp_f32_e32 v20, v20
	s_nop 0
	v_mul_f32_e32 v18, v20, v19
	v_mul_f32_e32 v18, v30, v18
	v_cvt_pk_bf16_f32 v18, v18, v119
	ds_read_u16 v19, v216 offset:12800
	ds_write_b16 v216, v18 offset:12288
	s_waitcnt lgkmcnt(1)
	v_lshlrev_b32_e32 v19, 16, v19
	v_mul_f32_e32 v20, 0xbfb8aa3b, v19
	v_exp_f32_e32 v20, v20
	s_nop 0
	v_add_f32_e32 v20, 1.0, v20
	v_rcp_f32_e32 v20, v20
	s_nop 0
	v_mul_f32_e32 v18, v20, v19
	v_mul_f32_e32 v18, v31, v18
	v_cvt_pk_bf16_f32 v18, v18, v119
	ds_read_u16 v19, v216 offset:13312
	ds_write_b16 v216, v18 offset:12800
	s_waitcnt lgkmcnt(1)
	v_lshlrev_b32_e32 v19, 16, v19
	v_mul_f32_e32 v20, 0xbfb8aa3b, v19
	v_exp_f32_e32 v20, v20
	s_nop 0
	v_add_f32_e32 v20, 1.0, v20
	v_rcp_f32_e32 v20, v20
	s_nop 0
	v_mul_f32_e32 v18, v20, v19
	v_mul_f32_e32 v18, v32, v18
	v_cvt_pk_bf16_f32 v18, v18, v119
	ds_read_u16 v19, v216 offset:13824
	ds_write_b16 v216, v18 offset:13312
	s_waitcnt lgkmcnt(1)
	v_lshlrev_b32_e32 v19, 16, v19
	v_mul_f32_e32 v20, 0xbfb8aa3b, v19
	v_exp_f32_e32 v20, v20
	s_nop 0
	v_add_f32_e32 v20, 1.0, v20
	v_rcp_f32_e32 v20, v20
	s_nop 0
	v_mul_f32_e32 v18, v20, v19
	v_mul_f32_e32 v18, v33, v18
	v_cvt_pk_bf16_f32 v18, v18, v119
	ds_read_u16 v19, v216 offset:64
	ds_write_b16 v216, v18 offset:13824
	s_waitcnt lgkmcnt(1)
	v_lshlrev_b32_e32 v19, 16, v19
	v_mul_f32_e32 v20, 0xbfb8aa3b, v19
	v_exp_f32_e32 v20, v20
	s_nop 0
	v_add_f32_e32 v20, 1.0, v20
	v_rcp_f32_e32 v20, v20
	s_nop 0
	v_mul_f32_e32 v18, v20, v19
	v_mul_f32_e32 v2, v2, v18
	v_cvt_pk_bf16_f32 v2, v2, v119
	ds_read_u16 v18, v216 offset:576
	ds_write_b16 v216, v2 offset:64
	s_waitcnt lgkmcnt(1)
	v_lshlrev_b32_e32 v18, 16, v18
	v_mul_f32_e32 v19, 0xbfb8aa3b, v18
	v_exp_f32_e32 v19, v19
	s_nop 0
	v_add_f32_e32 v19, 1.0, v19
	v_rcp_f32_e32 v19, v19
	s_nop 0
	v_mul_f32_e32 v2, v19, v18
	v_mul_f32_e32 v2, v3, v2
	v_cvt_pk_bf16_f32 v2, v2, v119
	ds_read_u16 v3, v216 offset:1088
	ds_write_b16 v216, v2 offset:576
	s_waitcnt lgkmcnt(1)
	v_lshlrev_b32_e32 v3, 16, v3
	v_mul_f32_e32 v18, 0xbfb8aa3b, v3
	v_exp_f32_e32 v18, v18
	s_nop 0
	v_add_f32_e32 v18, 1.0, v18
	v_rcp_f32_e32 v18, v18
	s_nop 0
	v_mul_f32_e32 v2, v18, v3
	v_mul_f32_e32 v2, v4, v2
	v_cvt_pk_bf16_f32 v2, v2, v119
	ds_read_u16 v3, v216 offset:1600
	ds_write_b16 v216, v2 offset:1088
	s_waitcnt lgkmcnt(1)
	v_lshlrev_b32_e32 v3, 16, v3
	v_mul_f32_e32 v4, 0xbfb8aa3b, v3
	v_exp_f32_e32 v4, v4
	s_nop 0
	v_add_f32_e32 v4, 1.0, v4
	v_rcp_f32_e32 v4, v4
	s_nop 0
	v_mul_f32_e32 v2, v4, v3
	v_mul_f32_e32 v2, v5, v2
	v_cvt_pk_bf16_f32 v2, v2, v119
	ds_read_u16 v3, v216 offset:4160
	ds_write_b16 v216, v2 offset:1600
	s_waitcnt lgkmcnt(1)
	v_lshlrev_b32_e32 v3, 16, v3
	v_mul_f32_e32 v4, 0xbfb8aa3b, v3
	v_exp_f32_e32 v4, v4
	s_nop 0
	v_add_f32_e32 v4, 1.0, v4
	v_rcp_f32_e32 v4, v4
	s_nop 0
	v_mul_f32_e32 v2, v4, v3
	v_mul_f32_e32 v2, v6, v2
	v_cvt_pk_bf16_f32 v2, v2, v119
	ds_read_u16 v3, v216 offset:4672
	ds_write_b16 v216, v2 offset:4160
	s_waitcnt lgkmcnt(1)
	v_lshlrev_b32_e32 v3, 16, v3
	v_mul_f32_e32 v4, 0xbfb8aa3b, v3
	v_exp_f32_e32 v4, v4
	s_nop 0
	v_add_f32_e32 v4, 1.0, v4
	v_rcp_f32_e32 v4, v4
	s_nop 0
	v_mul_f32_e32 v2, v4, v3
	v_mul_f32_e32 v2, v7, v2
	v_cvt_pk_bf16_f32 v2, v2, v119
	ds_read_u16 v3, v216 offset:5184
	ds_write_b16 v216, v2 offset:4672
	v_xor_b32_e32 v7, 1, v219
	s_waitcnt lgkmcnt(1)
	v_lshlrev_b32_e32 v3, 16, v3
	v_mul_f32_e32 v4, 0xbfb8aa3b, v3
	v_exp_f32_e32 v4, v4
	s_nop 0
	v_add_f32_e32 v4, 1.0, v4
	v_rcp_f32_e32 v4, v4
	s_nop 0
	v_mul_f32_e32 v2, v4, v3
	v_mul_f32_e32 v2, v8, v2
	v_cvt_pk_bf16_f32 v2, v2, v119
	ds_read_u16 v3, v216 offset:5696
	ds_write_b16 v216, v2 offset:5184
	v_and_b32_e32 v8, 64, v219
	v_add_u32_e32 v8, 64, v8
	v_cmp_lt_i32_e32 vcc, v7, v8
	s_waitcnt lgkmcnt(1)
	v_lshlrev_b32_e32 v3, 16, v3
	v_mul_f32_e32 v4, 0xbfb8aa3b, v3
	v_exp_f32_e32 v4, v4
	v_cndmask_b32_e32 v7, v219, v7, vcc
	v_add_f32_e32 v4, 1.0, v4
	v_rcp_f32_e32 v4, v4
	s_nop 0
	v_mul_f32_e32 v2, v4, v3
	v_mul_f32_e32 v2, v9, v2
	v_cvt_pk_bf16_f32 v2, v2, v119
	ds_read_u16 v3, v216 offset:8256
	ds_write_b16 v216, v2 offset:5696
	s_waitcnt lgkmcnt(1)
	v_lshlrev_b32_e32 v3, 16, v3
	v_mul_f32_e32 v4, 0xbfb8aa3b, v3
	v_exp_f32_e32 v4, v4
	s_nop 0
	v_add_f32_e32 v4, 1.0, v4
	v_rcp_f32_e32 v4, v4
	s_nop 0
	v_mul_f32_e32 v2, v4, v3
	v_mul_f32_e32 v2, v10, v2
	v_cvt_pk_bf16_f32 v2, v2, v119
	ds_read_u16 v3, v216 offset:8768
	ds_write_b16 v216, v2 offset:8256
	s_waitcnt lgkmcnt(1)
	v_lshlrev_b32_e32 v3, 16, v3
	v_mul_f32_e32 v4, 0xbfb8aa3b, v3
	v_exp_f32_e32 v4, v4
	s_nop 0
	v_add_f32_e32 v4, 1.0, v4
	v_rcp_f32_e32 v4, v4
	s_nop 0
	v_mul_f32_e32 v2, v4, v3
	v_mul_f32_e32 v2, v11, v2
	v_cvt_pk_bf16_f32 v2, v2, v119
	ds_read_u16 v3, v216 offset:9280
	ds_write_b16 v216, v2 offset:8768
	s_waitcnt lgkmcnt(1)
	v_lshlrev_b32_e32 v3, 16, v3
	v_mul_f32_e32 v4, 0xbfb8aa3b, v3
	v_exp_f32_e32 v4, v4
	s_nop 0
	v_add_f32_e32 v4, 1.0, v4
	v_rcp_f32_e32 v4, v4
	s_nop 0
	v_mul_f32_e32 v2, v4, v3
	v_mul_f32_e32 v2, v12, v2
	v_cvt_pk_bf16_f32 v2, v2, v119
	ds_read_u16 v3, v216 offset:9792
	ds_write_b16 v216, v2 offset:9280
	s_waitcnt lgkmcnt(1)
	v_lshlrev_b32_e32 v3, 16, v3
	v_mul_f32_e32 v4, 0xbfb8aa3b, v3
	v_exp_f32_e32 v4, v4
	s_nop 0
	v_add_f32_e32 v4, 1.0, v4
	v_rcp_f32_e32 v4, v4
	s_nop 0
	v_mul_f32_e32 v2, v4, v3
	v_mul_f32_e32 v2, v13, v2
	v_cvt_pk_bf16_f32 v2, v2, v119
	ds_read_u16 v3, v216 offset:12352
	ds_write_b16 v216, v2 offset:9792
	s_waitcnt lgkmcnt(1)
	v_lshlrev_b32_e32 v3, 16, v3
	v_mul_f32_e32 v4, 0xbfb8aa3b, v3
	v_exp_f32_e32 v4, v4
	s_nop 0
	v_add_f32_e32 v4, 1.0, v4
	v_rcp_f32_e32 v4, v4
	s_nop 0
	v_mul_f32_e32 v2, v4, v3
	v_mul_f32_e32 v2, v14, v2
	v_cvt_pk_bf16_f32 v2, v2, v119
	ds_read_u16 v3, v216 offset:12864
	ds_write_b16 v216, v2 offset:12352
	s_waitcnt lgkmcnt(1)
	v_lshlrev_b32_e32 v3, 16, v3
	v_mul_f32_e32 v4, 0xbfb8aa3b, v3
	v_exp_f32_e32 v4, v4
	s_nop 0
	v_add_f32_e32 v4, 1.0, v4
	v_rcp_f32_e32 v4, v4
	s_nop 0
	v_mul_f32_e32 v2, v4, v3
	v_mul_f32_e32 v2, v15, v2
	v_cvt_pk_bf16_f32 v2, v2, v119
	ds_read_u16 v3, v216 offset:13376
	ds_write_b16 v216, v2 offset:12864
	s_waitcnt lgkmcnt(1)
	v_lshlrev_b32_e32 v3, 16, v3
	v_mul_f32_e32 v4, 0xbfb8aa3b, v3
	v_exp_f32_e32 v4, v4
	s_nop 0
	v_add_f32_e32 v4, 1.0, v4
	v_rcp_f32_e32 v4, v4
	s_nop 0
	v_mul_f32_e32 v2, v4, v3
	v_mul_f32_e32 v2, v16, v2
	v_cvt_pk_bf16_f32 v2, v2, v119
	ds_read_u16 v3, v216 offset:13888
	ds_write_b16 v216, v2 offset:13376
	s_waitcnt lgkmcnt(1)
	v_lshlrev_b32_e32 v3, 16, v3
	v_mul_f32_e32 v4, 0xbfb8aa3b, v3
	v_exp_f32_e32 v4, v4
	s_nop 0
	v_add_f32_e32 v4, 1.0, v4
	v_rcp_f32_e32 v4, v4
	s_nop 0
	v_mul_f32_e32 v2, v4, v3
	v_mul_f32_e32 v2, v17, v2
	v_cvt_pk_bf16_f32 v2, v2, v119
	ds_read_u16 v3, v217
	ds_write_b16 v216, v2 offset:13888
	s_waitcnt lgkmcnt(1)
	v_lshlrev_b32_e32 v3, 16, v3
	v_mul_f32_e32 v4, 0xbfb8aa3b, v3
	v_exp_f32_e32 v4, v4
	s_nop 0
	v_add_f32_e32 v4, 1.0, v4
	v_rcp_f32_e32 v4, v4
	s_nop 0
	v_mul_f32_e32 v2, v4, v3
	v_mul_f32_e32 v2, v50, v2
	v_cvt_pk_bf16_f32 v2, v2, v119
	ds_read_u16 v3, v217 offset:512
	ds_write_b16 v217, v2
	s_waitcnt lgkmcnt(1)
	v_lshlrev_b32_e32 v3, 16, v3
	v_mul_f32_e32 v4, 0xbfb8aa3b, v3
	v_exp_f32_e32 v4, v4
	s_nop 0
	v_add_f32_e32 v4, 1.0, v4
	v_rcp_f32_e32 v4, v4
	s_nop 0
	v_mul_f32_e32 v2, v4, v3
	v_mul_f32_e32 v2, v51, v2
	v_cvt_pk_bf16_f32 v2, v2, v119
	ds_read_u16 v3, v217 offset:1024
	ds_write_b16 v217, v2 offset:512
	s_waitcnt lgkmcnt(1)
	v_lshlrev_b32_e32 v3, 16, v3
	v_mul_f32_e32 v4, 0xbfb8aa3b, v3
	v_exp_f32_e32 v4, v4
	s_nop 0
	v_add_f32_e32 v4, 1.0, v4
	v_rcp_f32_e32 v4, v4
	s_nop 0
	v_mul_f32_e32 v2, v4, v3
	v_mul_f32_e32 v2, v52, v2
	v_cvt_pk_bf16_f32 v2, v2, v119
	ds_read_u16 v3, v217 offset:1536
	ds_write_b16 v217, v2 offset:1024
	s_waitcnt lgkmcnt(1)
	v_lshlrev_b32_e32 v3, 16, v3
	v_mul_f32_e32 v4, 0xbfb8aa3b, v3
	v_exp_f32_e32 v4, v4
	s_nop 0
	v_add_f32_e32 v4, 1.0, v4
	v_rcp_f32_e32 v4, v4
	s_nop 0
	v_mul_f32_e32 v2, v4, v3
	v_mul_f32_e32 v2, v53, v2
	v_cvt_pk_bf16_f32 v2, v2, v119
	ds_read_u16 v3, v217 offset:4096
	ds_write_b16 v217, v2 offset:1536
	s_waitcnt lgkmcnt(1)
	v_lshlrev_b32_e32 v3, 16, v3
	v_mul_f32_e32 v4, 0xbfb8aa3b, v3
	v_exp_f32_e32 v4, v4
	s_nop 0
	v_add_f32_e32 v4, 1.0, v4
	v_rcp_f32_e32 v4, v4
	s_nop 0
	v_mul_f32_e32 v2, v4, v3
	v_mul_f32_e32 v2, v54, v2
	v_cvt_pk_bf16_f32 v2, v2, v119
	ds_read_u16 v3, v217 offset:4608
	ds_write_b16 v217, v2 offset:4096
	s_waitcnt lgkmcnt(1)
	v_lshlrev_b32_e32 v3, 16, v3
	v_mul_f32_e32 v4, 0xbfb8aa3b, v3
	v_exp_f32_e32 v4, v4
	s_nop 0
	v_add_f32_e32 v4, 1.0, v4
	v_rcp_f32_e32 v4, v4
	s_nop 0
	v_mul_f32_e32 v2, v4, v3
	v_mul_f32_e32 v2, v55, v2
	v_cvt_pk_bf16_f32 v2, v2, v119
	ds_read_u16 v3, v217 offset:5120
	ds_write_b16 v217, v2 offset:4608
	s_waitcnt lgkmcnt(1)
	v_lshlrev_b32_e32 v3, 16, v3
	v_mul_f32_e32 v4, 0xbfb8aa3b, v3
	v_exp_f32_e32 v4, v4
	s_nop 0
	v_add_f32_e32 v4, 1.0, v4
	v_rcp_f32_e32 v4, v4
	s_nop 0
	v_mul_f32_e32 v2, v4, v3
	v_mul_f32_e32 v2, v56, v2
	v_cvt_pk_bf16_f32 v2, v2, v119
	ds_read_u16 v3, v217 offset:5632
	ds_write_b16 v217, v2 offset:5120
	s_waitcnt lgkmcnt(1)
	v_lshlrev_b32_e32 v3, 16, v3
	v_mul_f32_e32 v4, 0xbfb8aa3b, v3
	v_exp_f32_e32 v4, v4
	s_nop 0
	v_add_f32_e32 v4, 1.0, v4
	v_rcp_f32_e32 v4, v4
	s_nop 0
	v_mul_f32_e32 v2, v4, v3
	v_mul_f32_e32 v2, v57, v2
	v_cvt_pk_bf16_f32 v2, v2, v119
	ds_read_u16 v3, v217 offset:8192
	ds_write_b16 v217, v2 offset:5632
	s_waitcnt lgkmcnt(1)
	v_lshlrev_b32_e32 v3, 16, v3
	v_mul_f32_e32 v4, 0xbfb8aa3b, v3
	v_exp_f32_e32 v4, v4
	s_nop 0
	v_add_f32_e32 v4, 1.0, v4
	v_rcp_f32_e32 v4, v4
	s_nop 0
	v_mul_f32_e32 v2, v4, v3
	v_mul_f32_e32 v2, v58, v2
	v_cvt_pk_bf16_f32 v2, v2, v119
	ds_read_u16 v3, v217 offset:8704
	ds_write_b16 v217, v2 offset:8192
	s_waitcnt lgkmcnt(1)
	v_lshlrev_b32_e32 v3, 16, v3
	v_mul_f32_e32 v4, 0xbfb8aa3b, v3
	v_exp_f32_e32 v4, v4
	s_nop 0
	v_add_f32_e32 v4, 1.0, v4
	v_rcp_f32_e32 v4, v4
	s_nop 0
	v_mul_f32_e32 v2, v4, v3
	v_mul_f32_e32 v2, v59, v2
	v_cvt_pk_bf16_f32 v2, v2, v119
	ds_read_u16 v3, v217 offset:9216
	ds_write_b16 v217, v2 offset:8704
	s_waitcnt lgkmcnt(1)
	v_lshlrev_b32_e32 v3, 16, v3
	v_mul_f32_e32 v4, 0xbfb8aa3b, v3
	v_exp_f32_e32 v4, v4
	s_nop 0
	v_add_f32_e32 v4, 1.0, v4
	v_rcp_f32_e32 v4, v4
	s_nop 0
	v_mul_f32_e32 v2, v4, v3
	v_mul_f32_e32 v2, v60, v2
	v_cvt_pk_bf16_f32 v2, v2, v119
	ds_read_u16 v3, v217 offset:9728
	ds_write_b16 v217, v2 offset:9216
	s_waitcnt lgkmcnt(1)
	v_lshlrev_b32_e32 v3, 16, v3
	v_mul_f32_e32 v4, 0xbfb8aa3b, v3
	v_exp_f32_e32 v4, v4
	s_nop 0
	v_add_f32_e32 v4, 1.0, v4
	v_rcp_f32_e32 v4, v4
	s_nop 0
	v_mul_f32_e32 v2, v4, v3
	v_mul_f32_e32 v2, v61, v2
	v_cvt_pk_bf16_f32 v2, v2, v119
	ds_read_u16 v3, v217 offset:12288
	ds_write_b16 v217, v2 offset:9728
	s_waitcnt lgkmcnt(1)
	v_lshlrev_b32_e32 v3, 16, v3
	v_mul_f32_e32 v4, 0xbfb8aa3b, v3
	v_exp_f32_e32 v4, v4
	s_nop 0
	v_add_f32_e32 v4, 1.0, v4
	v_rcp_f32_e32 v4, v4
	s_nop 0
	v_mul_f32_e32 v2, v4, v3
	v_mul_f32_e32 v2, v62, v2
	v_cvt_pk_bf16_f32 v2, v2, v119
	ds_read_u16 v3, v217 offset:12800
	ds_write_b16 v217, v2 offset:12288
	s_waitcnt lgkmcnt(1)
	v_lshlrev_b32_e32 v3, 16, v3
	v_mul_f32_e32 v4, 0xbfb8aa3b, v3
	v_exp_f32_e32 v4, v4
	s_nop 0
	v_add_f32_e32 v4, 1.0, v4
	v_rcp_f32_e32 v4, v4
	s_nop 0
	v_mul_f32_e32 v2, v4, v3
	v_mul_f32_e32 v2, v63, v2
	v_cvt_pk_bf16_f32 v2, v2, v119
	ds_read_u16 v3, v217 offset:13312
	ds_write_b16 v217, v2 offset:12800
	s_waitcnt lgkmcnt(1)
	v_lshlrev_b32_e32 v3, 16, v3
	v_mul_f32_e32 v4, 0xbfb8aa3b, v3
	v_exp_f32_e32 v4, v4
	s_nop 0
	v_add_f32_e32 v4, 1.0, v4
	v_rcp_f32_e32 v4, v4
	s_nop 0
	v_mul_f32_e32 v2, v4, v3
	v_mul_f32_e32 v2, v64, v2
	v_cvt_pk_bf16_f32 v2, v2, v119
	ds_read_u16 v3, v217 offset:13824
	ds_write_b16 v217, v2 offset:13312
	s_waitcnt lgkmcnt(1)
	v_lshlrev_b32_e32 v3, 16, v3
	v_mul_f32_e32 v4, 0xbfb8aa3b, v3
	v_exp_f32_e32 v4, v4
	s_nop 0
	v_add_f32_e32 v4, 1.0, v4
	v_rcp_f32_e32 v4, v4
	s_nop 0
	v_mul_f32_e32 v2, v4, v3
	v_mul_f32_e32 v2, v65, v2
	v_cvt_pk_bf16_f32 v2, v2, v119
	ds_read_u16 v3, v217 offset:64
	ds_write_b16 v217, v2 offset:13824
	s_waitcnt lgkmcnt(1)
	v_lshlrev_b32_e32 v3, 16, v3
	v_mul_f32_e32 v4, 0xbfb8aa3b, v3
	v_exp_f32_e32 v4, v4
	s_nop 0
	v_add_f32_e32 v4, 1.0, v4
	v_rcp_f32_e32 v4, v4
	s_nop 0
	v_mul_f32_e32 v2, v4, v3
	v_mul_f32_e32 v2, v34, v2
	v_cvt_pk_bf16_f32 v2, v2, v119
	ds_read_u16 v3, v217 offset:576
	ds_write_b16 v217, v2 offset:64
	s_waitcnt lgkmcnt(1)
	v_lshlrev_b32_e32 v3, 16, v3
	v_mul_f32_e32 v4, 0xbfb8aa3b, v3
	v_exp_f32_e32 v4, v4
	s_nop 0
	v_add_f32_e32 v4, 1.0, v4
	v_rcp_f32_e32 v4, v4
	s_nop 0
	v_mul_f32_e32 v2, v4, v3
	v_mul_f32_e32 v2, v35, v2
	v_cvt_pk_bf16_f32 v2, v2, v119
	ds_read_u16 v3, v217 offset:1088
	ds_write_b16 v217, v2 offset:576
	s_waitcnt lgkmcnt(1)
	v_lshlrev_b32_e32 v3, 16, v3
	v_mul_f32_e32 v4, 0xbfb8aa3b, v3
	v_exp_f32_e32 v4, v4
	s_nop 0
	v_add_f32_e32 v4, 1.0, v4
	v_rcp_f32_e32 v4, v4
	s_nop 0
	v_mul_f32_e32 v2, v4, v3
	v_mul_f32_e32 v2, v36, v2
	v_cvt_pk_bf16_f32 v2, v2, v119
	ds_read_u16 v3, v217 offset:1600
	ds_write_b16 v217, v2 offset:1088
	s_waitcnt lgkmcnt(1)
	v_lshlrev_b32_e32 v3, 16, v3
	v_mul_f32_e32 v4, 0xbfb8aa3b, v3
	v_exp_f32_e32 v4, v4
	s_nop 0
	v_add_f32_e32 v4, 1.0, v4
	v_rcp_f32_e32 v4, v4
	s_nop 0
	v_mul_f32_e32 v2, v4, v3
	v_mul_f32_e32 v2, v37, v2
	v_cvt_pk_bf16_f32 v2, v2, v119
	ds_read_u16 v3, v217 offset:4160
	ds_write_b16 v217, v2 offset:1600
	v_lshlrev_b32_e32 v37, 2, v7
	s_waitcnt lgkmcnt(1)
	v_lshlrev_b32_e32 v3, 16, v3
	v_mul_f32_e32 v4, 0xbfb8aa3b, v3
	v_exp_f32_e32 v4, v4
	s_nop 0
	v_add_f32_e32 v4, 1.0, v4
	v_rcp_f32_e32 v4, v4
	s_nop 0
	v_mul_f32_e32 v2, v4, v3
	v_mul_f32_e32 v2, v38, v2
	v_cvt_pk_bf16_f32 v2, v2, v119
	ds_read_u16 v3, v217 offset:4672
	ds_write_b16 v217, v2 offset:4160
	s_waitcnt lgkmcnt(1)
	v_lshlrev_b32_e32 v3, 16, v3
	v_mul_f32_e32 v4, 0xbfb8aa3b, v3
	v_exp_f32_e32 v4, v4
	s_nop 0
	v_add_f32_e32 v4, 1.0, v4
	v_rcp_f32_e32 v4, v4
	s_nop 0
	v_mul_f32_e32 v2, v4, v3
	v_mul_f32_e32 v2, v39, v2
	v_cvt_pk_bf16_f32 v2, v2, v119
	ds_read_u16 v3, v217 offset:5184
	ds_write_b16 v217, v2 offset:4672
	s_waitcnt lgkmcnt(1)
	v_lshlrev_b32_e32 v3, 16, v3
	v_mul_f32_e32 v4, 0xbfb8aa3b, v3
	v_exp_f32_e32 v4, v4
	s_nop 0
	v_add_f32_e32 v4, 1.0, v4
	v_rcp_f32_e32 v4, v4
	s_nop 0
	v_mul_f32_e32 v2, v4, v3
	v_mul_f32_e32 v2, v40, v2
	v_cvt_pk_bf16_f32 v2, v2, v119
	ds_read_u16 v3, v217 offset:5696
	ds_write_b16 v217, v2 offset:5184
	s_waitcnt lgkmcnt(1)
	v_lshlrev_b32_e32 v3, 16, v3
	v_mul_f32_e32 v4, 0xbfb8aa3b, v3
	v_exp_f32_e32 v4, v4
	s_nop 0
	v_add_f32_e32 v4, 1.0, v4
	v_rcp_f32_e32 v4, v4
	s_nop 0
	v_mul_f32_e32 v2, v4, v3
	v_mul_f32_e32 v2, v41, v2
	v_cvt_pk_bf16_f32 v2, v2, v119
	ds_read_u16 v3, v217 offset:8256
	ds_write_b16 v217, v2 offset:5696
	s_waitcnt lgkmcnt(1)
	v_lshlrev_b32_e32 v3, 16, v3
	v_mul_f32_e32 v4, 0xbfb8aa3b, v3
	v_exp_f32_e32 v4, v4
	s_nop 0
	v_add_f32_e32 v4, 1.0, v4
	v_rcp_f32_e32 v4, v4
	s_nop 0
	v_mul_f32_e32 v2, v4, v3
	v_mul_f32_e32 v2, v42, v2
	v_cvt_pk_bf16_f32 v2, v2, v119
	ds_read_u16 v3, v217 offset:8768
	ds_write_b16 v217, v2 offset:8256
	s_waitcnt lgkmcnt(1)
	v_lshlrev_b32_e32 v3, 16, v3
	v_mul_f32_e32 v4, 0xbfb8aa3b, v3
	v_exp_f32_e32 v4, v4
	s_nop 0
	v_add_f32_e32 v4, 1.0, v4
	v_rcp_f32_e32 v4, v4
	s_nop 0
	v_mul_f32_e32 v2, v4, v3
	v_mul_f32_e32 v2, v43, v2
	v_cvt_pk_bf16_f32 v2, v2, v119
	ds_read_u16 v3, v217 offset:9280
	ds_write_b16 v217, v2 offset:8768
	s_waitcnt lgkmcnt(1)
	v_lshlrev_b32_e32 v3, 16, v3
	v_mul_f32_e32 v4, 0xbfb8aa3b, v3
	v_exp_f32_e32 v4, v4
	s_nop 0
	v_add_f32_e32 v4, 1.0, v4
	v_rcp_f32_e32 v4, v4
	s_nop 0
	v_mul_f32_e32 v2, v4, v3
	v_mul_f32_e32 v2, v44, v2
	v_cvt_pk_bf16_f32 v2, v2, v119
	ds_read_u16 v3, v217 offset:9792
	ds_write_b16 v217, v2 offset:9280
	s_waitcnt lgkmcnt(1)
	v_lshlrev_b32_e32 v3, 16, v3
	v_mul_f32_e32 v4, 0xbfb8aa3b, v3
	v_exp_f32_e32 v4, v4
	s_nop 0
	v_add_f32_e32 v4, 1.0, v4
	v_rcp_f32_e32 v4, v4
	s_nop 0
	v_mul_f32_e32 v2, v4, v3
	v_mul_f32_e32 v2, v45, v2
	v_cvt_pk_bf16_f32 v2, v2, v119
	ds_read_u16 v3, v217 offset:12352
	ds_write_b16 v217, v2 offset:9792
	s_waitcnt lgkmcnt(1)
	v_lshlrev_b32_e32 v3, 16, v3
	v_mul_f32_e32 v4, 0xbfb8aa3b, v3
	v_exp_f32_e32 v4, v4
	s_nop 0
	v_add_f32_e32 v4, 1.0, v4
	v_rcp_f32_e32 v4, v4
	s_nop 0
	v_mul_f32_e32 v2, v4, v3
	v_mul_f32_e32 v2, v46, v2
	v_cvt_pk_bf16_f32 v2, v2, v119
	ds_read_u16 v3, v217 offset:12864
	ds_write_b16 v217, v2 offset:12352
	s_waitcnt lgkmcnt(1)
	v_lshlrev_b32_e32 v3, 16, v3
	v_mul_f32_e32 v4, 0xbfb8aa3b, v3
	v_exp_f32_e32 v4, v4
	s_nop 0
	v_add_f32_e32 v4, 1.0, v4
	v_rcp_f32_e32 v4, v4
	s_nop 0
	v_mul_f32_e32 v2, v4, v3
	v_mul_f32_e32 v2, v47, v2
	v_cvt_pk_bf16_f32 v4, v2, v119
	ds_read_u16 v2, v217 offset:13376
	ds_write_b16 v217, v4 offset:12864
	s_waitcnt lgkmcnt(1)
	v_lshlrev_b32_e32 v5, 16, v2
	v_mul_f32_e32 v2, 0xbfb8aa3b, v5
	v_exp_f32_e32 v6, v2
	v_lshlrev_b64 v[2:3], 13, v[98:99]
	v_lshl_add_u64 v[2:3], s[48:49], 0, v[2:3]
	v_lshl_add_u64 v[2:3], v[2:3], 0, s[42:43]
	v_add_f32_e32 v6, 1.0, v6
	v_rcp_f32_e32 v6, v6
	v_lshl_add_u64 v[34:35], v[2:3], 0, v[122:123]
	v_mul_f32_e32 v4, v6, v5
	v_mul_f32_e32 v4, v48, v4
	v_cvt_pk_bf16_f32 v4, v4, v119
	ds_read_u16 v5, v217 offset:13888
	v_xor_b32_e32 v6, 2, v219
	v_cmp_lt_i32_e32 vcc, v6, v8
	ds_write_b16 v217, v4 offset:13376
	s_waitcnt lgkmcnt(1)
	v_lshlrev_b32_e32 v5, 16, v5
	v_mul_f32_e32 v9, 0xbfb8aa3b, v5
	v_exp_f32_e32 v9, v9
	v_cndmask_b32_e32 v36, v219, v6, vcc
	v_add_f32_e32 v6, 1.0, v9
	v_rcp_f32_e32 v6, v6
	s_nop 0
	v_mul_f32_e32 v2, v6, v5
	v_mul_f32_e32 v2, v49, v2
	v_cvt_pk_bf16_f32 v2, v2, v119
	ds_write_b16 v217, v2 offset:13888
	s_waitcnt lgkmcnt(0)
	s_barrier
	ds_read_b128 v[2:5], v215
	ds_read_b128 v[6:9], v215 offset:16
	ds_read_b128 v[10:13], v215 offset:32
	ds_read_b128 v[14:17], v215 offset:48
	ds_read_b128 v[18:21], v215 offset:64
	ds_read_b128 v[22:25], v215 offset:80
	ds_read_b128 v[26:29], v215 offset:96
	ds_read_b128 v[30:33], v215 offset:112
	s_waitcnt lgkmcnt(7)
	v_and_b32_e32 v39, 0xffff0000, v2
	v_lshlrev_b32_e32 v38, 16, v2
	v_mul_f32_e32 v39, v39, v39
	v_lshlrev_b32_e32 v40, 16, v3
	v_fmac_f32_e32 v39, v38, v38
	v_and_b32_e32 v41, 0xffff0000, v3
	v_fmac_f32_e32 v39, v40, v40
	v_lshlrev_b32_e32 v42, 16, v4
	v_fmac_f32_e32 v39, v41, v41
	v_and_b32_e32 v43, 0xffff0000, v4
	v_fmac_f32_e32 v39, v42, v42
	v_lshlrev_b32_e32 v44, 16, v5
	v_fmac_f32_e32 v39, v43, v43
	v_and_b32_e32 v45, 0xffff0000, v5
	v_fmac_f32_e32 v39, v44, v44
	s_waitcnt lgkmcnt(6)
	v_lshlrev_b32_e32 v46, 16, v6
	v_fmac_f32_e32 v39, v45, v45
	v_and_b32_e32 v47, 0xffff0000, v6
	v_fmac_f32_e32 v39, v46, v46
	v_lshlrev_b32_e32 v48, 16, v7
	v_fmac_f32_e32 v39, v47, v47
	v_and_b32_e32 v49, 0xffff0000, v7
	v_fmac_f32_e32 v39, v48, v48
	v_lshlrev_b32_e32 v50, 16, v8
	v_fmac_f32_e32 v39, v49, v49
	v_and_b32_e32 v51, 0xffff0000, v8
	v_fmac_f32_e32 v39, v50, v50
	v_lshlrev_b32_e32 v52, 16, v9
	v_fmac_f32_e32 v39, v51, v51
	v_and_b32_e32 v53, 0xffff0000, v9
	v_fmac_f32_e32 v39, v52, v52
	s_waitcnt lgkmcnt(5)
	v_lshlrev_b32_e32 v54, 16, v10
	v_fmac_f32_e32 v39, v53, v53
	v_and_b32_e32 v55, 0xffff0000, v10
	v_fmac_f32_e32 v39, v54, v54
	v_lshlrev_b32_e32 v56, 16, v11
	v_fmac_f32_e32 v39, v55, v55
	v_and_b32_e32 v57, 0xffff0000, v11
	v_fmac_f32_e32 v39, v56, v56
	v_lshlrev_b32_e32 v58, 16, v12
	v_fmac_f32_e32 v39, v57, v57
	v_and_b32_e32 v59, 0xffff0000, v12
	v_fmac_f32_e32 v39, v58, v58
	v_lshlrev_b32_e32 v60, 16, v13
	v_fmac_f32_e32 v39, v59, v59
	v_and_b32_e32 v61, 0xffff0000, v13
	v_fmac_f32_e32 v39, v60, v60
	s_waitcnt lgkmcnt(4)
	v_lshlrev_b32_e32 v62, 16, v14
	v_fmac_f32_e32 v39, v61, v61
	v_and_b32_e32 v63, 0xffff0000, v14
	v_fmac_f32_e32 v39, v62, v62
	v_lshlrev_b32_e32 v64, 16, v15
	v_fmac_f32_e32 v39, v63, v63
	v_and_b32_e32 v65, 0xffff0000, v15
	v_fmac_f32_e32 v39, v64, v64
	v_lshlrev_b32_e32 v66, 16, v16
	v_fmac_f32_e32 v39, v65, v65
	v_and_b32_e32 v67, 0xffff0000, v16
	v_fmac_f32_e32 v39, v66, v66
	v_lshlrev_b32_e32 v68, 16, v17
	v_fmac_f32_e32 v39, v67, v67
	v_and_b32_e32 v69, 0xffff0000, v17
	v_fmac_f32_e32 v39, v68, v68
	s_waitcnt lgkmcnt(3)
	v_lshlrev_b32_e32 v70, 16, v18
	v_fmac_f32_e32 v39, v69, v69
	v_and_b32_e32 v71, 0xffff0000, v18
	v_fmac_f32_e32 v39, v70, v70
	v_lshlrev_b32_e32 v72, 16, v19
	v_fmac_f32_e32 v39, v71, v71
	v_and_b32_e32 v73, 0xffff0000, v19
	v_fmac_f32_e32 v39, v72, v72
	v_lshlrev_b32_e32 v74, 16, v20
	v_fmac_f32_e32 v39, v73, v73
	v_and_b32_e32 v75, 0xffff0000, v20
	v_fmac_f32_e32 v39, v74, v74
	v_lshlrev_b32_e32 v76, 16, v21
	v_fmac_f32_e32 v39, v75, v75
	v_and_b32_e32 v77, 0xffff0000, v21
	v_fmac_f32_e32 v39, v76, v76
	s_waitcnt lgkmcnt(2)
	v_lshlrev_b32_e32 v78, 16, v22
	v_fmac_f32_e32 v39, v77, v77
	v_and_b32_e32 v79, 0xffff0000, v22
	v_fmac_f32_e32 v39, v78, v78
	v_lshlrev_b32_e32 v80, 16, v23
	v_fmac_f32_e32 v39, v79, v79
	v_and_b32_e32 v81, 0xffff0000, v23
	v_fmac_f32_e32 v39, v80, v80
	v_lshlrev_b32_e32 v82, 16, v24
	v_fmac_f32_e32 v39, v81, v81
	v_and_b32_e32 v83, 0xffff0000, v24
	v_fmac_f32_e32 v39, v82, v82
	v_lshlrev_b32_e32 v84, 16, v25
	v_fmac_f32_e32 v39, v83, v83
	v_and_b32_e32 v85, 0xffff0000, v25
	v_fmac_f32_e32 v39, v84, v84
	s_waitcnt lgkmcnt(1)
	v_lshlrev_b32_e32 v86, 16, v26
	v_fmac_f32_e32 v39, v85, v85
	v_and_b32_e32 v87, 0xffff0000, v26
	v_fmac_f32_e32 v39, v86, v86
	v_lshlrev_b32_e32 v88, 16, v27
	v_fmac_f32_e32 v39, v87, v87
	v_and_b32_e32 v89, 0xffff0000, v27
	v_fmac_f32_e32 v39, v88, v88
	v_lshlrev_b32_e32 v90, 16, v28
	v_fmac_f32_e32 v39, v89, v89
	v_and_b32_e32 v91, 0xffff0000, v28
	v_fmac_f32_e32 v39, v90, v90
	v_lshlrev_b32_e32 v92, 16, v29
	v_fmac_f32_e32 v39, v91, v91
	v_and_b32_e32 v93, 0xffff0000, v29
	v_fmac_f32_e32 v39, v92, v92
	s_waitcnt lgkmcnt(0)
	v_lshlrev_b32_e32 v94, 16, v30
	v_fmac_f32_e32 v39, v93, v93
	v_and_b32_e32 v95, 0xffff0000, v30
	v_fmac_f32_e32 v39, v94, v94
	v_lshlrev_b32_e32 v96, 16, v31
	v_fmac_f32_e32 v39, v95, v95
	v_and_b32_e32 v97, 0xffff0000, v31
	v_fmac_f32_e32 v39, v96, v96
	v_lshlrev_b32_e32 v100, 16, v32
	v_fmac_f32_e32 v39, v97, v97
	v_and_b32_e32 v101, 0xffff0000, v32
	v_fmac_f32_e32 v39, v100, v100
	v_lshlrev_b32_e32 v102, 16, v33
	v_fmac_f32_e32 v39, v101, v101
	v_and_b32_e32 v103, 0xffff0000, v33
	v_fmac_f32_e32 v39, v102, v102
	v_fmac_f32_e32 v39, v103, v103
	ds_bpermute_b32 v37, v37, v39
	global_store_dwordx4 v[34:35], v[2:5], off
	global_store_dwordx4 v[34:35], v[6:9], off offset:16
	global_store_dwordx4 v[34:35], v[10:13], off offset:32
	global_store_dwordx4 v[34:35], v[14:17], off offset:48
	v_lshlrev_b32_e32 v3, 2, v36
	global_store_dwordx4 v[34:35], v[18:21], off offset:64
	global_store_dwordx4 v[34:35], v[22:25], off offset:80
	global_store_dwordx4 v[34:35], v[26:29], off offset:96
	global_store_dwordx4 v[34:35], v[30:33], off offset:112
	s_waitcnt lgkmcnt(0)
	v_add_f32_e32 v2, v39, v37
	ds_bpermute_b32 v3, v3, v2
	s_and_saveexec_b64 s[20:21], s[18:19]
	s_cbranch_execz .LBB0_1035
	s_waitcnt lgkmcnt(0)
	v_add_f32_e32 v4, v2, v3
	v_lshl_add_u64 v[2:3], v[98:99], 2, s[50:51]
	global_atomic_add_f32 v[2:3], v4, off
	s_branch .LBB0_1035
